# MFMA issue order per interval: 2x2 fragment blocks walked in a snake (each source fragment stays within a window of two for consecutive MFMAs), all k0 then all k1 (w_in, w_out, down, up loops)
# speedup vs baseline: 1.0118x; 1.0118x over previous
; #define PG8_STAGE(bufoff, gbase, voff) do { _Pragma("unroll") for (int _i = 0; _i < 2; ++_i) \
;         __builtin_amdgcn_global_load_lds((const unsigned*)((const char*)(gbase) + (voff)[_i]), (PG8_LAS unsigned*)(lds + (bufoff) + ldsw + _i * 8192), 16, 0, 0); } while (0)
; #define PG8_LDA(dst, b, h) do { _Pragma("unroll") for (int m = 0; m < 4; ++m) _Pragma("unroll") for (int k = 0; k < 2; ++k) dst[m][k] = *(const PG8_LAS bf16x8*)(lds + PG8_SA(b, h) + aoff + m * 2048 + k * 1024); } while (0)
; #define PG8_LDB(dst, b, h) do { _Pragma("unroll") for (int n = 0; n < 2; ++n) _Pragma("unroll") for (int k = 0; k < 2; ++k) dst[n][k] = *(const PG8_LAS bf16x8*)(lds + PG8_SB(b, h) + boff + n * 2048 + k * 1024); } while (0)
; #define PG8_WAIT_V(n) asm volatile("s_waitcnt vmcnt(" #n ")" ::: "memory")
; #define PG8_WAIT_L(n) asm volatile("s_waitcnt lgkmcnt(" #n ")" ::: "memory")
; #define PG8_BAR __builtin_amdgcn_s_barrier()
; #define PG8_SCHED __builtin_amdgcn_sched_barrier(0)
; template <class Epi, class Sched, bool ALIGN_EPI = false, bool SP2 = false>
; __device__ __forceinline__ void gemm_phase(PG8_LAS unsigned char* lds, const Gemm g, const Sched& S, const Epi& E) {
;     ...
;         const bool has_next = S.next(ui + 1, nxt);
;         const char* nA = has_next ? (const char*)g.A + (size_t)nxt.pm * tstep : cA; const char* nB = has_next ? (const char*)g.Bt + (size_t)nxt.pn * tstep : cB;
;         for (int t = 0; t < nt; t += 2) {
;             const bool last = (t == nt - 2);
;             const char* a1 = cA + (size_t)(t + 1) * kstep;
;             const char* a2 = last ? nA : cA + (size_t)(t + 2) * kstep; const char* b2 = last ? nB : cB + (size_t)(t + 2) * kstep;
;             const char* a3 = a2 + kstep; const char* b3 = b2 + kstep;
;             if (last && has_next) S.a_ready(nxt);
;             if constexpr (SP2) {
;             PG8_LDB(B0, 0, 0); PG8_LDB(B1, 0, 1); PG8_SCHED; PG8_LDA(At, 0, 0); PG8_STAGE(PG8_SA(1, 1), a1 + hstep, voffA);
;             PG8_WAIT_V(8); PG8_WAIT_L(0); PG8_BAR; PG8_MMA(0, 0, At, B0); PG8_MMA(0, 1, At, B1); PG8_BAR; PG8_SCHED;
;             PG8_LDA(At, 0, 1); PG8_STAGE(PG8_SB(0, 0), b2, voffB); PG8_STAGE(PG8_SB(0, 1), b2 + hstepB, voffB); PG8_STAGE(PG8_SA(0, 0), a2, voffA);
;             PG8_WAIT_V(8); PG8_WAIT_L(0); PG8_BAR; PG8_MMA(1, 0, At, B0); PG8_MMA(1, 1, At, B1); PG8_BAR; PG8_SCHED;
.LBB0_169:
	s_add_u32 s93, s46, 0x100
	s_addc_u32 s94, s47, 0
	s_ashr_i32 s69, s68, 31
	s_lshl_b64 s[4:5], s[68:69], 20
	s_add_u32 s76, s52, s4
	s_addc_u32 s77, s53, s5
	s_and_b64 s[4:5], s[38:39], exec
	s_cselect_b32 s4, s77, s71
	s_cselect_b32 s5, s76, s70
	s_ashr_i32 s63, s62, 31
	s_lshl_b64 s[6:7], s[62:63], 20
	v_readlane_b32 s8, v249, 19
	v_readlane_b32 s9, v249, 20
	s_add_u32 s72, s8, s6
	s_addc_u32 s73, s9, s7
	s_and_b64 s[6:7], s[38:39], exec
	s_cselect_b32 s6, s73, s47
	s_cselect_b32 s7, s72, s46
	s_add_u32 s8, s70, 0x80080
	s_addc_u32 s9, s71, 0
	v_lshl_add_u64 v[144:145], s[8:9], 0, v[140:141]
	v_lshl_add_u64 v[146:147], s[8:9], 0, v[142:143]
	s_mov_b32 s8, -2
	s_mov_b64 s[46:47], 0
	v_add_u32_e32 v186, 0x10000, v139
	v_add_u32_e32 v187, 0x14000, v139
	v_add_u32_e32 v198, 0x18000, v139
	v_add_u32_e32 v199, 0x1c000, v139
	s_add_u32 s9, s70, s46
	s_addc_u32 s10, s71, s47
	s_add_u32 s9, s9, 0x100
	s_addc_u32 s10, s10, 0
	s_add_u32 s100, s9, 0x7ff80
	s_addc_u32 s101, s10, 0
	s_add_u32 s11, s93, s46
	s_addc_u32 s12, s94, s47
	s_add_i32 s13, 0, 0x10000
	s_cmpk_eq_i32 s46, 0xf00
	s_cselect_b32 s85, s4, s10
	s_cselect_b32 s84, s5, s9
	s_cselect_b32 s81, s6, s12
	s_cselect_b32 s80, s7, s11
	s_add_i32 s9, 0, 0x14000
	ds_read_b128 v[148:151], v186
	ds_read_b128 v[152:155], v186 offset:1024
	ds_read_b128 v[156:159], v186 offset:2048
	ds_read_b128 v[160:163], v186 offset:3072
	ds_read_b128 v[166:169], v187
	ds_read_b128 v[170:173], v187 offset:1024
	ds_read_b128 v[174:177], v187 offset:2048
	ds_read_b128 v[178:181], v187 offset:3072
	s_add_i32 m0, s1, 0xc000
	ds_read_b128 v[182:185], v165
	ds_read_b128 v[206:209], v165 offset:1024
	ds_read_b128 v[210:213], v165 offset:2048
	ds_read_b128 v[214:217], v165 offset:3072
	ds_read_b128 v[218:221], v165 offset:4096
	ds_read_b128 v[236:239], v165 offset:5120
	ds_read_b128 v[240:243], v165 offset:6144
	ds_read_b128 v[244:247], v165 offset:7168
	global_load_lds_dwordx4 v140, s[100:101]
	s_add_i32 m0, s1, 0xe000
	s_nop 0
	global_load_lds_dwordx4 v142, s[100:101]
	s_waitcnt vmcnt(8)
	s_waitcnt lgkmcnt(0)
	s_barrier
	v_mfma_f32_16x16x32_bf16 v[126:129], v[148:151], v[182:185], 0
	v_mfma_f32_16x16x32_bf16 v[122:125], v[156:159], v[182:185], 0
	v_mfma_f32_16x16x32_bf16 v[114:117], v[156:159], v[210:213], 0
	v_mfma_f32_16x16x32_bf16 v[118:121], v[148:151], v[210:213], 0
	v_mfma_f32_16x16x32_bf16 v[86:89], v[166:169], v[210:213], 0
	v_mfma_f32_16x16x32_bf16 v[82:85], v[174:177], v[210:213], 0
	v_mfma_f32_16x16x32_bf16 v[90:93], v[174:177], v[182:185], 0
	v_mfma_f32_16x16x32_bf16 v[94:97], v[166:169], v[182:185], 0
	v_mfma_f32_16x16x32_bf16 v[78:81], v[166:169], v[218:221], 0
	v_mfma_f32_16x16x32_bf16 v[74:77], v[174:177], v[218:221], 0
	v_mfma_f32_16x16x32_bf16 v[66:69], v[174:177], v[240:243], 0
	v_mfma_f32_16x16x32_bf16 v[70:73], v[166:169], v[240:243], 0
	v_mfma_f32_16x16x32_bf16 v[102:105], v[148:151], v[240:243], 0
	v_mfma_f32_16x16x32_bf16 v[98:101], v[156:159], v[240:243], 0
	v_mfma_f32_16x16x32_bf16 v[106:109], v[156:159], v[218:221], 0
	v_mfma_f32_16x16x32_bf16 v[110:113], v[148:151], v[218:221], 0
	v_mfma_f32_16x16x32_bf16 v[126:129], v[152:155], v[206:209], v[126:129]
	v_mfma_f32_16x16x32_bf16 v[122:125], v[160:163], v[206:209], v[122:125]
	v_mfma_f32_16x16x32_bf16 v[114:117], v[160:163], v[214:217], v[114:117]
	v_mfma_f32_16x16x32_bf16 v[118:121], v[152:155], v[214:217], v[118:121]
	v_mfma_f32_16x16x32_bf16 v[86:89], v[170:173], v[214:217], v[86:89]
	v_mfma_f32_16x16x32_bf16 v[82:85], v[178:181], v[214:217], v[82:85]
	v_mfma_f32_16x16x32_bf16 v[90:93], v[178:181], v[206:209], v[90:93]
	v_mfma_f32_16x16x32_bf16 v[94:97], v[170:173], v[206:209], v[94:97]
	v_mfma_f32_16x16x32_bf16 v[78:81], v[170:173], v[236:239], v[78:81]
	v_mfma_f32_16x16x32_bf16 v[74:77], v[178:181], v[236:239], v[74:77]
	v_mfma_f32_16x16x32_bf16 v[66:69], v[178:181], v[244:247], v[66:69]
	v_mfma_f32_16x16x32_bf16 v[70:73], v[170:173], v[244:247], v[70:73]
	v_mfma_f32_16x16x32_bf16 v[102:105], v[152:155], v[244:247], v[102:105]
	v_mfma_f32_16x16x32_bf16 v[98:101], v[160:163], v[244:247], v[98:101]
	v_mfma_f32_16x16x32_bf16 v[106:109], v[160:163], v[236:239], v[106:109]
	v_mfma_f32_16x16x32_bf16 v[110:113], v[152:155], v[236:239], v[110:113]
	s_barrier
	s_add_i32 s10, s13, s0
	s_mov_b32 m0, s10
	ds_read_b128 v[182:185], v165 offset:16384
	ds_read_b128 v[206:209], v165 offset:17408
	ds_read_b128 v[210:213], v165 offset:18432
	ds_read_b128 v[214:217], v165 offset:19456
	ds_read_b128 v[218:221], v165 offset:20480
	ds_read_b128 v[236:239], v165 offset:21504
	ds_read_b128 v[240:243], v165 offset:22528
	ds_read_b128 v[244:247], v165 offset:23552
	global_load_lds_dwordx4 v132, s[80:81]
	s_add_i32 m0, s10, 0x2000
	s_add_u32 s10, s80, 0x20000
	s_addc_u32 s11, s81, 0
	s_add_i32 s9, s9, s0
	global_load_lds_dwordx4 v136, s[80:81]
	s_mov_b32 m0, s9
	s_nop 0
	global_load_lds_dwordx4 v132, s[10:11]
	s_add_i32 m0, s9, 0x2000
	s_nop 0
	global_load_lds_dwordx4 v136, s[10:11]
	s_mov_b32 m0, s1
	s_nop 0
	global_load_lds_dwordx4 v130, s[84:85]
	s_mov_b32 m0, s25
	s_nop 0
	global_load_lds_dwordx4 v134, s[84:85]
	s_waitcnt vmcnt(8)
	s_waitcnt lgkmcnt(0)
	s_barrier
; #define PG8_STAGE(bufoff, gbase, voff) do { _Pragma("unroll") for (int _i = 0; _i < 2; ++_i) \
;         __builtin_amdgcn_global_load_lds((const unsigned*)((const char*)(gbase) + (voff)[_i]), (PG8_LAS unsigned*)(lds + (bufoff) + ldsw + _i * 8192), 16, 0, 0); } while (0)
; #define PG8_LDA(dst, b, h) do { _Pragma("unroll") for (int m = 0; m < 4; ++m) _Pragma("unroll") for (int k = 0; k < 2; ++k) dst[m][k] = *(const PG8_LAS bf16x8*)(lds + PG8_SA(b, h) + aoff + m * 2048 + k * 1024); } while (0)
; #define PG8_LDB(dst, b, h) do { _Pragma("unroll") for (int n = 0; n < 2; ++n) _Pragma("unroll") for (int k = 0; k < 2; ++k) dst[n][k] = *(const PG8_LAS bf16x8*)(lds + PG8_SB(b, h) + boff + n * 2048 + k * 1024); } while (0)
; #define PG8_MMA(ai, bj, At, Bt) do { __builtin_amdgcn_s_setprio(1); _Pragma("unroll") for (int m = 0; m < 4; ++m) _Pragma("unroll") for (int n = 0; n < 2; ++n) _Pragma("unroll") for (int k = 0; k < 2; ++k) \
;         acc[ai][bj][m][n] = __builtin_amdgcn_mfma_f32_16x16x32_bf16(Bt[n][k], At[m][k], acc[ai][bj][m][n], 0, 0, 0); __builtin_amdgcn_s_setprio(0); } while (0)
; #define PG8_WAIT_V(n) asm volatile("s_waitcnt vmcnt(" #n ")" ::: "memory")
; #define PG8_WAIT_L(n) asm volatile("s_waitcnt lgkmcnt(" #n ")" ::: "memory")
; #define PG8_BAR __builtin_amdgcn_s_barrier()
; #define PG8_SCHED __builtin_amdgcn_sched_barrier(0)
; template <class Epi, class Sched, bool ALIGN_EPI = false, bool SP2 = false>
; __device__ __forceinline__ void gemm_phase(PG8_LAS unsigned char* lds, const Gemm g, const Sched& S, const Epi& E) {
;     ...
;             PG8_WAIT_V(8); PG8_WAIT_L(0); PG8_BAR; PG8_MMA(1, 0, At, B0); PG8_MMA(1, 1, At, B1); PG8_BAR; PG8_SCHED;
;             PG8_LDB(B0, 1, 0); PG8_LDB(B1, 1, 1); PG8_SCHED; PG8_LDA(At, 1, 0); PG8_STAGE(PG8_SA(0, 1), a2 + hstep, voffA);
;             PG8_WAIT_V(8); PG8_WAIT_L(0); PG8_BAR; PG8_MMA(0, 0, At, B0); PG8_MMA(0, 1, At, B1); PG8_BAR; PG8_SCHED;
	v_mfma_f32_16x16x32_bf16 v[62:65], v[148:151], v[182:185], 0
	v_mfma_f32_16x16x32_bf16 v[58:61], v[156:159], v[182:185], 0
	v_mfma_f32_16x16x32_bf16 v[50:53], v[156:159], v[210:213], 0
	v_mfma_f32_16x16x32_bf16 v[54:57], v[148:151], v[210:213], 0
	v_mfma_f32_16x16x32_bf16 v[22:25], v[166:169], v[210:213], 0
	v_mfma_f32_16x16x32_bf16 v[18:21], v[174:177], v[210:213], 0
	v_mfma_f32_16x16x32_bf16 v[26:29], v[174:177], v[182:185], 0
	v_mfma_f32_16x16x32_bf16 v[30:33], v[166:169], v[182:185], 0
	v_mfma_f32_16x16x32_bf16 v[14:17], v[166:169], v[218:221], 0
	v_mfma_f32_16x16x32_bf16 v[10:13], v[174:177], v[218:221], 0
	v_mfma_f32_16x16x32_bf16 v[2:5], v[174:177], v[240:243], 0
	v_mfma_f32_16x16x32_bf16 v[6:9], v[166:169], v[240:243], 0
	v_mfma_f32_16x16x32_bf16 v[38:41], v[148:151], v[240:243], 0
	v_mfma_f32_16x16x32_bf16 v[34:37], v[156:159], v[240:243], 0
	v_mfma_f32_16x16x32_bf16 v[42:45], v[156:159], v[218:221], 0
	v_mfma_f32_16x16x32_bf16 v[46:49], v[148:151], v[218:221], 0
	v_mfma_f32_16x16x32_bf16 v[62:65], v[152:155], v[206:209], v[62:65]
	v_mfma_f32_16x16x32_bf16 v[58:61], v[160:163], v[206:209], v[58:61]
	v_mfma_f32_16x16x32_bf16 v[50:53], v[160:163], v[214:217], v[50:53]
	v_mfma_f32_16x16x32_bf16 v[54:57], v[152:155], v[214:217], v[54:57]
	v_mfma_f32_16x16x32_bf16 v[22:25], v[170:173], v[214:217], v[22:25]
	v_mfma_f32_16x16x32_bf16 v[18:21], v[178:181], v[214:217], v[18:21]
	v_mfma_f32_16x16x32_bf16 v[26:29], v[178:181], v[206:209], v[26:29]
	v_mfma_f32_16x16x32_bf16 v[30:33], v[170:173], v[206:209], v[30:33]
	v_mfma_f32_16x16x32_bf16 v[14:17], v[170:173], v[236:239], v[14:17]
	v_mfma_f32_16x16x32_bf16 v[10:13], v[178:181], v[236:239], v[10:13]
	v_mfma_f32_16x16x32_bf16 v[2:5], v[178:181], v[244:247], v[2:5]
	v_mfma_f32_16x16x32_bf16 v[6:9], v[170:173], v[244:247], v[6:9]
	v_mfma_f32_16x16x32_bf16 v[38:41], v[152:155], v[244:247], v[38:41]
	v_mfma_f32_16x16x32_bf16 v[34:37], v[160:163], v[244:247], v[34:37]
	v_mfma_f32_16x16x32_bf16 v[42:45], v[160:163], v[236:239], v[42:45]
	v_mfma_f32_16x16x32_bf16 v[46:49], v[152:155], v[236:239], v[46:49]
	s_barrier
	s_add_i32 s9, 0, 0x18000
	s_add_i32 s12, 0, 0x1c000
	ds_read_b128 v[148:151], v198
	ds_read_b128 v[152:155], v198 offset:1024
	ds_read_b128 v[156:159], v198 offset:2048
	ds_read_b128 v[160:163], v198 offset:3072
	ds_read_b128 v[166:169], v199
	ds_read_b128 v[170:173], v199 offset:1024
	ds_read_b128 v[174:177], v199 offset:2048
	ds_read_b128 v[178:181], v199 offset:3072
	s_add_u32 s10, s84, 0x80000
	s_addc_u32 s11, s85, 0
	s_mov_b32 m0, s42
	ds_read_b128 v[182:185], v165 offset:32768
	ds_read_b128 v[206:209], v165 offset:33792
	ds_read_b128 v[210:213], v165 offset:34816
	ds_read_b128 v[214:217], v165 offset:35840
	ds_read_b128 v[218:221], v165 offset:36864
	ds_read_b128 v[236:239], v165 offset:37888
	ds_read_b128 v[240:243], v165 offset:38912
	ds_read_b128 v[244:247], v165 offset:39936
	global_load_lds_dwordx4 v130, s[10:11]
	s_mov_b32 m0, s51
	s_nop 0
	global_load_lds_dwordx4 v134, s[10:11]
	s_waitcnt vmcnt(8)
	s_waitcnt lgkmcnt(0)
	s_barrier
	v_mfma_f32_16x16x32_bf16 v[126:129], v[148:151], v[182:185], v[126:129]
	v_mfma_f32_16x16x32_bf16 v[122:125], v[156:159], v[182:185], v[122:125]
	v_mfma_f32_16x16x32_bf16 v[114:117], v[156:159], v[210:213], v[114:117]
	v_mfma_f32_16x16x32_bf16 v[118:121], v[148:151], v[210:213], v[118:121]
	v_mfma_f32_16x16x32_bf16 v[86:89], v[166:169], v[210:213], v[86:89]
	v_mfma_f32_16x16x32_bf16 v[82:85], v[174:177], v[210:213], v[82:85]
	v_mfma_f32_16x16x32_bf16 v[90:93], v[174:177], v[182:185], v[90:93]
	v_mfma_f32_16x16x32_bf16 v[94:97], v[166:169], v[182:185], v[94:97]
	v_mfma_f32_16x16x32_bf16 v[78:81], v[166:169], v[218:221], v[78:81]
	v_mfma_f32_16x16x32_bf16 v[74:77], v[174:177], v[218:221], v[74:77]
	v_mfma_f32_16x16x32_bf16 v[66:69], v[174:177], v[240:243], v[66:69]
	v_mfma_f32_16x16x32_bf16 v[70:73], v[166:169], v[240:243], v[70:73]
	v_mfma_f32_16x16x32_bf16 v[102:105], v[148:151], v[240:243], v[102:105]
	v_mfma_f32_16x16x32_bf16 v[98:101], v[156:159], v[240:243], v[98:101]
	v_mfma_f32_16x16x32_bf16 v[106:109], v[156:159], v[218:221], v[106:109]
	v_mfma_f32_16x16x32_bf16 v[110:113], v[148:151], v[218:221], v[110:113]
	v_mfma_f32_16x16x32_bf16 v[126:129], v[152:155], v[206:209], v[126:129]
	v_mfma_f32_16x16x32_bf16 v[122:125], v[160:163], v[206:209], v[122:125]
	v_mfma_f32_16x16x32_bf16 v[114:117], v[160:163], v[214:217], v[114:117]
	v_mfma_f32_16x16x32_bf16 v[118:121], v[152:155], v[214:217], v[118:121]
	v_mfma_f32_16x16x32_bf16 v[86:89], v[170:173], v[214:217], v[86:89]
	v_mfma_f32_16x16x32_bf16 v[82:85], v[178:181], v[214:217], v[82:85]
	v_mfma_f32_16x16x32_bf16 v[90:93], v[178:181], v[206:209], v[90:93]
	v_mfma_f32_16x16x32_bf16 v[94:97], v[170:173], v[206:209], v[94:97]
	v_mfma_f32_16x16x32_bf16 v[78:81], v[170:173], v[236:239], v[78:81]
	v_mfma_f32_16x16x32_bf16 v[74:77], v[178:181], v[236:239], v[74:77]
	v_mfma_f32_16x16x32_bf16 v[66:69], v[178:181], v[244:247], v[66:69]
	v_mfma_f32_16x16x32_bf16 v[70:73], v[170:173], v[244:247], v[70:73]
	v_mfma_f32_16x16x32_bf16 v[102:105], v[152:155], v[244:247], v[102:105]
	v_mfma_f32_16x16x32_bf16 v[98:101], v[160:163], v[244:247], v[98:101]
	v_mfma_f32_16x16x32_bf16 v[106:109], v[160:163], v[236:239], v[106:109]
	v_mfma_f32_16x16x32_bf16 v[110:113], v[152:155], v[236:239], v[110:113]
	s_barrier
; #define PG8_STAGE(bufoff, gbase, voff) do { _Pragma("unroll") for (int _i = 0; _i < 2; ++_i) \
;         __builtin_amdgcn_global_load_lds((const unsigned*)((const char*)(gbase) + (voff)[_i]), (PG8_LAS unsigned*)(lds + (bufoff) + ldsw + _i * 8192), 16, 0, 0); } while (0)
; #define PG8_LDA(dst, b, h) do { _Pragma("unroll") for (int m = 0; m < 4; ++m) _Pragma("unroll") for (int k = 0; k < 2; ++k) dst[m][k] = *(const PG8_LAS bf16x8*)(lds + PG8_SA(b, h) + aoff + m * 2048 + k * 1024); } while (0)
; #define PG8_LDB(dst, b, h) do { _Pragma("unroll") for (int n = 0; n < 2; ++n) _Pragma("unroll") for (int k = 0; k < 2; ++k) dst[n][k] = *(const PG8_LAS bf16x8*)(lds + PG8_SB(b, h) + boff + n * 2048 + k * 1024); } while (0)
; template <class Epi, class Sched, bool ALIGN_EPI = false, bool SP2 = false>
; __device__ __forceinline__ void gemm_phase(PG8_LAS unsigned char* lds, const Gemm g, const Sched& S, const Epi& E) {
;     ...
;         for (int t = 0; t < nt; t += 2) {
;             const bool last = (t == nt - 2);
;             const char* a1 = cA + (size_t)(t + 1) * kstep;
;             const char* a2 = last ? nA : cA + (size_t)(t + 2) * kstep; const char* b2 = last ? nB : cB + (size_t)(t + 2) * kstep;
;             const char* a3 = a2 + kstep; const char* b3 = b2 + kstep;
;             if (last && has_next) S.a_ready(nxt);
;             if constexpr (SP2) {
;             PG8_LDB(B0, 0, 0); PG8_LDB(B1, 0, 1); PG8_SCHED; PG8_LDA(At, 0, 0); PG8_STAGE(PG8_SA(1, 1), a1 + hstep, voffA);
;             PG8_WAIT_V(8); PG8_WAIT_L(0); PG8_BAR; PG8_MMA(0, 0, At, B0); PG8_MMA(0, 1, At, B1); PG8_BAR; PG8_SCHED;
;             PG8_LDA(At, 0, 1); PG8_STAGE(PG8_SB(0, 0), b2, voffB); PG8_STAGE(PG8_SB(0, 1), b2 + hstepB, voffB); PG8_STAGE(PG8_SA(0, 0), a2, voffA);
;             PG8_WAIT_V(8); PG8_WAIT_L(0); PG8_BAR; PG8_MMA(1, 0, At, B0); PG8_MMA(1, 1, At, B1); PG8_BAR; PG8_SCHED;
;             PG8_LDB(B0, 1, 0); PG8_LDB(B1, 1, 1); PG8_SCHED; PG8_LDA(At, 1, 0); PG8_STAGE(PG8_SA(0, 1), a2 + hstep, voffA);
;             PG8_WAIT_V(8); PG8_WAIT_L(0); PG8_BAR; PG8_MMA(0, 0, At, B0); PG8_MMA(0, 1, At, B1); PG8_BAR; PG8_SCHED;
;             PG8_LDA(At, 1, 1); PG8_STAGE(PG8_SB(1, 0), b3, voffB); PG8_STAGE(PG8_SB(1, 1), b3 + hstepB, voffB); PG8_STAGE(PG8_SA(1, 0), a3, voffA);
;             PG8_WAIT_V(8); PG8_WAIT_L(0); PG8_BAR; PG8_MMA(1, 0, At, B0); PG8_MMA(1, 1, At, B1); PG8_BAR; PG8_SCHED;
	s_add_i32 s9, s9, s0
	s_mov_b32 m0, s9
	ds_read_b128 v[182:185], v165 offset:49152
	ds_read_b128 v[206:209], v165 offset:50176
	ds_read_b128 v[210:213], v165 offset:51200
	ds_read_b128 v[214:217], v165 offset:52224
	ds_read_b128 v[218:221], v165 offset:53248
	ds_read_b128 v[236:239], v165 offset:54272
	ds_read_b128 v[240:243], v165 offset:55296
	ds_read_b128 v[244:247], v165 offset:56320
	s_add_u32 s100, s80, s60
	s_addc_u32 s101, s81, s61
	global_load_lds_dwordx4 v132, s[100:101]
	s_add_i32 m0, s9, 0x2000
	s_add_u32 s10, s80, 0x20080
	s_addc_u32 s11, s81, 0
	s_add_i32 s9, s12, s0
	global_load_lds_dwordx4 v136, s[100:101]
	s_mov_b32 m0, s9
	s_nop 0
	global_load_lds_dwordx4 v132, s[10:11]
	s_add_i32 m0, s9, 0x2000
	s_nop 0
	global_load_lds_dwordx4 v136, s[10:11]
	s_mov_b32 m0, s66
	s_add_u32 s100, s84, s60
	s_addc_u32 s101, s85, s61
	global_load_lds_dwordx4 v130, s[100:101]
	s_mov_b32 m0, s67
	s_nop 0
	global_load_lds_dwordx4 v134, s[100:101]
	s_waitcnt vmcnt(8)
	s_waitcnt lgkmcnt(0)
	s_barrier
	v_mfma_f32_16x16x32_bf16 v[62:65], v[148:151], v[182:185], v[62:65]
	v_mfma_f32_16x16x32_bf16 v[58:61], v[156:159], v[182:185], v[58:61]
	v_mfma_f32_16x16x32_bf16 v[50:53], v[156:159], v[210:213], v[50:53]
	v_mfma_f32_16x16x32_bf16 v[54:57], v[148:151], v[210:213], v[54:57]
	v_mfma_f32_16x16x32_bf16 v[22:25], v[166:169], v[210:213], v[22:25]
	v_mfma_f32_16x16x32_bf16 v[18:21], v[174:177], v[210:213], v[18:21]
	v_mfma_f32_16x16x32_bf16 v[26:29], v[174:177], v[182:185], v[26:29]
	v_mfma_f32_16x16x32_bf16 v[30:33], v[166:169], v[182:185], v[30:33]
	v_mfma_f32_16x16x32_bf16 v[14:17], v[166:169], v[218:221], v[14:17]
	v_mfma_f32_16x16x32_bf16 v[10:13], v[174:177], v[218:221], v[10:13]
	v_mfma_f32_16x16x32_bf16 v[2:5], v[174:177], v[240:243], v[2:5]
	v_mfma_f32_16x16x32_bf16 v[6:9], v[166:169], v[240:243], v[6:9]
	v_mfma_f32_16x16x32_bf16 v[38:41], v[148:151], v[240:243], v[38:41]
	v_mfma_f32_16x16x32_bf16 v[34:37], v[156:159], v[240:243], v[34:37]
	v_mfma_f32_16x16x32_bf16 v[42:45], v[156:159], v[218:221], v[42:45]
	v_mfma_f32_16x16x32_bf16 v[46:49], v[148:151], v[218:221], v[46:49]
	v_mfma_f32_16x16x32_bf16 v[62:65], v[152:155], v[206:209], v[62:65]
	v_mfma_f32_16x16x32_bf16 v[58:61], v[160:163], v[206:209], v[58:61]
	v_mfma_f32_16x16x32_bf16 v[50:53], v[160:163], v[214:217], v[50:53]
	v_mfma_f32_16x16x32_bf16 v[54:57], v[152:155], v[214:217], v[54:57]
	v_mfma_f32_16x16x32_bf16 v[22:25], v[170:173], v[214:217], v[22:25]
	v_mfma_f32_16x16x32_bf16 v[18:21], v[178:181], v[214:217], v[18:21]
	v_mfma_f32_16x16x32_bf16 v[26:29], v[178:181], v[206:209], v[26:29]
	v_mfma_f32_16x16x32_bf16 v[30:33], v[170:173], v[206:209], v[30:33]
	v_mfma_f32_16x16x32_bf16 v[14:17], v[170:173], v[236:239], v[14:17]
	v_mfma_f32_16x16x32_bf16 v[10:13], v[178:181], v[236:239], v[10:13]
	v_mfma_f32_16x16x32_bf16 v[2:5], v[178:181], v[244:247], v[2:5]
	v_mfma_f32_16x16x32_bf16 v[6:9], v[170:173], v[244:247], v[6:9]
	v_mfma_f32_16x16x32_bf16 v[38:41], v[152:155], v[244:247], v[38:41]
	v_mfma_f32_16x16x32_bf16 v[34:37], v[160:163], v[244:247], v[34:37]
	v_mfma_f32_16x16x32_bf16 v[42:45], v[160:163], v[236:239], v[42:45]
	v_mfma_f32_16x16x32_bf16 v[46:49], v[152:155], v[236:239], v[46:49]
	s_barrier
	s_add_i32 s8, s8, 2
	s_add_u32 s46, s46, 0x100
	s_addc_u32 s47, s47, 0
	s_cmp_gt_u32 s8, 29
.LBB0_170:
	s_add_u32 s9, s70, s46
	s_addc_u32 s10, s71, s47
	s_add_u32 s9, s9, 0x100
	s_addc_u32 s10, s10, 0
	s_add_u32 s100, s9, 0x7ff80
	s_addc_u32 s101, s10, 0
	s_add_u32 s11, s93, s46
	s_addc_u32 s12, s94, s47
	s_add_i32 s13, 0, 0x10000
	s_cmpk_eq_i32 s46, 0xf00
	s_cselect_b32 s85, s4, s10
	s_cselect_b32 s84, s5, s9
	s_cselect_b32 s81, s6, s12
	s_cselect_b32 s80, s7, s11
	s_add_i32 s9, 0, 0x14000
	ds_read_b128 v[148:151], v186
	ds_read_b128 v[152:155], v186 offset:1024
	ds_read_b128 v[156:159], v186 offset:2048
	ds_read_b128 v[160:163], v186 offset:3072
	ds_read_b128 v[166:169], v187
	ds_read_b128 v[170:173], v187 offset:1024
	ds_read_b128 v[174:177], v187 offset:2048
	ds_read_b128 v[178:181], v187 offset:3072
	s_add_i32 m0, s1, 0xc000
	ds_read_b128 v[182:185], v165
	ds_read_b128 v[206:209], v165 offset:1024
	ds_read_b128 v[210:213], v165 offset:2048
	ds_read_b128 v[214:217], v165 offset:3072
	ds_read_b128 v[218:221], v165 offset:4096
	ds_read_b128 v[236:239], v165 offset:5120
	ds_read_b128 v[240:243], v165 offset:6144
	ds_read_b128 v[244:247], v165 offset:7168
	global_load_lds_dwordx4 v140, s[100:101]
	s_add_i32 m0, s1, 0xe000
	s_nop 0
	global_load_lds_dwordx4 v142, s[100:101]
	s_waitcnt vmcnt(8)
	s_waitcnt lgkmcnt(0)
	s_barrier
; #define PG8_STAGE(bufoff, gbase, voff) do { _Pragma("unroll") for (int _i = 0; _i < 2; ++_i) \
;         __builtin_amdgcn_global_load_lds((const unsigned*)((const char*)(gbase) + (voff)[_i]), (PG8_LAS unsigned*)(lds + (bufoff) + ldsw + _i * 8192), 16, 0, 0); } while (0)
; #define PG8_LDA(dst, b, h) do { _Pragma("unroll") for (int m = 0; m < 4; ++m) _Pragma("unroll") for (int k = 0; k < 2; ++k) dst[m][k] = *(const PG8_LAS bf16x8*)(lds + PG8_SA(b, h) + aoff + m * 2048 + k * 1024); } while (0)
; #define PG8_MMA(ai, bj, At, Bt) do { __builtin_amdgcn_s_setprio(1); _Pragma("unroll") for (int m = 0; m < 4; ++m) _Pragma("unroll") for (int n = 0; n < 2; ++n) _Pragma("unroll") for (int k = 0; k < 2; ++k) \
;         acc[ai][bj][m][n] = __builtin_amdgcn_mfma_f32_16x16x32_bf16(Bt[n][k], At[m][k], acc[ai][bj][m][n], 0, 0, 0); __builtin_amdgcn_s_setprio(0); } while (0)
; #define PG8_WAIT_V(n) asm volatile("s_waitcnt vmcnt(" #n ")" ::: "memory")
; #define PG8_WAIT_L(n) asm volatile("s_waitcnt lgkmcnt(" #n ")" ::: "memory")
; #define PG8_BAR __builtin_amdgcn_s_barrier()
; #define PG8_SCHED __builtin_amdgcn_sched_barrier(0)
; template <class Epi, class Sched, bool ALIGN_EPI = false, bool SP2 = false>
; __device__ __forceinline__ void gemm_phase(PG8_LAS unsigned char* lds, const Gemm g, const Sched& S, const Epi& E) {
;     ...
;             PG8_WAIT_V(8); PG8_WAIT_L(0); PG8_BAR; PG8_MMA(0, 0, At, B0); PG8_MMA(0, 1, At, B1); PG8_BAR; PG8_SCHED;
;             PG8_LDA(At, 0, 1); PG8_STAGE(PG8_SB(0, 0), b2, voffB); PG8_STAGE(PG8_SB(0, 1), b2 + hstepB, voffB); PG8_STAGE(PG8_SA(0, 0), a2, voffA);
;             PG8_WAIT_V(8); PG8_WAIT_L(0); PG8_BAR; PG8_MMA(1, 0, At, B0); PG8_MMA(1, 1, At, B1); PG8_BAR; PG8_SCHED;
	v_mfma_f32_16x16x32_bf16 v[126:129], v[148:151], v[182:185], v[126:129]
	v_mfma_f32_16x16x32_bf16 v[122:125], v[156:159], v[182:185], v[122:125]
	v_mfma_f32_16x16x32_bf16 v[114:117], v[156:159], v[210:213], v[114:117]
	v_mfma_f32_16x16x32_bf16 v[118:121], v[148:151], v[210:213], v[118:121]
	v_mfma_f32_16x16x32_bf16 v[86:89], v[166:169], v[210:213], v[86:89]
	v_mfma_f32_16x16x32_bf16 v[82:85], v[174:177], v[210:213], v[82:85]
	v_mfma_f32_16x16x32_bf16 v[90:93], v[174:177], v[182:185], v[90:93]
	v_mfma_f32_16x16x32_bf16 v[94:97], v[166:169], v[182:185], v[94:97]
	v_mfma_f32_16x16x32_bf16 v[78:81], v[166:169], v[218:221], v[78:81]
	v_mfma_f32_16x16x32_bf16 v[74:77], v[174:177], v[218:221], v[74:77]
	v_mfma_f32_16x16x32_bf16 v[66:69], v[174:177], v[240:243], v[66:69]
	v_mfma_f32_16x16x32_bf16 v[70:73], v[166:169], v[240:243], v[70:73]
	v_mfma_f32_16x16x32_bf16 v[102:105], v[148:151], v[240:243], v[102:105]
	v_mfma_f32_16x16x32_bf16 v[98:101], v[156:159], v[240:243], v[98:101]
	v_mfma_f32_16x16x32_bf16 v[106:109], v[156:159], v[218:221], v[106:109]
	v_mfma_f32_16x16x32_bf16 v[110:113], v[148:151], v[218:221], v[110:113]
	v_mfma_f32_16x16x32_bf16 v[126:129], v[152:155], v[206:209], v[126:129]
	v_mfma_f32_16x16x32_bf16 v[122:125], v[160:163], v[206:209], v[122:125]
	v_mfma_f32_16x16x32_bf16 v[114:117], v[160:163], v[214:217], v[114:117]
	v_mfma_f32_16x16x32_bf16 v[118:121], v[152:155], v[214:217], v[118:121]
	v_mfma_f32_16x16x32_bf16 v[86:89], v[170:173], v[214:217], v[86:89]
	v_mfma_f32_16x16x32_bf16 v[82:85], v[178:181], v[214:217], v[82:85]
	v_mfma_f32_16x16x32_bf16 v[90:93], v[178:181], v[206:209], v[90:93]
	v_mfma_f32_16x16x32_bf16 v[94:97], v[170:173], v[206:209], v[94:97]
	v_mfma_f32_16x16x32_bf16 v[78:81], v[170:173], v[236:239], v[78:81]
	v_mfma_f32_16x16x32_bf16 v[74:77], v[178:181], v[236:239], v[74:77]
	v_mfma_f32_16x16x32_bf16 v[66:69], v[178:181], v[244:247], v[66:69]
	v_mfma_f32_16x16x32_bf16 v[70:73], v[170:173], v[244:247], v[70:73]
	v_mfma_f32_16x16x32_bf16 v[102:105], v[152:155], v[244:247], v[102:105]
	v_mfma_f32_16x16x32_bf16 v[98:101], v[160:163], v[244:247], v[98:101]
	v_mfma_f32_16x16x32_bf16 v[106:109], v[160:163], v[236:239], v[106:109]
	v_mfma_f32_16x16x32_bf16 v[110:113], v[152:155], v[236:239], v[110:113]
	s_barrier
	s_add_i32 s10, s13, s0
	s_mov_b32 m0, s10
	ds_read_b128 v[182:185], v165 offset:16384
	ds_read_b128 v[206:209], v165 offset:17408
	ds_read_b128 v[210:213], v165 offset:18432
	ds_read_b128 v[214:217], v165 offset:19456
	ds_read_b128 v[218:221], v165 offset:20480
	ds_read_b128 v[236:239], v165 offset:21504
	ds_read_b128 v[240:243], v165 offset:22528
	ds_read_b128 v[244:247], v165 offset:23552
	global_load_lds_dwordx4 v132, s[80:81]
	s_add_i32 m0, s10, 0x2000
	s_add_u32 s10, s80, 0x20000
	s_addc_u32 s11, s81, 0
	s_add_i32 s9, s9, s0
	global_load_lds_dwordx4 v136, s[80:81]
	s_mov_b32 m0, s9
	s_nop 0
	global_load_lds_dwordx4 v132, s[10:11]
	s_add_i32 m0, s9, 0x2000
	s_nop 0
	global_load_lds_dwordx4 v136, s[10:11]
	s_mov_b32 m0, s1
	s_nop 0
	global_load_lds_dwordx4 v130, s[84:85]
	s_mov_b32 m0, s25
	s_nop 0
	global_load_lds_dwordx4 v134, s[84:85]
	s_waitcnt vmcnt(8)
	s_waitcnt lgkmcnt(0)
	s_barrier
	v_mfma_f32_16x16x32_bf16 v[62:65], v[148:151], v[182:185], v[62:65]
	v_mfma_f32_16x16x32_bf16 v[58:61], v[156:159], v[182:185], v[58:61]
	v_mfma_f32_16x16x32_bf16 v[50:53], v[156:159], v[210:213], v[50:53]
	v_mfma_f32_16x16x32_bf16 v[54:57], v[148:151], v[210:213], v[54:57]
	v_mfma_f32_16x16x32_bf16 v[22:25], v[166:169], v[210:213], v[22:25]
	v_mfma_f32_16x16x32_bf16 v[18:21], v[174:177], v[210:213], v[18:21]
	v_mfma_f32_16x16x32_bf16 v[26:29], v[174:177], v[182:185], v[26:29]
	v_mfma_f32_16x16x32_bf16 v[30:33], v[166:169], v[182:185], v[30:33]
	v_mfma_f32_16x16x32_bf16 v[14:17], v[166:169], v[218:221], v[14:17]
	v_mfma_f32_16x16x32_bf16 v[10:13], v[174:177], v[218:221], v[10:13]
	v_mfma_f32_16x16x32_bf16 v[2:5], v[174:177], v[240:243], v[2:5]
	v_mfma_f32_16x16x32_bf16 v[6:9], v[166:169], v[240:243], v[6:9]
	v_mfma_f32_16x16x32_bf16 v[38:41], v[148:151], v[240:243], v[38:41]
	v_mfma_f32_16x16x32_bf16 v[34:37], v[156:159], v[240:243], v[34:37]
	v_mfma_f32_16x16x32_bf16 v[42:45], v[156:159], v[218:221], v[42:45]
	v_mfma_f32_16x16x32_bf16 v[46:49], v[148:151], v[218:221], v[46:49]
	v_mfma_f32_16x16x32_bf16 v[62:65], v[152:155], v[206:209], v[62:65]
	v_mfma_f32_16x16x32_bf16 v[58:61], v[160:163], v[206:209], v[58:61]
	v_mfma_f32_16x16x32_bf16 v[50:53], v[160:163], v[214:217], v[50:53]
	v_mfma_f32_16x16x32_bf16 v[54:57], v[152:155], v[214:217], v[54:57]
	v_mfma_f32_16x16x32_bf16 v[22:25], v[170:173], v[214:217], v[22:25]
	v_mfma_f32_16x16x32_bf16 v[18:21], v[178:181], v[214:217], v[18:21]
	v_mfma_f32_16x16x32_bf16 v[26:29], v[178:181], v[206:209], v[26:29]
	v_mfma_f32_16x16x32_bf16 v[30:33], v[170:173], v[206:209], v[30:33]
	v_mfma_f32_16x16x32_bf16 v[14:17], v[170:173], v[236:239], v[14:17]
	v_mfma_f32_16x16x32_bf16 v[10:13], v[178:181], v[236:239], v[10:13]
	v_mfma_f32_16x16x32_bf16 v[2:5], v[178:181], v[244:247], v[2:5]
	v_mfma_f32_16x16x32_bf16 v[6:9], v[170:173], v[244:247], v[6:9]
	v_mfma_f32_16x16x32_bf16 v[38:41], v[152:155], v[244:247], v[38:41]
	v_mfma_f32_16x16x32_bf16 v[34:37], v[160:163], v[244:247], v[34:37]
	v_mfma_f32_16x16x32_bf16 v[42:45], v[160:163], v[236:239], v[42:45]
	v_mfma_f32_16x16x32_bf16 v[46:49], v[152:155], v[236:239], v[46:49]
	s_barrier
; #define PG8_STAGE(bufoff, gbase, voff) do { _Pragma("unroll") for (int _i = 0; _i < 2; ++_i) \
;         __builtin_amdgcn_global_load_lds((const unsigned*)((const char*)(gbase) + (voff)[_i]), (PG8_LAS unsigned*)(lds + (bufoff) + ldsw + _i * 8192), 16, 0, 0); } while (0)
; #define PG8_LDA(dst, b, h) do { _Pragma("unroll") for (int m = 0; m < 4; ++m) _Pragma("unroll") for (int k = 0; k < 2; ++k) dst[m][k] = *(const PG8_LAS bf16x8*)(lds + PG8_SA(b, h) + aoff + m * 2048 + k * 1024); } while (0)
; #define PG8_LDB(dst, b, h) do { _Pragma("unroll") for (int n = 0; n < 2; ++n) _Pragma("unroll") for (int k = 0; k < 2; ++k) dst[n][k] = *(const PG8_LAS bf16x8*)(lds + PG8_SB(b, h) + boff + n * 2048 + k * 1024); } while (0)
; #define PG8_MMA(ai, bj, At, Bt) do { __builtin_amdgcn_s_setprio(1); _Pragma("unroll") for (int m = 0; m < 4; ++m) _Pragma("unroll") for (int n = 0; n < 2; ++n) _Pragma("unroll") for (int k = 0; k < 2; ++k) \
;         acc[ai][bj][m][n] = __builtin_amdgcn_mfma_f32_16x16x32_bf16(Bt[n][k], At[m][k], acc[ai][bj][m][n], 0, 0, 0); __builtin_amdgcn_s_setprio(0); } while (0)
; #define PG8_WAIT_V(n) asm volatile("s_waitcnt vmcnt(" #n ")" ::: "memory")
; #define PG8_WAIT_L(n) asm volatile("s_waitcnt lgkmcnt(" #n ")" ::: "memory")
; #define PG8_BAR __builtin_amdgcn_s_barrier()
; #define PG8_SCHED __builtin_amdgcn_sched_barrier(0)
; template <class Epi, class Sched, bool ALIGN_EPI = false, bool SP2 = false>
; __device__ __forceinline__ void gemm_phase(PG8_LAS unsigned char* lds, const Gemm g, const Sched& S, const Epi& E) {
;     ...
;             PG8_LDB(B0, 1, 0); PG8_LDB(B1, 1, 1); PG8_SCHED; PG8_LDA(At, 1, 0); PG8_STAGE(PG8_SA(0, 1), a2 + hstep, voffA);
;             PG8_WAIT_V(8); PG8_WAIT_L(0); PG8_BAR; PG8_MMA(0, 0, At, B0); PG8_MMA(0, 1, At, B1); PG8_BAR; PG8_SCHED;
;             PG8_LDA(At, 1, 1); PG8_STAGE(PG8_SB(1, 0), b3, voffB); PG8_STAGE(PG8_SB(1, 1), b3 + hstepB, voffB); PG8_STAGE(PG8_SA(1, 0), a3, voffA);
;             PG8_WAIT_V(8); PG8_WAIT_L(0); PG8_BAR; PG8_MMA(1, 0, At, B0); PG8_MMA(1, 1, At, B1); PG8_BAR; PG8_SCHED;
;     ...
;         if constexpr (ALIGN_EPI) { if (wr == 0) PG8_BAR; }
	s_add_i32 s9, 0, 0x18000
	s_add_i32 s12, 0, 0x1c000
	ds_read_b128 v[148:151], v198
	ds_read_b128 v[152:155], v198 offset:1024
	ds_read_b128 v[156:159], v198 offset:2048
	ds_read_b128 v[160:163], v198 offset:3072
	ds_read_b128 v[166:169], v199
	ds_read_b128 v[170:173], v199 offset:1024
	ds_read_b128 v[174:177], v199 offset:2048
	ds_read_b128 v[178:181], v199 offset:3072
	s_add_u32 s10, s84, 0x80000
	s_addc_u32 s11, s85, 0
	s_mov_b32 m0, s42
	ds_read_b128 v[182:185], v165 offset:32768
	ds_read_b128 v[206:209], v165 offset:33792
	ds_read_b128 v[210:213], v165 offset:34816
	ds_read_b128 v[214:217], v165 offset:35840
	ds_read_b128 v[218:221], v165 offset:36864
	ds_read_b128 v[236:239], v165 offset:37888
	ds_read_b128 v[240:243], v165 offset:38912
	ds_read_b128 v[244:247], v165 offset:39936
	global_load_lds_dwordx4 v130, s[10:11]
	s_mov_b32 m0, s51
	s_nop 0
	global_load_lds_dwordx4 v134, s[10:11]
	s_waitcnt vmcnt(8)
	s_waitcnt lgkmcnt(0)
	s_barrier
	v_mfma_f32_16x16x32_bf16 v[126:129], v[148:151], v[182:185], v[126:129]
	v_mfma_f32_16x16x32_bf16 v[122:125], v[156:159], v[182:185], v[122:125]
	v_mfma_f32_16x16x32_bf16 v[114:117], v[156:159], v[210:213], v[114:117]
	v_mfma_f32_16x16x32_bf16 v[118:121], v[148:151], v[210:213], v[118:121]
	v_mfma_f32_16x16x32_bf16 v[86:89], v[166:169], v[210:213], v[86:89]
	v_mfma_f32_16x16x32_bf16 v[82:85], v[174:177], v[210:213], v[82:85]
	v_mfma_f32_16x16x32_bf16 v[90:93], v[174:177], v[182:185], v[90:93]
	v_mfma_f32_16x16x32_bf16 v[94:97], v[166:169], v[182:185], v[94:97]
	v_mfma_f32_16x16x32_bf16 v[78:81], v[166:169], v[218:221], v[78:81]
	v_mfma_f32_16x16x32_bf16 v[74:77], v[174:177], v[218:221], v[74:77]
	v_mfma_f32_16x16x32_bf16 v[66:69], v[174:177], v[240:243], v[66:69]
	v_mfma_f32_16x16x32_bf16 v[70:73], v[166:169], v[240:243], v[70:73]
	v_mfma_f32_16x16x32_bf16 v[102:105], v[148:151], v[240:243], v[102:105]
	v_mfma_f32_16x16x32_bf16 v[98:101], v[156:159], v[240:243], v[98:101]
	v_mfma_f32_16x16x32_bf16 v[106:109], v[156:159], v[218:221], v[106:109]
	v_mfma_f32_16x16x32_bf16 v[110:113], v[148:151], v[218:221], v[110:113]
	v_mfma_f32_16x16x32_bf16 v[126:129], v[152:155], v[206:209], v[126:129]
	v_mfma_f32_16x16x32_bf16 v[122:125], v[160:163], v[206:209], v[122:125]
	v_mfma_f32_16x16x32_bf16 v[114:117], v[160:163], v[214:217], v[114:117]
	v_mfma_f32_16x16x32_bf16 v[118:121], v[152:155], v[214:217], v[118:121]
	v_mfma_f32_16x16x32_bf16 v[86:89], v[170:173], v[214:217], v[86:89]
	v_mfma_f32_16x16x32_bf16 v[82:85], v[178:181], v[214:217], v[82:85]
	v_mfma_f32_16x16x32_bf16 v[90:93], v[178:181], v[206:209], v[90:93]
	v_mfma_f32_16x16x32_bf16 v[94:97], v[170:173], v[206:209], v[94:97]
	v_mfma_f32_16x16x32_bf16 v[78:81], v[170:173], v[236:239], v[78:81]
	v_mfma_f32_16x16x32_bf16 v[74:77], v[178:181], v[236:239], v[74:77]
	v_mfma_f32_16x16x32_bf16 v[66:69], v[178:181], v[244:247], v[66:69]
	v_mfma_f32_16x16x32_bf16 v[70:73], v[170:173], v[244:247], v[70:73]
	v_mfma_f32_16x16x32_bf16 v[102:105], v[152:155], v[244:247], v[102:105]
	v_mfma_f32_16x16x32_bf16 v[98:101], v[160:163], v[244:247], v[98:101]
	v_mfma_f32_16x16x32_bf16 v[106:109], v[160:163], v[236:239], v[106:109]
	v_mfma_f32_16x16x32_bf16 v[110:113], v[152:155], v[236:239], v[110:113]
	s_barrier
	s_add_i32 s9, s9, s0
	s_mov_b32 m0, s9
	ds_read_b128 v[182:185], v165 offset:49152
	ds_read_b128 v[206:209], v165 offset:50176
	ds_read_b128 v[210:213], v165 offset:51200
	ds_read_b128 v[214:217], v165 offset:52224
	ds_read_b128 v[218:221], v165 offset:53248
	ds_read_b128 v[236:239], v165 offset:54272
	ds_read_b128 v[240:243], v165 offset:55296
	ds_read_b128 v[244:247], v165 offset:56320
	s_add_u32 s100, s80, s60
	s_addc_u32 s101, s81, s61
	global_load_lds_dwordx4 v132, s[100:101]
	s_add_i32 m0, s9, 0x2000
	s_add_u32 s10, s80, 0x20080
	s_addc_u32 s11, s81, 0
	s_add_i32 s9, s12, s0
	global_load_lds_dwordx4 v136, s[100:101]
	s_mov_b32 m0, s9
	s_nop 0
	global_load_lds_dwordx4 v132, s[10:11]
	s_add_i32 m0, s9, 0x2000
	s_nop 0
	global_load_lds_dwordx4 v136, s[10:11]
	s_mov_b32 m0, s66
	s_add_u32 s100, s84, s60
	s_addc_u32 s101, s85, s61
	global_load_lds_dwordx4 v130, s[100:101]
	s_mov_b32 m0, s67
	s_nop 0
	global_load_lds_dwordx4 v134, s[100:101]
	s_waitcnt vmcnt(8)
	s_waitcnt lgkmcnt(0)
	s_barrier
	v_mfma_f32_16x16x32_bf16 v[62:65], v[148:151], v[182:185], v[62:65]
	v_mfma_f32_16x16x32_bf16 v[58:61], v[156:159], v[182:185], v[58:61]
	v_mfma_f32_16x16x32_bf16 v[50:53], v[156:159], v[210:213], v[50:53]
	v_mfma_f32_16x16x32_bf16 v[54:57], v[148:151], v[210:213], v[54:57]
	v_mfma_f32_16x16x32_bf16 v[22:25], v[166:169], v[210:213], v[22:25]
	v_mfma_f32_16x16x32_bf16 v[18:21], v[174:177], v[210:213], v[18:21]
	v_mfma_f32_16x16x32_bf16 v[26:29], v[174:177], v[182:185], v[26:29]
	v_mfma_f32_16x16x32_bf16 v[30:33], v[166:169], v[182:185], v[30:33]
	v_mfma_f32_16x16x32_bf16 v[14:17], v[166:169], v[218:221], v[14:17]
	v_mfma_f32_16x16x32_bf16 v[10:13], v[174:177], v[218:221], v[10:13]
	v_mfma_f32_16x16x32_bf16 v[2:5], v[174:177], v[240:243], v[2:5]
	v_mfma_f32_16x16x32_bf16 v[6:9], v[166:169], v[240:243], v[6:9]
	v_mfma_f32_16x16x32_bf16 v[38:41], v[148:151], v[240:243], v[38:41]
	v_mfma_f32_16x16x32_bf16 v[34:37], v[156:159], v[240:243], v[34:37]
	v_mfma_f32_16x16x32_bf16 v[42:45], v[156:159], v[218:221], v[42:45]
	v_mfma_f32_16x16x32_bf16 v[46:49], v[148:151], v[218:221], v[46:49]
	v_mfma_f32_16x16x32_bf16 v[62:65], v[152:155], v[206:209], v[62:65]
	v_mfma_f32_16x16x32_bf16 v[58:61], v[160:163], v[206:209], v[58:61]
	v_mfma_f32_16x16x32_bf16 v[50:53], v[160:163], v[214:217], v[50:53]
	v_mfma_f32_16x16x32_bf16 v[54:57], v[152:155], v[214:217], v[54:57]
	v_mfma_f32_16x16x32_bf16 v[22:25], v[170:173], v[214:217], v[22:25]
	v_mfma_f32_16x16x32_bf16 v[18:21], v[178:181], v[214:217], v[18:21]
	v_mfma_f32_16x16x32_bf16 v[26:29], v[178:181], v[206:209], v[26:29]
	v_mfma_f32_16x16x32_bf16 v[30:33], v[170:173], v[206:209], v[30:33]
	v_mfma_f32_16x16x32_bf16 v[14:17], v[170:173], v[236:239], v[14:17]
	v_mfma_f32_16x16x32_bf16 v[10:13], v[178:181], v[236:239], v[10:13]
	v_mfma_f32_16x16x32_bf16 v[2:5], v[178:181], v[244:247], v[2:5]
	v_mfma_f32_16x16x32_bf16 v[6:9], v[170:173], v[244:247], v[6:9]
	v_mfma_f32_16x16x32_bf16 v[38:41], v[152:155], v[244:247], v[38:41]
	v_mfma_f32_16x16x32_bf16 v[34:37], v[160:163], v[244:247], v[34:37]
	v_mfma_f32_16x16x32_bf16 v[42:45], v[160:163], v[236:239], v[42:45]
	v_mfma_f32_16x16x32_bf16 v[46:49], v[152:155], v[236:239], v[46:49]
	s_barrier
	s_add_i32 s8, s8, 2
	s_add_u32 s46, s46, 0x100
	s_addc_u32 s47, s47, 0
	s_cmp_gt_u32 s8, 29
	s_cbranch_scc0 .LBB0_170
	s_and_b64 vcc, exec, s[54:55]
	s_cbranch_vccz .LBB0_173
	s_barrier

; #define PG8_STAGE(bufoff, gbase, voff) do { _Pragma("unroll") for (int _i = 0; _i < 2; ++_i) \
;         __builtin_amdgcn_global_load_lds((const unsigned*)((const char*)(gbase) + (voff)[_i]), (PG8_LAS unsigned*)(lds + (bufoff) + ldsw + _i * 8192), 16, 0, 0); } while (0)
; #define PG8_LDA(dst, b, h) do { _Pragma("unroll") for (int m = 0; m < 4; ++m) _Pragma("unroll") for (int k = 0; k < 2; ++k) dst[m][k] = *(const PG8_LAS bf16x8*)(lds + PG8_SA(b, h) + aoff + m * 2048 + k * 1024); } while (0)
; #define PG8_LDB(dst, b, h) do { _Pragma("unroll") for (int n = 0; n < 2; ++n) _Pragma("unroll") for (int k = 0; k < 2; ++k) dst[n][k] = *(const PG8_LAS bf16x8*)(lds + PG8_SB(b, h) + boff + n * 2048 + k * 1024); } while (0)
; #define PG8_MMA(ai, bj, At, Bt) do { __builtin_amdgcn_s_setprio(1); _Pragma("unroll") for (int m = 0; m < 4; ++m) _Pragma("unroll") for (int n = 0; n < 2; ++n) _Pragma("unroll") for (int k = 0; k < 2; ++k) \
;         acc[ai][bj][m][n] = __builtin_amdgcn_mfma_f32_16x16x32_bf16(Bt[n][k], At[m][k], acc[ai][bj][m][n], 0, 0, 0); __builtin_amdgcn_s_setprio(0); } while (0)
; #define PG8_WAIT_V(n) asm volatile("s_waitcnt vmcnt(" #n ")" ::: "memory")
; #define PG8_WAIT_L(n) asm volatile("s_waitcnt lgkmcnt(" #n ")" ::: "memory")
; #define PG8_BAR __builtin_amdgcn_s_barrier()
; template <class Epi, class Sched, bool ALIGN_EPI = false, bool SP2 = false>
; __device__ __forceinline__ void gemm_phase(PG8_LAS unsigned char* lds, const Gemm g, const Sched& S, const Epi& E) {
;     ...
;         const bool has_next = S.next(ui + 1, nxt);
;         const char* nA = has_next ? (const char*)g.A + (size_t)nxt.pm * tstep : cA; const char* nB = has_next ? (const char*)g.Bt + (size_t)nxt.pn * tstep : cB;
;         for (int t = 0; t < nt; t += 2) {
;             const bool last = (t == nt - 2);
;             const char* a1 = cA + (size_t)(t + 1) * kstep;
;             const char* a2 = last ? nA : cA + (size_t)(t + 2) * kstep; const char* b2 = last ? nB : cB + (size_t)(t + 2) * kstep;
;             const char* a3 = a2 + kstep; const char* b3 = b2 + kstep;
;             if (last && has_next) S.a_ready(nxt);
;             if constexpr (SP2) {
;             PG8_LDB(B0, 0, 0); PG8_LDB(B1, 0, 1); PG8_SCHED; PG8_LDA(At, 0, 0); PG8_STAGE(PG8_SA(1, 1), a1 + hstep, voffA);
;             PG8_WAIT_V(8); PG8_WAIT_L(0); PG8_BAR; PG8_MMA(0, 0, At, B0); PG8_MMA(0, 1, At, B1); PG8_BAR; PG8_SCHED;
.LBB0_926:
	s_ashr_i32 s73, s72, 31
	s_lshl_b64 s[4:5], s[72:73], 20
	v_readlane_b32 s6, v249, 9
	v_readlane_b32 s7, v249, 10
	s_add_u32 s76, s6, s4
	s_addc_u32 s77, s7, s5
	s_and_b64 s[4:5], s[92:93], exec
	s_cselect_b32 s36, s77, s39
	s_cselect_b32 s37, s76, s38
	s_ashr_i32 s69, s68, 31
	s_lshl_b64 s[4:5], s[68:69], 20
	v_readlane_b32 s6, v249, 17
	v_readlane_b32 s7, v249, 18
	s_add_u32 s80, s6, s4
	s_addc_u32 s81, s7, s5
	s_and_b64 s[4:5], s[92:93], exec
	s_cselect_b32 s4, s81, s47
	s_cselect_b32 s5, s80, s46
	s_add_u32 s38, s38, 0x80080
	s_addc_u32 s39, s39, 0
	s_add_u32 s6, s46, 0x100
	v_mov_b32_e32 v2, 0
	s_addc_u32 s7, s47, 0
	s_mov_b32 s8, -2
	v_mov_b32_e32 v3, v2
	v_mov_b32_e32 v4, v2
	v_mov_b32_e32 v5, v2
	v_mov_b32_e32 v6, v2
	v_mov_b32_e32 v7, v2
	v_mov_b32_e32 v8, v2
	v_mov_b32_e32 v9, v2
	v_mov_b32_e32 v18, v2
	v_mov_b32_e32 v19, v2
	v_mov_b32_e32 v20, v2
	v_mov_b32_e32 v21, v2
	v_mov_b32_e32 v22, v2
	v_mov_b32_e32 v23, v2
	v_mov_b32_e32 v24, v2
	v_mov_b32_e32 v25, v2
	v_mov_b32_e32 v34, v2
	s_waitcnt lgkmcnt(0)
	v_add_u32_e32 v186, 0x10000, v193
	v_add_u32_e32 v187, 0x14000, v193
	v_add_u32_e32 v198, 0x18000, v193
	v_add_u32_e32 v199, 0x1c000, v193
	s_add_u32 s9, s38, 0xfff80080
	s_addc_u32 s10, s39, -1
	s_add_i32 s11, 0, 0x10000
	s_cmp_eq_u32 s8, 28
	s_cselect_b32 s95, s36, s10
	s_cselect_b32 s94, s37, s9
	s_cselect_b32 s47, s4, s7
	s_cselect_b32 s46, s5, s6
	s_add_i32 s9, 0, 0x14000
	ds_read_b128 v[66:69], v186
	ds_read_b128 v[70:73], v186 offset:1024
	ds_read_b128 v[78:81], v186 offset:2048
	ds_read_b128 v[86:89], v186 offset:3072
	ds_read_b128 v[146:149], v187
	ds_read_b128 v[150:153], v187 offset:1024
	ds_read_b128 v[154:157], v187 offset:2048
	ds_read_b128 v[158:161], v187 offset:3072
	s_add_i32 m0, s66, 0xc000
	ds_read_b128 v[162:165], v236
	ds_read_b128 v[166:169], v236 offset:1024
	ds_read_b128 v[170:173], v236 offset:2048
	ds_read_b128 v[174:177], v236 offset:3072
	ds_read_b128 v[178:181], v236 offset:4096
	ds_read_b128 v[182:185], v236 offset:5120
	ds_read_b128 v[216:219], v236 offset:6144
	ds_read_b128 v[220:223], v236 offset:7168
	global_load_lds_dwordx4 v212, s[38:39]
	s_add_i32 m0, s66, 0xe000
	s_nop 0
	global_load_lds_dwordx4 v214, s[38:39]
	s_waitcnt vmcnt(8)
	s_waitcnt lgkmcnt(0)
	s_barrier
	v_mfma_f32_16x16x32_bf16 v[142:145], v[66:69], v[162:165], 0
	v_mfma_f32_16x16x32_bf16 v[138:141], v[78:81], v[162:165], 0
	v_mfma_f32_16x16x32_bf16 v[122:125], v[78:81], v[170:173], 0
	v_mfma_f32_16x16x32_bf16 v[126:129], v[66:69], v[170:173], 0
	v_mfma_f32_16x16x32_bf16 v[118:121], v[146:149], v[170:173], 0
	v_mfma_f32_16x16x32_bf16 v[114:117], v[154:157], v[170:173], 0
	v_mfma_f32_16x16x32_bf16 v[130:133], v[154:157], v[162:165], 0
	v_mfma_f32_16x16x32_bf16 v[134:137], v[146:149], v[162:165], 0
	v_mfma_f32_16x16x32_bf16 v[102:105], v[146:149], v[178:181], 0
	v_mfma_f32_16x16x32_bf16 v[98:101], v[154:157], v[178:181], 0
	v_mfma_f32_16x16x32_bf16 v[74:77], v[154:157], v[216:219], 0
	v_mfma_f32_16x16x32_bf16 v[82:85], v[146:149], v[216:219], 0
	v_mfma_f32_16x16x32_bf16 v[94:97], v[66:69], v[216:219], 0
	v_mfma_f32_16x16x32_bf16 v[90:93], v[78:81], v[216:219], 0
	v_mfma_f32_16x16x32_bf16 v[106:109], v[78:81], v[178:181], 0
	v_mfma_f32_16x16x32_bf16 v[110:113], v[66:69], v[178:181], 0
	v_mfma_f32_16x16x32_bf16 v[142:145], v[70:73], v[166:169], v[142:145]
	v_mfma_f32_16x16x32_bf16 v[138:141], v[86:89], v[166:169], v[138:141]
	v_mfma_f32_16x16x32_bf16 v[122:125], v[86:89], v[174:177], v[122:125]
	v_mfma_f32_16x16x32_bf16 v[126:129], v[70:73], v[174:177], v[126:129]
	v_mfma_f32_16x16x32_bf16 v[118:121], v[150:153], v[174:177], v[118:121]
	v_mfma_f32_16x16x32_bf16 v[114:117], v[158:161], v[174:177], v[114:117]
	v_mfma_f32_16x16x32_bf16 v[130:133], v[158:161], v[166:169], v[130:133]
	v_mfma_f32_16x16x32_bf16 v[134:137], v[150:153], v[166:169], v[134:137]
	v_mfma_f32_16x16x32_bf16 v[102:105], v[150:153], v[182:185], v[102:105]
	v_mfma_f32_16x16x32_bf16 v[98:101], v[158:161], v[182:185], v[98:101]
	v_mfma_f32_16x16x32_bf16 v[74:77], v[158:161], v[220:223], v[74:77]
	v_mfma_f32_16x16x32_bf16 v[82:85], v[150:153], v[220:223], v[82:85]
	v_mfma_f32_16x16x32_bf16 v[94:97], v[70:73], v[220:223], v[94:97]
	v_mfma_f32_16x16x32_bf16 v[90:93], v[86:89], v[220:223], v[90:93]
	v_mfma_f32_16x16x32_bf16 v[106:109], v[86:89], v[182:185], v[106:109]
	v_mfma_f32_16x16x32_bf16 v[110:113], v[70:73], v[182:185], v[110:113]
	s_barrier
	s_add_i32 s10, s11, s25
	s_mov_b32 m0, s10
	ds_read_b128 v[162:165], v236 offset:16384
	ds_read_b128 v[166:169], v236 offset:17408
	ds_read_b128 v[170:173], v236 offset:18432
	ds_read_b128 v[174:177], v236 offset:19456
	ds_read_b128 v[178:181], v236 offset:20480
	ds_read_b128 v[182:185], v236 offset:21504
	ds_read_b128 v[216:219], v236 offset:22528
	ds_read_b128 v[220:223], v236 offset:23552
	global_load_lds_dwordx4 v190, s[46:47]
	s_add_i32 m0, s10, 0x2000
	s_add_u32 s10, s46, 0x20000
	s_addc_u32 s11, s47, 0
	s_add_i32 s9, s9, s25
	global_load_lds_dwordx4 v206, s[46:47]
	s_mov_b32 m0, s9
	s_nop 0
	global_load_lds_dwordx4 v190, s[10:11]
	s_add_i32 m0, s9, 0x2000
	s_nop 0
	global_load_lds_dwordx4 v206, s[10:11]
	s_mov_b32 m0, s66
	s_nop 0
	global_load_lds_dwordx4 v210, s[94:95]
	s_mov_b32 m0, s67
	s_nop 0
	global_load_lds_dwordx4 v208, s[94:95]
	s_waitcnt vmcnt(8)
	s_waitcnt lgkmcnt(0)
	s_barrier
; #define PG8_STAGE(bufoff, gbase, voff) do { _Pragma("unroll") for (int _i = 0; _i < 2; ++_i) \
;         __builtin_amdgcn_global_load_lds((const unsigned*)((const char*)(gbase) + (voff)[_i]), (PG8_LAS unsigned*)(lds + (bufoff) + ldsw + _i * 8192), 16, 0, 0); } while (0)
; #define PG8_LDA(dst, b, h) do { _Pragma("unroll") for (int m = 0; m < 4; ++m) _Pragma("unroll") for (int k = 0; k < 2; ++k) dst[m][k] = *(const PG8_LAS bf16x8*)(lds + PG8_SA(b, h) + aoff + m * 2048 + k * 1024); } while (0)
; #define PG8_LDB(dst, b, h) do { _Pragma("unroll") for (int n = 0; n < 2; ++n) _Pragma("unroll") for (int k = 0; k < 2; ++k) dst[n][k] = *(const PG8_LAS bf16x8*)(lds + PG8_SB(b, h) + boff + n * 2048 + k * 1024); } while (0)
; #define PG8_MMA(ai, bj, At, Bt) do { __builtin_amdgcn_s_setprio(1); _Pragma("unroll") for (int m = 0; m < 4; ++m) _Pragma("unroll") for (int n = 0; n < 2; ++n) _Pragma("unroll") for (int k = 0; k < 2; ++k) \
;         acc[ai][bj][m][n] = __builtin_amdgcn_mfma_f32_16x16x32_bf16(Bt[n][k], At[m][k], acc[ai][bj][m][n], 0, 0, 0); __builtin_amdgcn_s_setprio(0); } while (0)
; #define PG8_WAIT_V(n) asm volatile("s_waitcnt vmcnt(" #n ")" ::: "memory")
; #define PG8_WAIT_L(n) asm volatile("s_waitcnt lgkmcnt(" #n ")" ::: "memory")
; #define PG8_BAR __builtin_amdgcn_s_barrier()
; #define PG8_SCHED __builtin_amdgcn_sched_barrier(0)
; template <class Epi, class Sched, bool ALIGN_EPI = false, bool SP2 = false>
; __device__ __forceinline__ void gemm_phase(PG8_LAS unsigned char* lds, const Gemm g, const Sched& S, const Epi& E) {
;     ...
;             PG8_WAIT_V(8); PG8_WAIT_L(0); PG8_BAR; PG8_MMA(1, 0, At, B0); PG8_MMA(1, 1, At, B1); PG8_BAR; PG8_SCHED;
;             PG8_LDB(B0, 1, 0); PG8_LDB(B1, 1, 1); PG8_SCHED; PG8_LDA(At, 1, 0); PG8_STAGE(PG8_SA(0, 1), a2 + hstep, voffA);
;             PG8_WAIT_V(8); PG8_WAIT_L(0); PG8_BAR; PG8_MMA(0, 0, At, B0); PG8_MMA(0, 1, At, B1); PG8_BAR; PG8_SCHED;
	v_mfma_f32_16x16x32_bf16 v[62:65], v[66:69], v[162:165], 0
	v_mfma_f32_16x16x32_bf16 v[58:61], v[78:81], v[162:165], 0
	v_mfma_f32_16x16x32_bf16 v[42:45], v[78:81], v[170:173], 0
	v_mfma_f32_16x16x32_bf16 v[46:49], v[66:69], v[170:173], 0
	v_mfma_f32_16x16x32_bf16 v[38:41], v[146:149], v[170:173], 0
	v_mfma_f32_16x16x32_bf16 v[34:37], v[154:157], v[170:173], 0
	v_mfma_f32_16x16x32_bf16 v[50:53], v[154:157], v[162:165], 0
	v_mfma_f32_16x16x32_bf16 v[54:57], v[146:149], v[162:165], 0
	v_mfma_f32_16x16x32_bf16 v[22:25], v[146:149], v[178:181], 0
	v_mfma_f32_16x16x32_bf16 v[18:21], v[154:157], v[178:181], 0
	v_mfma_f32_16x16x32_bf16 v[2:5], v[154:157], v[216:219], 0
	v_mfma_f32_16x16x32_bf16 v[6:9], v[146:149], v[216:219], 0
	v_mfma_f32_16x16x32_bf16 v[14:17], v[66:69], v[216:219], 0
	v_mfma_f32_16x16x32_bf16 v[10:13], v[78:81], v[216:219], 0
	v_mfma_f32_16x16x32_bf16 v[26:29], v[78:81], v[178:181], 0
	v_mfma_f32_16x16x32_bf16 v[30:33], v[66:69], v[178:181], 0
	v_mfma_f32_16x16x32_bf16 v[62:65], v[70:73], v[166:169], v[62:65]
	v_mfma_f32_16x16x32_bf16 v[58:61], v[86:89], v[166:169], v[58:61]
	v_mfma_f32_16x16x32_bf16 v[42:45], v[86:89], v[174:177], v[42:45]
	v_mfma_f32_16x16x32_bf16 v[46:49], v[70:73], v[174:177], v[46:49]
	v_mfma_f32_16x16x32_bf16 v[38:41], v[150:153], v[174:177], v[38:41]
	v_mfma_f32_16x16x32_bf16 v[34:37], v[158:161], v[174:177], v[34:37]
	v_mfma_f32_16x16x32_bf16 v[50:53], v[158:161], v[166:169], v[50:53]
	v_mfma_f32_16x16x32_bf16 v[54:57], v[150:153], v[166:169], v[54:57]
	v_mfma_f32_16x16x32_bf16 v[22:25], v[150:153], v[182:185], v[22:25]
	v_mfma_f32_16x16x32_bf16 v[18:21], v[158:161], v[182:185], v[18:21]
	v_mfma_f32_16x16x32_bf16 v[2:5], v[158:161], v[220:223], v[2:5]
	v_mfma_f32_16x16x32_bf16 v[6:9], v[150:153], v[220:223], v[6:9]
	v_mfma_f32_16x16x32_bf16 v[14:17], v[70:73], v[220:223], v[14:17]
	v_mfma_f32_16x16x32_bf16 v[10:13], v[86:89], v[220:223], v[10:13]
	v_mfma_f32_16x16x32_bf16 v[26:29], v[86:89], v[182:185], v[26:29]
	v_mfma_f32_16x16x32_bf16 v[30:33], v[70:73], v[182:185], v[30:33]
	s_barrier
	s_add_i32 s9, 0, 0x18000
	s_add_i32 s12, 0, 0x1c000
	ds_read_b128 v[66:69], v198
	ds_read_b128 v[70:73], v198 offset:1024
	ds_read_b128 v[78:81], v198 offset:2048
	ds_read_b128 v[86:89], v198 offset:3072
	ds_read_b128 v[146:149], v199
	ds_read_b128 v[150:153], v199 offset:1024
	ds_read_b128 v[154:157], v199 offset:2048
	ds_read_b128 v[158:161], v199 offset:3072
	s_add_u32 s10, s94, 0x80000
	s_addc_u32 s11, s95, 0
	s_mov_b32 m0, s59
	ds_read_b128 v[162:165], v236 offset:32768
	ds_read_b128 v[166:169], v236 offset:33792
	ds_read_b128 v[170:173], v236 offset:34816
	ds_read_b128 v[174:177], v236 offset:35840
	ds_read_b128 v[178:181], v236 offset:36864
	ds_read_b128 v[182:185], v236 offset:37888
	ds_read_b128 v[216:219], v236 offset:38912
	ds_read_b128 v[220:223], v236 offset:39936
	global_load_lds_dwordx4 v210, s[10:11]
	s_mov_b32 m0, s74
	s_nop 0
	global_load_lds_dwordx4 v208, s[10:11]
	s_waitcnt vmcnt(8)
	s_waitcnt lgkmcnt(0)
	s_barrier
	v_mfma_f32_16x16x32_bf16 v[142:145], v[66:69], v[162:165], v[142:145]
	v_mfma_f32_16x16x32_bf16 v[138:141], v[78:81], v[162:165], v[138:141]
	v_mfma_f32_16x16x32_bf16 v[122:125], v[78:81], v[170:173], v[122:125]
	v_mfma_f32_16x16x32_bf16 v[126:129], v[66:69], v[170:173], v[126:129]
	v_mfma_f32_16x16x32_bf16 v[118:121], v[146:149], v[170:173], v[118:121]
	v_mfma_f32_16x16x32_bf16 v[114:117], v[154:157], v[170:173], v[114:117]
	v_mfma_f32_16x16x32_bf16 v[130:133], v[154:157], v[162:165], v[130:133]
	v_mfma_f32_16x16x32_bf16 v[134:137], v[146:149], v[162:165], v[134:137]
	v_mfma_f32_16x16x32_bf16 v[102:105], v[146:149], v[178:181], v[102:105]
	v_mfma_f32_16x16x32_bf16 v[98:101], v[154:157], v[178:181], v[98:101]
	v_mfma_f32_16x16x32_bf16 v[74:77], v[154:157], v[216:219], v[74:77]
	v_mfma_f32_16x16x32_bf16 v[82:85], v[146:149], v[216:219], v[82:85]
	v_mfma_f32_16x16x32_bf16 v[94:97], v[66:69], v[216:219], v[94:97]
	v_mfma_f32_16x16x32_bf16 v[90:93], v[78:81], v[216:219], v[90:93]
	v_mfma_f32_16x16x32_bf16 v[106:109], v[78:81], v[178:181], v[106:109]
	v_mfma_f32_16x16x32_bf16 v[110:113], v[66:69], v[178:181], v[110:113]
	v_mfma_f32_16x16x32_bf16 v[142:145], v[70:73], v[166:169], v[142:145]
	v_mfma_f32_16x16x32_bf16 v[138:141], v[86:89], v[166:169], v[138:141]
	v_mfma_f32_16x16x32_bf16 v[122:125], v[86:89], v[174:177], v[122:125]
	v_mfma_f32_16x16x32_bf16 v[126:129], v[70:73], v[174:177], v[126:129]
	v_mfma_f32_16x16x32_bf16 v[118:121], v[150:153], v[174:177], v[118:121]
	v_mfma_f32_16x16x32_bf16 v[114:117], v[158:161], v[174:177], v[114:117]
	v_mfma_f32_16x16x32_bf16 v[130:133], v[158:161], v[166:169], v[130:133]
	v_mfma_f32_16x16x32_bf16 v[134:137], v[150:153], v[166:169], v[134:137]
	v_mfma_f32_16x16x32_bf16 v[102:105], v[150:153], v[182:185], v[102:105]
	v_mfma_f32_16x16x32_bf16 v[98:101], v[158:161], v[182:185], v[98:101]
	v_mfma_f32_16x16x32_bf16 v[74:77], v[158:161], v[220:223], v[74:77]
	v_mfma_f32_16x16x32_bf16 v[82:85], v[150:153], v[220:223], v[82:85]
	v_mfma_f32_16x16x32_bf16 v[94:97], v[70:73], v[220:223], v[94:97]
	v_mfma_f32_16x16x32_bf16 v[90:93], v[86:89], v[220:223], v[90:93]
	v_mfma_f32_16x16x32_bf16 v[106:109], v[86:89], v[182:185], v[106:109]
	v_mfma_f32_16x16x32_bf16 v[110:113], v[70:73], v[182:185], v[110:113]
	s_barrier
; #define PG8_STAGE(bufoff, gbase, voff) do { _Pragma("unroll") for (int _i = 0; _i < 2; ++_i) \
;         __builtin_amdgcn_global_load_lds((const unsigned*)((const char*)(gbase) + (voff)[_i]), (PG8_LAS unsigned*)(lds + (bufoff) + ldsw + _i * 8192), 16, 0, 0); } while (0)
; #define PG8_LDA(dst, b, h) do { _Pragma("unroll") for (int m = 0; m < 4; ++m) _Pragma("unroll") for (int k = 0; k < 2; ++k) dst[m][k] = *(const PG8_LAS bf16x8*)(lds + PG8_SA(b, h) + aoff + m * 2048 + k * 1024); } while (0)
; #define PG8_LDB(dst, b, h) do { _Pragma("unroll") for (int n = 0; n < 2; ++n) _Pragma("unroll") for (int k = 0; k < 2; ++k) dst[n][k] = *(const PG8_LAS bf16x8*)(lds + PG8_SB(b, h) + boff + n * 2048 + k * 1024); } while (0)
; template <class Epi, class Sched, bool ALIGN_EPI = false, bool SP2 = false>
; __device__ __forceinline__ void gemm_phase(PG8_LAS unsigned char* lds, const Gemm g, const Sched& S, const Epi& E) {
;     ...
;         for (int t = 0; t < nt; t += 2) {
;             const bool last = (t == nt - 2);
;             const char* a1 = cA + (size_t)(t + 1) * kstep;
;             const char* a2 = last ? nA : cA + (size_t)(t + 2) * kstep; const char* b2 = last ? nB : cB + (size_t)(t + 2) * kstep;
;             const char* a3 = a2 + kstep; const char* b3 = b2 + kstep;
;             if (last && has_next) S.a_ready(nxt);
;             if constexpr (SP2) {
;             PG8_LDB(B0, 0, 0); PG8_LDB(B1, 0, 1); PG8_SCHED; PG8_LDA(At, 0, 0); PG8_STAGE(PG8_SA(1, 1), a1 + hstep, voffA);
;             PG8_WAIT_V(8); PG8_WAIT_L(0); PG8_BAR; PG8_MMA(0, 0, At, B0); PG8_MMA(0, 1, At, B1); PG8_BAR; PG8_SCHED;
;             PG8_LDA(At, 0, 1); PG8_STAGE(PG8_SB(0, 0), b2, voffB); PG8_STAGE(PG8_SB(0, 1), b2 + hstepB, voffB); PG8_STAGE(PG8_SA(0, 0), a2, voffA);
;             PG8_WAIT_V(8); PG8_WAIT_L(0); PG8_BAR; PG8_MMA(1, 0, At, B0); PG8_MMA(1, 1, At, B1); PG8_BAR; PG8_SCHED;
;             PG8_LDB(B0, 1, 0); PG8_LDB(B1, 1, 1); PG8_SCHED; PG8_LDA(At, 1, 0); PG8_STAGE(PG8_SA(0, 1), a2 + hstep, voffA);
;             PG8_WAIT_V(8); PG8_WAIT_L(0); PG8_BAR; PG8_MMA(0, 0, At, B0); PG8_MMA(0, 1, At, B1); PG8_BAR; PG8_SCHED;
;             PG8_LDA(At, 1, 1); PG8_STAGE(PG8_SB(1, 0), b3, voffB); PG8_STAGE(PG8_SB(1, 1), b3 + hstepB, voffB); PG8_STAGE(PG8_SA(1, 0), a3, voffA);
;             PG8_WAIT_V(8); PG8_WAIT_L(0); PG8_BAR; PG8_MMA(1, 0, At, B0); PG8_MMA(1, 1, At, B1); PG8_BAR; PG8_SCHED;
	s_add_i32 s9, s9, s25
	s_mov_b32 m0, s9
	ds_read_b128 v[162:165], v236 offset:49152
	ds_read_b128 v[166:169], v236 offset:50176
	ds_read_b128 v[170:173], v236 offset:51200
	ds_read_b128 v[174:177], v236 offset:52224
	ds_read_b128 v[178:181], v236 offset:53248
	ds_read_b128 v[182:185], v236 offset:54272
	ds_read_b128 v[216:219], v236 offset:55296
	ds_read_b128 v[220:223], v236 offset:56320
	s_add_u32 s100, s46, s60
	s_addc_u32 s101, s47, s61
	global_load_lds_dwordx4 v190, s[100:101]
	s_add_i32 m0, s9, 0x2000
	s_add_u32 s10, s46, 0x20080
	s_addc_u32 s11, s47, 0
	s_add_i32 s9, s12, s25
	global_load_lds_dwordx4 v206, s[100:101]
	s_mov_b32 m0, s9
	s_nop 0
	global_load_lds_dwordx4 v190, s[10:11]
	s_add_i32 m0, s9, 0x2000
	s_nop 0
	global_load_lds_dwordx4 v206, s[10:11]
	s_mov_b32 m0, s75
	s_add_u32 s100, s94, s60
	s_addc_u32 s101, s95, s61
	global_load_lds_dwordx4 v210, s[100:101]
	s_mov_b32 m0, s0
	s_nop 0
	global_load_lds_dwordx4 v208, s[100:101]
	s_waitcnt vmcnt(8)
	s_waitcnt lgkmcnt(0)
	s_barrier
	v_mfma_f32_16x16x32_bf16 v[62:65], v[66:69], v[162:165], v[62:65]
	v_mfma_f32_16x16x32_bf16 v[58:61], v[78:81], v[162:165], v[58:61]
	v_mfma_f32_16x16x32_bf16 v[42:45], v[78:81], v[170:173], v[42:45]
	v_mfma_f32_16x16x32_bf16 v[46:49], v[66:69], v[170:173], v[46:49]
	v_mfma_f32_16x16x32_bf16 v[38:41], v[146:149], v[170:173], v[38:41]
	v_mfma_f32_16x16x32_bf16 v[34:37], v[154:157], v[170:173], v[34:37]
	v_mfma_f32_16x16x32_bf16 v[50:53], v[154:157], v[162:165], v[50:53]
	v_mfma_f32_16x16x32_bf16 v[54:57], v[146:149], v[162:165], v[54:57]
	v_mfma_f32_16x16x32_bf16 v[22:25], v[146:149], v[178:181], v[22:25]
	v_mfma_f32_16x16x32_bf16 v[18:21], v[154:157], v[178:181], v[18:21]
	v_mfma_f32_16x16x32_bf16 v[2:5], v[154:157], v[216:219], v[2:5]
	v_mfma_f32_16x16x32_bf16 v[6:9], v[146:149], v[216:219], v[6:9]
	v_mfma_f32_16x16x32_bf16 v[14:17], v[66:69], v[216:219], v[14:17]
	v_mfma_f32_16x16x32_bf16 v[10:13], v[78:81], v[216:219], v[10:13]
	v_mfma_f32_16x16x32_bf16 v[26:29], v[78:81], v[178:181], v[26:29]
	v_mfma_f32_16x16x32_bf16 v[30:33], v[66:69], v[178:181], v[30:33]
	v_mfma_f32_16x16x32_bf16 v[62:65], v[70:73], v[166:169], v[62:65]
	v_mfma_f32_16x16x32_bf16 v[58:61], v[86:89], v[166:169], v[58:61]
	v_mfma_f32_16x16x32_bf16 v[42:45], v[86:89], v[174:177], v[42:45]
	v_mfma_f32_16x16x32_bf16 v[46:49], v[70:73], v[174:177], v[46:49]
	v_mfma_f32_16x16x32_bf16 v[38:41], v[150:153], v[174:177], v[38:41]
	v_mfma_f32_16x16x32_bf16 v[34:37], v[158:161], v[174:177], v[34:37]
	v_mfma_f32_16x16x32_bf16 v[50:53], v[158:161], v[166:169], v[50:53]
	v_mfma_f32_16x16x32_bf16 v[54:57], v[150:153], v[166:169], v[54:57]
	v_mfma_f32_16x16x32_bf16 v[22:25], v[150:153], v[182:185], v[22:25]
	v_mfma_f32_16x16x32_bf16 v[18:21], v[158:161], v[182:185], v[18:21]
	v_mfma_f32_16x16x32_bf16 v[2:5], v[158:161], v[220:223], v[2:5]
	v_mfma_f32_16x16x32_bf16 v[6:9], v[150:153], v[220:223], v[6:9]
	v_mfma_f32_16x16x32_bf16 v[14:17], v[70:73], v[220:223], v[14:17]
	v_mfma_f32_16x16x32_bf16 v[10:13], v[86:89], v[220:223], v[10:13]
	v_mfma_f32_16x16x32_bf16 v[26:29], v[86:89], v[182:185], v[26:29]
	v_mfma_f32_16x16x32_bf16 v[30:33], v[70:73], v[182:185], v[30:33]
	s_barrier
	s_add_i32 s8, s8, 2
	s_add_u32 s38, s38, 0x100
	s_addc_u32 s39, s39, 0
	s_add_u32 s6, s6, 0x100
	s_addc_u32 s7, s7, 0
	s_cmp_gt_u32 s8, 29
.LBB0_927:
	s_add_u32 s9, s38, 0xfff80080
	s_addc_u32 s10, s39, -1
	s_add_i32 s11, 0, 0x10000
	s_cmp_eq_u32 s8, 28
	s_cselect_b32 s95, s36, s10
	s_cselect_b32 s94, s37, s9
	s_cselect_b32 s47, s4, s7
	s_cselect_b32 s46, s5, s6
	s_add_i32 s9, 0, 0x14000
	ds_read_b128 v[66:69], v186
	ds_read_b128 v[70:73], v186 offset:1024
	ds_read_b128 v[78:81], v186 offset:2048
	ds_read_b128 v[86:89], v186 offset:3072
	ds_read_b128 v[146:149], v187
	ds_read_b128 v[150:153], v187 offset:1024
	ds_read_b128 v[154:157], v187 offset:2048
	ds_read_b128 v[158:161], v187 offset:3072
	s_add_i32 m0, s66, 0xc000
	ds_read_b128 v[162:165], v236
	ds_read_b128 v[166:169], v236 offset:1024
	ds_read_b128 v[170:173], v236 offset:2048
	ds_read_b128 v[174:177], v236 offset:3072
	ds_read_b128 v[178:181], v236 offset:4096
	ds_read_b128 v[182:185], v236 offset:5120
	ds_read_b128 v[216:219], v236 offset:6144
	ds_read_b128 v[220:223], v236 offset:7168
	global_load_lds_dwordx4 v212, s[38:39]
	s_add_i32 m0, s66, 0xe000
	s_nop 0
	global_load_lds_dwordx4 v214, s[38:39]
	s_waitcnt vmcnt(8)
	s_waitcnt lgkmcnt(0)
	s_barrier
	v_mfma_f32_16x16x32_bf16 v[142:145], v[66:69], v[162:165], v[142:145]
	v_mfma_f32_16x16x32_bf16 v[138:141], v[78:81], v[162:165], v[138:141]
	v_mfma_f32_16x16x32_bf16 v[122:125], v[78:81], v[170:173], v[122:125]
	v_mfma_f32_16x16x32_bf16 v[126:129], v[66:69], v[170:173], v[126:129]
	v_mfma_f32_16x16x32_bf16 v[118:121], v[146:149], v[170:173], v[118:121]
	v_mfma_f32_16x16x32_bf16 v[114:117], v[154:157], v[170:173], v[114:117]
	v_mfma_f32_16x16x32_bf16 v[130:133], v[154:157], v[162:165], v[130:133]
	v_mfma_f32_16x16x32_bf16 v[134:137], v[146:149], v[162:165], v[134:137]
	v_mfma_f32_16x16x32_bf16 v[102:105], v[146:149], v[178:181], v[102:105]
	v_mfma_f32_16x16x32_bf16 v[98:101], v[154:157], v[178:181], v[98:101]
	v_mfma_f32_16x16x32_bf16 v[74:77], v[154:157], v[216:219], v[74:77]
	v_mfma_f32_16x16x32_bf16 v[82:85], v[146:149], v[216:219], v[82:85]
	v_mfma_f32_16x16x32_bf16 v[94:97], v[66:69], v[216:219], v[94:97]
	v_mfma_f32_16x16x32_bf16 v[90:93], v[78:81], v[216:219], v[90:93]
	v_mfma_f32_16x16x32_bf16 v[106:109], v[78:81], v[178:181], v[106:109]
	v_mfma_f32_16x16x32_bf16 v[110:113], v[66:69], v[178:181], v[110:113]
	v_mfma_f32_16x16x32_bf16 v[142:145], v[70:73], v[166:169], v[142:145]
	v_mfma_f32_16x16x32_bf16 v[138:141], v[86:89], v[166:169], v[138:141]
	v_mfma_f32_16x16x32_bf16 v[122:125], v[86:89], v[174:177], v[122:125]
	v_mfma_f32_16x16x32_bf16 v[126:129], v[70:73], v[174:177], v[126:129]
	v_mfma_f32_16x16x32_bf16 v[118:121], v[150:153], v[174:177], v[118:121]
	v_mfma_f32_16x16x32_bf16 v[114:117], v[158:161], v[174:177], v[114:117]
	v_mfma_f32_16x16x32_bf16 v[130:133], v[158:161], v[166:169], v[130:133]
	v_mfma_f32_16x16x32_bf16 v[134:137], v[150:153], v[166:169], v[134:137]
	v_mfma_f32_16x16x32_bf16 v[102:105], v[150:153], v[182:185], v[102:105]
	v_mfma_f32_16x16x32_bf16 v[98:101], v[158:161], v[182:185], v[98:101]
	v_mfma_f32_16x16x32_bf16 v[74:77], v[158:161], v[220:223], v[74:77]
	v_mfma_f32_16x16x32_bf16 v[82:85], v[150:153], v[220:223], v[82:85]
	v_mfma_f32_16x16x32_bf16 v[94:97], v[70:73], v[220:223], v[94:97]
	v_mfma_f32_16x16x32_bf16 v[90:93], v[86:89], v[220:223], v[90:93]
	v_mfma_f32_16x16x32_bf16 v[106:109], v[86:89], v[182:185], v[106:109]
	v_mfma_f32_16x16x32_bf16 v[110:113], v[70:73], v[182:185], v[110:113]
	s_barrier
; #define PG8_STAGE(bufoff, gbase, voff) do { _Pragma("unroll") for (int _i = 0; _i < 2; ++_i) \
;         __builtin_amdgcn_global_load_lds((const unsigned*)((const char*)(gbase) + (voff)[_i]), (PG8_LAS unsigned*)(lds + (bufoff) + ldsw + _i * 8192), 16, 0, 0); } while (0)
; #define PG8_LDA(dst, b, h) do { _Pragma("unroll") for (int m = 0; m < 4; ++m) _Pragma("unroll") for (int k = 0; k < 2; ++k) dst[m][k] = *(const PG8_LAS bf16x8*)(lds + PG8_SA(b, h) + aoff + m * 2048 + k * 1024); } while (0)
; #define PG8_LDB(dst, b, h) do { _Pragma("unroll") for (int n = 0; n < 2; ++n) _Pragma("unroll") for (int k = 0; k < 2; ++k) dst[n][k] = *(const PG8_LAS bf16x8*)(lds + PG8_SB(b, h) + boff + n * 2048 + k * 1024); } while (0)
; #define PG8_MMA(ai, bj, At, Bt) do { __builtin_amdgcn_s_setprio(1); _Pragma("unroll") for (int m = 0; m < 4; ++m) _Pragma("unroll") for (int n = 0; n < 2; ++n) _Pragma("unroll") for (int k = 0; k < 2; ++k) \
;         acc[ai][bj][m][n] = __builtin_amdgcn_mfma_f32_16x16x32_bf16(Bt[n][k], At[m][k], acc[ai][bj][m][n], 0, 0, 0); __builtin_amdgcn_s_setprio(0); } while (0)
; #define PG8_WAIT_V(n) asm volatile("s_waitcnt vmcnt(" #n ")" ::: "memory")
; #define PG8_WAIT_L(n) asm volatile("s_waitcnt lgkmcnt(" #n ")" ::: "memory")
; #define PG8_BAR __builtin_amdgcn_s_barrier()
; #define PG8_SCHED __builtin_amdgcn_sched_barrier(0)
; template <class Epi, class Sched, bool ALIGN_EPI = false, bool SP2 = false>
; __device__ __forceinline__ void gemm_phase(PG8_LAS unsigned char* lds, const Gemm g, const Sched& S, const Epi& E) {
;     ...
;             PG8_LDA(At, 0, 1); PG8_STAGE(PG8_SB(0, 0), b2, voffB); PG8_STAGE(PG8_SB(0, 1), b2 + hstepB, voffB); PG8_STAGE(PG8_SA(0, 0), a2, voffA);
;             PG8_WAIT_V(8); PG8_WAIT_L(0); PG8_BAR; PG8_MMA(1, 0, At, B0); PG8_MMA(1, 1, At, B1); PG8_BAR; PG8_SCHED;
;             PG8_LDB(B0, 1, 0); PG8_LDB(B1, 1, 1); PG8_SCHED; PG8_LDA(At, 1, 0); PG8_STAGE(PG8_SA(0, 1), a2 + hstep, voffA);
	s_add_i32 s10, s11, s25
	s_mov_b32 m0, s10
	ds_read_b128 v[162:165], v236 offset:16384
	ds_read_b128 v[166:169], v236 offset:17408
	ds_read_b128 v[170:173], v236 offset:18432
	ds_read_b128 v[174:177], v236 offset:19456
	ds_read_b128 v[178:181], v236 offset:20480
	ds_read_b128 v[182:185], v236 offset:21504
	ds_read_b128 v[216:219], v236 offset:22528
	ds_read_b128 v[220:223], v236 offset:23552
	global_load_lds_dwordx4 v190, s[46:47]
	s_add_i32 m0, s10, 0x2000
	s_add_u32 s10, s46, 0x20000
	s_addc_u32 s11, s47, 0
	s_add_i32 s9, s9, s25
	global_load_lds_dwordx4 v206, s[46:47]
	s_mov_b32 m0, s9
	s_nop 0
	global_load_lds_dwordx4 v190, s[10:11]
	s_add_i32 m0, s9, 0x2000
	s_nop 0
	global_load_lds_dwordx4 v206, s[10:11]
	s_mov_b32 m0, s66
	s_nop 0
	global_load_lds_dwordx4 v210, s[94:95]
	s_mov_b32 m0, s67
	s_nop 0
	global_load_lds_dwordx4 v208, s[94:95]
	s_waitcnt vmcnt(8)
	s_waitcnt lgkmcnt(0)
	s_barrier
	v_mfma_f32_16x16x32_bf16 v[62:65], v[66:69], v[162:165], v[62:65]
	v_mfma_f32_16x16x32_bf16 v[58:61], v[78:81], v[162:165], v[58:61]
	v_mfma_f32_16x16x32_bf16 v[42:45], v[78:81], v[170:173], v[42:45]
	v_mfma_f32_16x16x32_bf16 v[46:49], v[66:69], v[170:173], v[46:49]
	v_mfma_f32_16x16x32_bf16 v[38:41], v[146:149], v[170:173], v[38:41]
	v_mfma_f32_16x16x32_bf16 v[34:37], v[154:157], v[170:173], v[34:37]
	v_mfma_f32_16x16x32_bf16 v[50:53], v[154:157], v[162:165], v[50:53]
	v_mfma_f32_16x16x32_bf16 v[54:57], v[146:149], v[162:165], v[54:57]
	v_mfma_f32_16x16x32_bf16 v[22:25], v[146:149], v[178:181], v[22:25]
	v_mfma_f32_16x16x32_bf16 v[18:21], v[154:157], v[178:181], v[18:21]
	v_mfma_f32_16x16x32_bf16 v[2:5], v[154:157], v[216:219], v[2:5]
	v_mfma_f32_16x16x32_bf16 v[6:9], v[146:149], v[216:219], v[6:9]
	v_mfma_f32_16x16x32_bf16 v[14:17], v[66:69], v[216:219], v[14:17]
	v_mfma_f32_16x16x32_bf16 v[10:13], v[78:81], v[216:219], v[10:13]
	v_mfma_f32_16x16x32_bf16 v[26:29], v[78:81], v[178:181], v[26:29]
	v_mfma_f32_16x16x32_bf16 v[30:33], v[66:69], v[178:181], v[30:33]
	v_mfma_f32_16x16x32_bf16 v[62:65], v[70:73], v[166:169], v[62:65]
	v_mfma_f32_16x16x32_bf16 v[58:61], v[86:89], v[166:169], v[58:61]
	v_mfma_f32_16x16x32_bf16 v[42:45], v[86:89], v[174:177], v[42:45]
	v_mfma_f32_16x16x32_bf16 v[46:49], v[70:73], v[174:177], v[46:49]
	v_mfma_f32_16x16x32_bf16 v[38:41], v[150:153], v[174:177], v[38:41]
	v_mfma_f32_16x16x32_bf16 v[34:37], v[158:161], v[174:177], v[34:37]
	v_mfma_f32_16x16x32_bf16 v[50:53], v[158:161], v[166:169], v[50:53]
	v_mfma_f32_16x16x32_bf16 v[54:57], v[150:153], v[166:169], v[54:57]
	v_mfma_f32_16x16x32_bf16 v[22:25], v[150:153], v[182:185], v[22:25]
	v_mfma_f32_16x16x32_bf16 v[18:21], v[158:161], v[182:185], v[18:21]
	v_mfma_f32_16x16x32_bf16 v[2:5], v[158:161], v[220:223], v[2:5]
	v_mfma_f32_16x16x32_bf16 v[6:9], v[150:153], v[220:223], v[6:9]
	v_mfma_f32_16x16x32_bf16 v[14:17], v[70:73], v[220:223], v[14:17]
	v_mfma_f32_16x16x32_bf16 v[10:13], v[86:89], v[220:223], v[10:13]
	v_mfma_f32_16x16x32_bf16 v[26:29], v[86:89], v[182:185], v[26:29]
	v_mfma_f32_16x16x32_bf16 v[30:33], v[70:73], v[182:185], v[30:33]
	s_barrier
	s_add_i32 s9, 0, 0x18000
	s_add_i32 s12, 0, 0x1c000
	ds_read_b128 v[66:69], v198
	ds_read_b128 v[70:73], v198 offset:1024
	ds_read_b128 v[78:81], v198 offset:2048
	ds_read_b128 v[86:89], v198 offset:3072
	ds_read_b128 v[146:149], v199
	ds_read_b128 v[150:153], v199 offset:1024
	ds_read_b128 v[154:157], v199 offset:2048
	ds_read_b128 v[158:161], v199 offset:3072
	s_add_u32 s10, s94, 0x80000
	s_addc_u32 s11, s95, 0
	s_mov_b32 m0, s59
	ds_read_b128 v[162:165], v236 offset:32768
	ds_read_b128 v[166:169], v236 offset:33792
	ds_read_b128 v[170:173], v236 offset:34816
	ds_read_b128 v[174:177], v236 offset:35840
	ds_read_b128 v[178:181], v236 offset:36864
	ds_read_b128 v[182:185], v236 offset:37888
	ds_read_b128 v[216:219], v236 offset:38912
	ds_read_b128 v[220:223], v236 offset:39936
	global_load_lds_dwordx4 v210, s[10:11]
	s_mov_b32 m0, s74
	s_nop 0
	global_load_lds_dwordx4 v208, s[10:11]
	s_waitcnt vmcnt(8)
	s_waitcnt lgkmcnt(0)
	s_barrier
; #define PG8_STAGE(bufoff, gbase, voff) do { _Pragma("unroll") for (int _i = 0; _i < 2; ++_i) \
;         __builtin_amdgcn_global_load_lds((const unsigned*)((const char*)(gbase) + (voff)[_i]), (PG8_LAS unsigned*)(lds + (bufoff) + ldsw + _i * 8192), 16, 0, 0); } while (0)
; #define PG8_LDA(dst, b, h) do { _Pragma("unroll") for (int m = 0; m < 4; ++m) _Pragma("unroll") for (int k = 0; k < 2; ++k) dst[m][k] = *(const PG8_LAS bf16x8*)(lds + PG8_SA(b, h) + aoff + m * 2048 + k * 1024); } while (0)
; #define PG8_MMA(ai, bj, At, Bt) do { __builtin_amdgcn_s_setprio(1); _Pragma("unroll") for (int m = 0; m < 4; ++m) _Pragma("unroll") for (int n = 0; n < 2; ++n) _Pragma("unroll") for (int k = 0; k < 2; ++k) \
;         acc[ai][bj][m][n] = __builtin_amdgcn_mfma_f32_16x16x32_bf16(Bt[n][k], At[m][k], acc[ai][bj][m][n], 0, 0, 0); __builtin_amdgcn_s_setprio(0); } while (0)
; #define PG8_WAIT_V(n) asm volatile("s_waitcnt vmcnt(" #n ")" ::: "memory")
; #define PG8_WAIT_L(n) asm volatile("s_waitcnt lgkmcnt(" #n ")" ::: "memory")
; #define PG8_BAR __builtin_amdgcn_s_barrier()
; #define PG8_SCHED __builtin_amdgcn_sched_barrier(0)
; template <class Epi, class Sched, bool ALIGN_EPI = false, bool SP2 = false>
; __device__ __forceinline__ void gemm_phase(PG8_LAS unsigned char* lds, const Gemm g, const Sched& S, const Epi& E) {
;     ...
;             PG8_WAIT_V(8); PG8_WAIT_L(0); PG8_BAR; PG8_MMA(0, 0, At, B0); PG8_MMA(0, 1, At, B1); PG8_BAR; PG8_SCHED;
;             PG8_LDA(At, 1, 1); PG8_STAGE(PG8_SB(1, 0), b3, voffB); PG8_STAGE(PG8_SB(1, 1), b3 + hstepB, voffB); PG8_STAGE(PG8_SA(1, 0), a3, voffA);
;             PG8_WAIT_V(8); PG8_WAIT_L(0); PG8_BAR; PG8_MMA(1, 0, At, B0); PG8_MMA(1, 1, At, B1); PG8_BAR; PG8_SCHED;
	v_mfma_f32_16x16x32_bf16 v[142:145], v[66:69], v[162:165], v[142:145]
	v_mfma_f32_16x16x32_bf16 v[138:141], v[78:81], v[162:165], v[138:141]
	v_mfma_f32_16x16x32_bf16 v[122:125], v[78:81], v[170:173], v[122:125]
	v_mfma_f32_16x16x32_bf16 v[126:129], v[66:69], v[170:173], v[126:129]
	v_mfma_f32_16x16x32_bf16 v[118:121], v[146:149], v[170:173], v[118:121]
	v_mfma_f32_16x16x32_bf16 v[114:117], v[154:157], v[170:173], v[114:117]
	v_mfma_f32_16x16x32_bf16 v[130:133], v[154:157], v[162:165], v[130:133]
	v_mfma_f32_16x16x32_bf16 v[134:137], v[146:149], v[162:165], v[134:137]
	v_mfma_f32_16x16x32_bf16 v[102:105], v[146:149], v[178:181], v[102:105]
	v_mfma_f32_16x16x32_bf16 v[98:101], v[154:157], v[178:181], v[98:101]
	v_mfma_f32_16x16x32_bf16 v[74:77], v[154:157], v[216:219], v[74:77]
	v_mfma_f32_16x16x32_bf16 v[82:85], v[146:149], v[216:219], v[82:85]
	v_mfma_f32_16x16x32_bf16 v[94:97], v[66:69], v[216:219], v[94:97]
	v_mfma_f32_16x16x32_bf16 v[90:93], v[78:81], v[216:219], v[90:93]
	v_mfma_f32_16x16x32_bf16 v[106:109], v[78:81], v[178:181], v[106:109]
	v_mfma_f32_16x16x32_bf16 v[110:113], v[66:69], v[178:181], v[110:113]
	v_mfma_f32_16x16x32_bf16 v[142:145], v[70:73], v[166:169], v[142:145]
	v_mfma_f32_16x16x32_bf16 v[138:141], v[86:89], v[166:169], v[138:141]
	v_mfma_f32_16x16x32_bf16 v[122:125], v[86:89], v[174:177], v[122:125]
	v_mfma_f32_16x16x32_bf16 v[126:129], v[70:73], v[174:177], v[126:129]
	v_mfma_f32_16x16x32_bf16 v[118:121], v[150:153], v[174:177], v[118:121]
	v_mfma_f32_16x16x32_bf16 v[114:117], v[158:161], v[174:177], v[114:117]
	v_mfma_f32_16x16x32_bf16 v[130:133], v[158:161], v[166:169], v[130:133]
	v_mfma_f32_16x16x32_bf16 v[134:137], v[150:153], v[166:169], v[134:137]
	v_mfma_f32_16x16x32_bf16 v[102:105], v[150:153], v[182:185], v[102:105]
	v_mfma_f32_16x16x32_bf16 v[98:101], v[158:161], v[182:185], v[98:101]
	v_mfma_f32_16x16x32_bf16 v[74:77], v[158:161], v[220:223], v[74:77]
	v_mfma_f32_16x16x32_bf16 v[82:85], v[150:153], v[220:223], v[82:85]
	v_mfma_f32_16x16x32_bf16 v[94:97], v[70:73], v[220:223], v[94:97]
	v_mfma_f32_16x16x32_bf16 v[90:93], v[86:89], v[220:223], v[90:93]
	v_mfma_f32_16x16x32_bf16 v[106:109], v[86:89], v[182:185], v[106:109]
	v_mfma_f32_16x16x32_bf16 v[110:113], v[70:73], v[182:185], v[110:113]
	s_barrier
	s_add_i32 s9, s9, s25
	s_mov_b32 m0, s9
	ds_read_b128 v[162:165], v236 offset:49152
	ds_read_b128 v[166:169], v236 offset:50176
	ds_read_b128 v[170:173], v236 offset:51200
	ds_read_b128 v[174:177], v236 offset:52224
	ds_read_b128 v[178:181], v236 offset:53248
	ds_read_b128 v[182:185], v236 offset:54272
	ds_read_b128 v[216:219], v236 offset:55296
	ds_read_b128 v[220:223], v236 offset:56320
	s_add_u32 s100, s46, s60
	s_addc_u32 s101, s47, s61
	global_load_lds_dwordx4 v190, s[100:101]
	s_add_i32 m0, s9, 0x2000
	s_add_u32 s10, s46, 0x20080
	s_addc_u32 s11, s47, 0
	s_add_i32 s9, s12, s25
	global_load_lds_dwordx4 v206, s[100:101]
	s_mov_b32 m0, s9
	s_nop 0
	global_load_lds_dwordx4 v190, s[10:11]
	s_add_i32 m0, s9, 0x2000
	s_nop 0
	global_load_lds_dwordx4 v206, s[10:11]
	s_mov_b32 m0, s75
	s_add_u32 s100, s94, s60
	s_addc_u32 s101, s95, s61
	global_load_lds_dwordx4 v210, s[100:101]
	s_mov_b32 m0, s0
	s_nop 0
	global_load_lds_dwordx4 v208, s[100:101]
	s_waitcnt vmcnt(8)
	s_waitcnt lgkmcnt(0)
	s_barrier
	v_mfma_f32_16x16x32_bf16 v[62:65], v[66:69], v[162:165], v[62:65]
	v_mfma_f32_16x16x32_bf16 v[58:61], v[78:81], v[162:165], v[58:61]
	v_mfma_f32_16x16x32_bf16 v[42:45], v[78:81], v[170:173], v[42:45]
	v_mfma_f32_16x16x32_bf16 v[46:49], v[66:69], v[170:173], v[46:49]
	v_mfma_f32_16x16x32_bf16 v[38:41], v[146:149], v[170:173], v[38:41]
	v_mfma_f32_16x16x32_bf16 v[34:37], v[154:157], v[170:173], v[34:37]
	v_mfma_f32_16x16x32_bf16 v[50:53], v[154:157], v[162:165], v[50:53]
	v_mfma_f32_16x16x32_bf16 v[54:57], v[146:149], v[162:165], v[54:57]
	v_mfma_f32_16x16x32_bf16 v[22:25], v[146:149], v[178:181], v[22:25]
	v_mfma_f32_16x16x32_bf16 v[18:21], v[154:157], v[178:181], v[18:21]
	v_mfma_f32_16x16x32_bf16 v[2:5], v[154:157], v[216:219], v[2:5]
	v_mfma_f32_16x16x32_bf16 v[6:9], v[146:149], v[216:219], v[6:9]
	v_mfma_f32_16x16x32_bf16 v[14:17], v[66:69], v[216:219], v[14:17]
	v_mfma_f32_16x16x32_bf16 v[10:13], v[78:81], v[216:219], v[10:13]
	v_mfma_f32_16x16x32_bf16 v[26:29], v[78:81], v[178:181], v[26:29]
	v_mfma_f32_16x16x32_bf16 v[30:33], v[66:69], v[178:181], v[30:33]
	v_mfma_f32_16x16x32_bf16 v[62:65], v[70:73], v[166:169], v[62:65]
	v_mfma_f32_16x16x32_bf16 v[58:61], v[86:89], v[166:169], v[58:61]
	v_mfma_f32_16x16x32_bf16 v[42:45], v[86:89], v[174:177], v[42:45]
	v_mfma_f32_16x16x32_bf16 v[46:49], v[70:73], v[174:177], v[46:49]
	v_mfma_f32_16x16x32_bf16 v[38:41], v[150:153], v[174:177], v[38:41]
	v_mfma_f32_16x16x32_bf16 v[34:37], v[158:161], v[174:177], v[34:37]
	v_mfma_f32_16x16x32_bf16 v[50:53], v[158:161], v[166:169], v[50:53]
	v_mfma_f32_16x16x32_bf16 v[54:57], v[150:153], v[166:169], v[54:57]
	v_mfma_f32_16x16x32_bf16 v[22:25], v[150:153], v[182:185], v[22:25]
	v_mfma_f32_16x16x32_bf16 v[18:21], v[158:161], v[182:185], v[18:21]
	v_mfma_f32_16x16x32_bf16 v[2:5], v[158:161], v[220:223], v[2:5]
	v_mfma_f32_16x16x32_bf16 v[6:9], v[150:153], v[220:223], v[6:9]
	v_mfma_f32_16x16x32_bf16 v[14:17], v[70:73], v[220:223], v[14:17]
	v_mfma_f32_16x16x32_bf16 v[10:13], v[86:89], v[220:223], v[10:13]
	v_mfma_f32_16x16x32_bf16 v[26:29], v[86:89], v[182:185], v[26:29]
	v_mfma_f32_16x16x32_bf16 v[30:33], v[70:73], v[182:185], v[30:33]
	s_barrier
	s_add_i32 s8, s8, 2
	s_add_u32 s38, s38, 0x100
	s_addc_u32 s39, s39, 0
	s_add_u32 s6, s6, 0x100
	s_addc_u32 s7, s7, 0
	s_cmp_gt_u32 s8, 29
	s_cbranch_scc0 .LBB0_927
	s_and_b64 vcc, exec, s[70:71]
	s_cbranch_vccz .LBB0_930
	s_barrier

; #define PG8_STAGE(bufoff, gbase, voff) do { _Pragma("unroll") for (int _i = 0; _i < 2; ++_i) \
;         __builtin_amdgcn_global_load_lds((const unsigned*)((const char*)(gbase) + (voff)[_i]), (PG8_LAS unsigned*)(lds + (bufoff) + ldsw + _i * 8192), 16, 0, 0); } while (0)
; #define PG8_LDA(dst, b, h) do { _Pragma("unroll") for (int m = 0; m < 4; ++m) _Pragma("unroll") for (int k = 0; k < 2; ++k) dst[m][k] = *(const PG8_LAS bf16x8*)(lds + PG8_SA(b, h) + aoff + m * 2048 + k * 1024); } while (0)
; #define PG8_LDB(dst, b, h) do { _Pragma("unroll") for (int n = 0; n < 2; ++n) _Pragma("unroll") for (int k = 0; k < 2; ++k) dst[n][k] = *(const PG8_LAS bf16x8*)(lds + PG8_SB(b, h) + boff + n * 2048 + k * 1024); } while (0)
; #define PG8_MMA(ai, bj, At, Bt) do { __builtin_amdgcn_s_setprio(1); _Pragma("unroll") for (int m = 0; m < 4; ++m) _Pragma("unroll") for (int n = 0; n < 2; ++n) _Pragma("unroll") for (int k = 0; k < 2; ++k) \
;         acc[ai][bj][m][n] = __builtin_amdgcn_mfma_f32_16x16x32_bf16(Bt[n][k], At[m][k], acc[ai][bj][m][n], 0, 0, 0); __builtin_amdgcn_s_setprio(0); } while (0)
; #define PG8_BAR __builtin_amdgcn_s_barrier()
; template <class Epi, class Sched, bool ALIGN_EPI = false, bool SP2 = false>
; __device__ __forceinline__ void gemm_phase(PG8_LAS unsigned char* lds, const Gemm g, const Sched& S, const Epi& E) {
;     ...
;         const bool has_next = S.next(ui + 1, nxt);
;         const char* nA = has_next ? (const char*)g.A + (size_t)nxt.pm * tstep : cA; const char* nB = has_next ? (const char*)g.Bt + (size_t)nxt.pn * tstep : cB;
;         for (int t = 0; t < nt; t += 2) {
;             const bool last = (t == nt - 2);
;             const char* a1 = cA + (size_t)(t + 1) * kstep;
;             const char* a2 = last ? nA : cA + (size_t)(t + 2) * kstep; const char* b2 = last ? nB : cB + (size_t)(t + 2) * kstep;
;             const char* a3 = a2 + kstep; const char* b3 = b2 + kstep;
;             if (last && has_next) S.a_ready(nxt);
;             if constexpr (SP2) {
;             PG8_LDB(B0, 0, 0); PG8_LDB(B1, 0, 1); PG8_SCHED; PG8_LDA(At, 0, 0); PG8_STAGE(PG8_SA(1, 1), a1 + hstep, voffA);
;             PG8_WAIT_V(8); PG8_WAIT_L(0); PG8_BAR; PG8_MMA(0, 0, At, B0); PG8_MMA(0, 1, At, B1); PG8_BAR; PG8_SCHED;
;             PG8_LDA(At, 0, 1); PG8_STAGE(PG8_SB(0, 0), b2, voffB); PG8_STAGE(PG8_SB(0, 1), b2 + hstepB, voffB); PG8_STAGE(PG8_SA(0, 0), a2, voffA);
.LBB0_1070:
	s_ashr_i32 s97, s96, 31
	s_lshl_b64 s[4:5], s[96:97], 22
	s_add_u32 s26, s0, s4
	s_addc_u32 s27, s1, s5
	s_and_b64 s[4:5], s[92:93], exec
	s_cselect_b32 s97, s27, s39
	s_cselect_b32 s4, s26, s38
	s_ashr_i32 s85, s84, 31
	s_lshl_b64 s[6:7], s[84:85], 22
	s_add_u32 s94, s56, s6
	s_addc_u32 s95, s57, s7
	s_and_b64 s[6:7], s[92:93], exec
	s_cselect_b32 s5, s95, s47
	s_cselect_b32 s6, s94, s46
	s_add_u32 s38, s38, 0x200080
	s_addc_u32 s39, s39, 0
	s_add_u32 s7, s46, 0x100
	s_addc_u32 s8, s47, 0
	s_mov_b32 s9, -2
	s_waitcnt lgkmcnt(0)
	v_add_u32_e32 v186, 0x10000, v164
	v_add_u32_e32 v187, 0x14000, v164
	v_add_u32_e32 v198, 0x18000, v164
	v_add_u32_e32 v199, 0x1c000, v164
	s_add_u32 s10, s38, 0xffe00080
	s_addc_u32 s11, s39, -1
	s_add_i32 s12, 0, 0x10000
	s_cmpk_eq_i32 s9, 0x7c
	s_cselect_b32 vcc_hi, s97, s11
	s_cselect_b32 vcc_lo, s4, s10
	s_cselect_b32 s47, s5, s8
	s_cselect_b32 s46, s6, s7
	s_add_i32 s13, 0, 0x14000
	ds_read_b128 v[130:133], v186
	ds_read_b128 v[134:137], v186 offset:1024
	ds_read_b128 v[138:141], v186 offset:2048
	ds_read_b128 v[152:155], v186 offset:3072
	ds_read_b128 v[156:159], v187
	ds_read_b128 v[160:163], v187 offset:1024
	ds_read_b128 v[168:171], v187 offset:2048
	ds_read_b128 v[172:175], v187 offset:3072
	s_add_i32 m0, s74, 0xc000
	ds_read_b128 v[176:179], v166
	ds_read_b128 v[180:183], v166 offset:1024
	ds_read_b128 v[206:209], v166 offset:2048
	ds_read_b128 v[210:213], v166 offset:3072
	ds_read_b128 v[214:217], v166 offset:4096
	ds_read_b128 v[218:221], v166 offset:5120
	ds_read_b128 v[236:239], v166 offset:6144
	ds_read_b128 v[240:243], v166 offset:7168
	global_load_lds_dwordx4 v148, s[38:39]
	s_add_i32 m0, s74, 0xe000
	s_nop 0
	global_load_lds_dwordx4 v150, s[38:39]
	s_waitcnt vmcnt(8)
	s_waitcnt lgkmcnt(0)
	s_barrier
	v_mfma_f32_16x16x32_bf16 v[126:129], v[130:133], v[176:179], 0
	v_mfma_f32_16x16x32_bf16 v[122:125], v[138:141], v[176:179], 0
	v_mfma_f32_16x16x32_bf16 v[106:109], v[138:141], v[206:209], 0
	v_mfma_f32_16x16x32_bf16 v[110:113], v[130:133], v[206:209], 0
	v_mfma_f32_16x16x32_bf16 v[102:105], v[156:159], v[206:209], 0
	v_mfma_f32_16x16x32_bf16 v[98:101], v[168:171], v[206:209], 0
	v_mfma_f32_16x16x32_bf16 v[114:117], v[168:171], v[176:179], 0
	v_mfma_f32_16x16x32_bf16 v[118:121], v[156:159], v[176:179], 0
	v_mfma_f32_16x16x32_bf16 v[86:89], v[156:159], v[214:217], 0
	v_mfma_f32_16x16x32_bf16 v[82:85], v[168:171], v[214:217], 0
	v_mfma_f32_16x16x32_bf16 v[66:69], v[168:171], v[236:239], 0
	v_mfma_f32_16x16x32_bf16 v[70:73], v[156:159], v[236:239], 0
	v_mfma_f32_16x16x32_bf16 v[78:81], v[130:133], v[236:239], 0
	v_mfma_f32_16x16x32_bf16 v[74:77], v[138:141], v[236:239], 0
	v_mfma_f32_16x16x32_bf16 v[90:93], v[138:141], v[214:217], 0
	v_mfma_f32_16x16x32_bf16 v[94:97], v[130:133], v[214:217], 0
	v_mfma_f32_16x16x32_bf16 v[126:129], v[134:137], v[180:183], v[126:129]
	v_mfma_f32_16x16x32_bf16 v[122:125], v[152:155], v[180:183], v[122:125]
	v_mfma_f32_16x16x32_bf16 v[106:109], v[152:155], v[210:213], v[106:109]
	v_mfma_f32_16x16x32_bf16 v[110:113], v[134:137], v[210:213], v[110:113]
	v_mfma_f32_16x16x32_bf16 v[102:105], v[160:163], v[210:213], v[102:105]
	v_mfma_f32_16x16x32_bf16 v[98:101], v[172:175], v[210:213], v[98:101]
	v_mfma_f32_16x16x32_bf16 v[114:117], v[172:175], v[180:183], v[114:117]
	v_mfma_f32_16x16x32_bf16 v[118:121], v[160:163], v[180:183], v[118:121]
	v_mfma_f32_16x16x32_bf16 v[86:89], v[160:163], v[218:221], v[86:89]
	v_mfma_f32_16x16x32_bf16 v[82:85], v[172:175], v[218:221], v[82:85]
	v_mfma_f32_16x16x32_bf16 v[66:69], v[172:175], v[240:243], v[66:69]
	v_mfma_f32_16x16x32_bf16 v[70:73], v[160:163], v[240:243], v[70:73]
	v_mfma_f32_16x16x32_bf16 v[78:81], v[134:137], v[240:243], v[78:81]
	v_mfma_f32_16x16x32_bf16 v[74:77], v[152:155], v[240:243], v[74:77]
	v_mfma_f32_16x16x32_bf16 v[90:93], v[152:155], v[218:221], v[90:93]
	v_mfma_f32_16x16x32_bf16 v[94:97], v[134:137], v[218:221], v[94:97]
	s_barrier
	s_add_i32 s10, s12, s67
	s_mov_b32 m0, s10
	ds_read_b128 v[176:179], v166 offset:16384
	ds_read_b128 v[180:183], v166 offset:17408
	ds_read_b128 v[206:209], v166 offset:18432
	ds_read_b128 v[210:213], v166 offset:19456
	ds_read_b128 v[214:217], v166 offset:20480
	ds_read_b128 v[218:221], v166 offset:21504
	ds_read_b128 v[236:239], v166 offset:22528
	ds_read_b128 v[240:243], v166 offset:23552
	global_load_lds_dwordx4 v146, s[46:47]
	s_add_i32 m0, s10, 0x2000
	s_add_u32 s10, s46, 0x80000
	s_addc_u32 s11, s47, 0
	s_add_i32 s12, s13, s67
	global_load_lds_dwordx4 v142, s[46:47]
	s_mov_b32 m0, s12
	s_nop 0
	global_load_lds_dwordx4 v146, s[10:11]
	s_add_i32 m0, s12, 0x2000
	s_nop 0
	global_load_lds_dwordx4 v142, s[10:11]
	s_mov_b32 m0, s74
	s_nop 0
	global_load_lds_dwordx4 v190, vcc
	s_mov_b32 m0, s75
	s_nop 0
	global_load_lds_dwordx4 v144, vcc
	s_waitcnt vmcnt(8)
	s_waitcnt lgkmcnt(0)
	s_barrier
; #define PG8_STAGE(bufoff, gbase, voff) do { _Pragma("unroll") for (int _i = 0; _i < 2; ++_i) \
;         __builtin_amdgcn_global_load_lds((const unsigned*)((const char*)(gbase) + (voff)[_i]), (PG8_LAS unsigned*)(lds + (bufoff) + ldsw + _i * 8192), 16, 0, 0); } while (0)
; #define PG8_LDA(dst, b, h) do { _Pragma("unroll") for (int m = 0; m < 4; ++m) _Pragma("unroll") for (int k = 0; k < 2; ++k) dst[m][k] = *(const PG8_LAS bf16x8*)(lds + PG8_SA(b, h) + aoff + m * 2048 + k * 1024); } while (0)
; #define PG8_LDB(dst, b, h) do { _Pragma("unroll") for (int n = 0; n < 2; ++n) _Pragma("unroll") for (int k = 0; k < 2; ++k) dst[n][k] = *(const PG8_LAS bf16x8*)(lds + PG8_SB(b, h) + boff + n * 2048 + k * 1024); } while (0)
; #define PG8_MMA(ai, bj, At, Bt) do { __builtin_amdgcn_s_setprio(1); _Pragma("unroll") for (int m = 0; m < 4; ++m) _Pragma("unroll") for (int n = 0; n < 2; ++n) _Pragma("unroll") for (int k = 0; k < 2; ++k) \
;         acc[ai][bj][m][n] = __builtin_amdgcn_mfma_f32_16x16x32_bf16(Bt[n][k], At[m][k], acc[ai][bj][m][n], 0, 0, 0); __builtin_amdgcn_s_setprio(0); } while (0)
; #define PG8_WAIT_V(n) asm volatile("s_waitcnt vmcnt(" #n ")" ::: "memory")
; #define PG8_WAIT_L(n) asm volatile("s_waitcnt lgkmcnt(" #n ")" ::: "memory")
; #define PG8_BAR __builtin_amdgcn_s_barrier()
; #define PG8_SCHED __builtin_amdgcn_sched_barrier(0)
; template <class Epi, class Sched, bool ALIGN_EPI = false, bool SP2 = false>
; __device__ __forceinline__ void gemm_phase(PG8_LAS unsigned char* lds, const Gemm g, const Sched& S, const Epi& E) {
;     ...
;             PG8_WAIT_V(8); PG8_WAIT_L(0); PG8_BAR; PG8_MMA(1, 0, At, B0); PG8_MMA(1, 1, At, B1); PG8_BAR; PG8_SCHED;
;             PG8_LDB(B0, 1, 0); PG8_LDB(B1, 1, 1); PG8_SCHED; PG8_LDA(At, 1, 0); PG8_STAGE(PG8_SA(0, 1), a2 + hstep, voffA);
;             PG8_WAIT_V(8); PG8_WAIT_L(0); PG8_BAR; PG8_MMA(0, 0, At, B0); PG8_MMA(0, 1, At, B1); PG8_BAR; PG8_SCHED;
	v_mfma_f32_16x16x32_bf16 v[62:65], v[130:133], v[176:179], 0
	v_mfma_f32_16x16x32_bf16 v[58:61], v[138:141], v[176:179], 0
	v_mfma_f32_16x16x32_bf16 v[42:45], v[138:141], v[206:209], 0
	v_mfma_f32_16x16x32_bf16 v[46:49], v[130:133], v[206:209], 0
	v_mfma_f32_16x16x32_bf16 v[38:41], v[156:159], v[206:209], 0
	v_mfma_f32_16x16x32_bf16 v[34:37], v[168:171], v[206:209], 0
	v_mfma_f32_16x16x32_bf16 v[50:53], v[168:171], v[176:179], 0
	v_mfma_f32_16x16x32_bf16 v[54:57], v[156:159], v[176:179], 0
	v_mfma_f32_16x16x32_bf16 v[22:25], v[156:159], v[214:217], 0
	v_mfma_f32_16x16x32_bf16 v[18:21], v[168:171], v[214:217], 0
	v_mfma_f32_16x16x32_bf16 v[2:5], v[168:171], v[236:239], 0
	v_mfma_f32_16x16x32_bf16 v[6:9], v[156:159], v[236:239], 0
	v_mfma_f32_16x16x32_bf16 v[14:17], v[130:133], v[236:239], 0
	v_mfma_f32_16x16x32_bf16 v[10:13], v[138:141], v[236:239], 0
	v_mfma_f32_16x16x32_bf16 v[26:29], v[138:141], v[214:217], 0
	v_mfma_f32_16x16x32_bf16 v[30:33], v[130:133], v[214:217], 0
	v_mfma_f32_16x16x32_bf16 v[62:65], v[134:137], v[180:183], v[62:65]
	v_mfma_f32_16x16x32_bf16 v[58:61], v[152:155], v[180:183], v[58:61]
	v_mfma_f32_16x16x32_bf16 v[42:45], v[152:155], v[210:213], v[42:45]
	v_mfma_f32_16x16x32_bf16 v[46:49], v[134:137], v[210:213], v[46:49]
	v_mfma_f32_16x16x32_bf16 v[38:41], v[160:163], v[210:213], v[38:41]
	v_mfma_f32_16x16x32_bf16 v[34:37], v[172:175], v[210:213], v[34:37]
	v_mfma_f32_16x16x32_bf16 v[50:53], v[172:175], v[180:183], v[50:53]
	v_mfma_f32_16x16x32_bf16 v[54:57], v[160:163], v[180:183], v[54:57]
	v_mfma_f32_16x16x32_bf16 v[22:25], v[160:163], v[218:221], v[22:25]
	v_mfma_f32_16x16x32_bf16 v[18:21], v[172:175], v[218:221], v[18:21]
	v_mfma_f32_16x16x32_bf16 v[2:5], v[172:175], v[240:243], v[2:5]
	v_mfma_f32_16x16x32_bf16 v[6:9], v[160:163], v[240:243], v[6:9]
	v_mfma_f32_16x16x32_bf16 v[14:17], v[134:137], v[240:243], v[14:17]
	v_mfma_f32_16x16x32_bf16 v[10:13], v[152:155], v[240:243], v[10:13]
	v_mfma_f32_16x16x32_bf16 v[26:29], v[152:155], v[218:221], v[26:29]
	v_mfma_f32_16x16x32_bf16 v[30:33], v[134:137], v[218:221], v[30:33]
	s_barrier
	s_add_i32 s12, 0, 0x18000
	s_add_i32 s13, 0, 0x1c000
	ds_read_b128 v[130:133], v198
	ds_read_b128 v[134:137], v198 offset:1024
	ds_read_b128 v[138:141], v198 offset:2048
	ds_read_b128 v[152:155], v198 offset:3072
	ds_read_b128 v[156:159], v199
	ds_read_b128 v[160:163], v199 offset:1024
	ds_read_b128 v[168:171], v199 offset:2048
	ds_read_b128 v[172:175], v199 offset:3072
	s_add_u32 s10, vcc_lo, 0x200000
	s_addc_u32 s11, vcc_hi, 0
	s_mov_b32 m0, s86
	ds_read_b128 v[176:179], v166 offset:32768
	ds_read_b128 v[180:183], v166 offset:33792
	ds_read_b128 v[206:209], v166 offset:34816
	ds_read_b128 v[210:213], v166 offset:35840
	ds_read_b128 v[214:217], v166 offset:36864
	ds_read_b128 v[218:221], v166 offset:37888
	ds_read_b128 v[236:239], v166 offset:38912
	ds_read_b128 v[240:243], v166 offset:39936
	global_load_lds_dwordx4 v190, s[10:11]
	s_mov_b32 m0, s87
	s_nop 0
	global_load_lds_dwordx4 v144, s[10:11]
	s_waitcnt vmcnt(8)
	s_waitcnt lgkmcnt(0)
	s_barrier
	v_mfma_f32_16x16x32_bf16 v[126:129], v[130:133], v[176:179], v[126:129]
	v_mfma_f32_16x16x32_bf16 v[122:125], v[138:141], v[176:179], v[122:125]
	v_mfma_f32_16x16x32_bf16 v[106:109], v[138:141], v[206:209], v[106:109]
	v_mfma_f32_16x16x32_bf16 v[110:113], v[130:133], v[206:209], v[110:113]
	v_mfma_f32_16x16x32_bf16 v[102:105], v[156:159], v[206:209], v[102:105]
	v_mfma_f32_16x16x32_bf16 v[98:101], v[168:171], v[206:209], v[98:101]
	v_mfma_f32_16x16x32_bf16 v[114:117], v[168:171], v[176:179], v[114:117]
	v_mfma_f32_16x16x32_bf16 v[118:121], v[156:159], v[176:179], v[118:121]
	v_mfma_f32_16x16x32_bf16 v[86:89], v[156:159], v[214:217], v[86:89]
	v_mfma_f32_16x16x32_bf16 v[82:85], v[168:171], v[214:217], v[82:85]
	v_mfma_f32_16x16x32_bf16 v[66:69], v[168:171], v[236:239], v[66:69]
	v_mfma_f32_16x16x32_bf16 v[70:73], v[156:159], v[236:239], v[70:73]
	v_mfma_f32_16x16x32_bf16 v[78:81], v[130:133], v[236:239], v[78:81]
	v_mfma_f32_16x16x32_bf16 v[74:77], v[138:141], v[236:239], v[74:77]
	v_mfma_f32_16x16x32_bf16 v[90:93], v[138:141], v[214:217], v[90:93]
	v_mfma_f32_16x16x32_bf16 v[94:97], v[130:133], v[214:217], v[94:97]
	v_mfma_f32_16x16x32_bf16 v[126:129], v[134:137], v[180:183], v[126:129]
	v_mfma_f32_16x16x32_bf16 v[122:125], v[152:155], v[180:183], v[122:125]
	v_mfma_f32_16x16x32_bf16 v[106:109], v[152:155], v[210:213], v[106:109]
	v_mfma_f32_16x16x32_bf16 v[110:113], v[134:137], v[210:213], v[110:113]
	v_mfma_f32_16x16x32_bf16 v[102:105], v[160:163], v[210:213], v[102:105]
	v_mfma_f32_16x16x32_bf16 v[98:101], v[172:175], v[210:213], v[98:101]
	v_mfma_f32_16x16x32_bf16 v[114:117], v[172:175], v[180:183], v[114:117]
	v_mfma_f32_16x16x32_bf16 v[118:121], v[160:163], v[180:183], v[118:121]
	v_mfma_f32_16x16x32_bf16 v[86:89], v[160:163], v[218:221], v[86:89]
	v_mfma_f32_16x16x32_bf16 v[82:85], v[172:175], v[218:221], v[82:85]
	v_mfma_f32_16x16x32_bf16 v[66:69], v[172:175], v[240:243], v[66:69]
	v_mfma_f32_16x16x32_bf16 v[70:73], v[160:163], v[240:243], v[70:73]
	v_mfma_f32_16x16x32_bf16 v[78:81], v[134:137], v[240:243], v[78:81]
	v_mfma_f32_16x16x32_bf16 v[74:77], v[152:155], v[240:243], v[74:77]
	v_mfma_f32_16x16x32_bf16 v[90:93], v[152:155], v[218:221], v[90:93]
	v_mfma_f32_16x16x32_bf16 v[94:97], v[134:137], v[218:221], v[94:97]
	s_barrier
; #define PG8_STAGE(bufoff, gbase, voff) do { _Pragma("unroll") for (int _i = 0; _i < 2; ++_i) \
;         __builtin_amdgcn_global_load_lds((const unsigned*)((const char*)(gbase) + (voff)[_i]), (PG8_LAS unsigned*)(lds + (bufoff) + ldsw + _i * 8192), 16, 0, 0); } while (0)
; #define PG8_LDA(dst, b, h) do { _Pragma("unroll") for (int m = 0; m < 4; ++m) _Pragma("unroll") for (int k = 0; k < 2; ++k) dst[m][k] = *(const PG8_LAS bf16x8*)(lds + PG8_SA(b, h) + aoff + m * 2048 + k * 1024); } while (0)
; #define PG8_LDB(dst, b, h) do { _Pragma("unroll") for (int n = 0; n < 2; ++n) _Pragma("unroll") for (int k = 0; k < 2; ++k) dst[n][k] = *(const PG8_LAS bf16x8*)(lds + PG8_SB(b, h) + boff + n * 2048 + k * 1024); } while (0)
; template <class Epi, class Sched, bool ALIGN_EPI = false, bool SP2 = false>
; __device__ __forceinline__ void gemm_phase(PG8_LAS unsigned char* lds, const Gemm g, const Sched& S, const Epi& E) {
;     ...
;         for (int t = 0; t < nt; t += 2) {
;             const bool last = (t == nt - 2);
;             const char* a1 = cA + (size_t)(t + 1) * kstep;
;             const char* a2 = last ? nA : cA + (size_t)(t + 2) * kstep; const char* b2 = last ? nB : cB + (size_t)(t + 2) * kstep;
;             const char* a3 = a2 + kstep; const char* b3 = b2 + kstep;
;             if (last && has_next) S.a_ready(nxt);
;             if constexpr (SP2) {
;             PG8_LDB(B0, 0, 0); PG8_LDB(B1, 0, 1); PG8_SCHED; PG8_LDA(At, 0, 0); PG8_STAGE(PG8_SA(1, 1), a1 + hstep, voffA);
;             PG8_WAIT_V(8); PG8_WAIT_L(0); PG8_BAR; PG8_MMA(0, 0, At, B0); PG8_MMA(0, 1, At, B1); PG8_BAR; PG8_SCHED;
;             PG8_LDA(At, 0, 1); PG8_STAGE(PG8_SB(0, 0), b2, voffB); PG8_STAGE(PG8_SB(0, 1), b2 + hstepB, voffB); PG8_STAGE(PG8_SA(0, 0), a2, voffA);
;             PG8_WAIT_V(8); PG8_WAIT_L(0); PG8_BAR; PG8_MMA(1, 0, At, B0); PG8_MMA(1, 1, At, B1); PG8_BAR; PG8_SCHED;
;             PG8_LDB(B0, 1, 0); PG8_LDB(B1, 1, 1); PG8_SCHED; PG8_LDA(At, 1, 0); PG8_STAGE(PG8_SA(0, 1), a2 + hstep, voffA);
;             PG8_WAIT_V(8); PG8_WAIT_L(0); PG8_BAR; PG8_MMA(0, 0, At, B0); PG8_MMA(0, 1, At, B1); PG8_BAR; PG8_SCHED;
;             PG8_LDA(At, 1, 1); PG8_STAGE(PG8_SB(1, 0), b3, voffB); PG8_STAGE(PG8_SB(1, 1), b3 + hstepB, voffB); PG8_STAGE(PG8_SA(1, 0), a3, voffA);
;             PG8_WAIT_V(8); PG8_WAIT_L(0); PG8_BAR; PG8_MMA(1, 0, At, B0); PG8_MMA(1, 1, At, B1); PG8_BAR; PG8_SCHED;
	s_add_i32 s10, s12, s67
	s_mov_b32 m0, s10
	ds_read_b128 v[176:179], v166 offset:49152
	ds_read_b128 v[180:183], v166 offset:50176
	ds_read_b128 v[206:209], v166 offset:51200
	ds_read_b128 v[210:213], v166 offset:52224
	ds_read_b128 v[214:217], v166 offset:53248
	ds_read_b128 v[218:221], v166 offset:54272
	ds_read_b128 v[236:239], v166 offset:55296
	ds_read_b128 v[240:243], v166 offset:56320
	s_add_u32 s100, s46, s60
	s_addc_u32 s101, s47, s61
	global_load_lds_dwordx4 v146, s[100:101]
	s_add_i32 m0, s10, 0x2000
	s_add_u32 s10, s46, 0x80080
	s_addc_u32 s11, s47, 0
	s_add_i32 s12, s13, s67
	global_load_lds_dwordx4 v142, s[100:101]
	s_mov_b32 m0, s12
	s_nop 0
	global_load_lds_dwordx4 v146, s[10:11]
	s_add_i32 m0, s12, 0x2000
	s_nop 0
	global_load_lds_dwordx4 v142, s[10:11]
	s_mov_b32 m0, s82
	s_add_u32 s100, vcc_lo, s60
	s_addc_u32 s101, vcc_hi, s61
	global_load_lds_dwordx4 v190, s[100:101]
	s_mov_b32 m0, s42
	s_nop 0
	global_load_lds_dwordx4 v144, s[100:101]
	s_waitcnt vmcnt(8)
	s_waitcnt lgkmcnt(0)
	s_barrier
	v_mfma_f32_16x16x32_bf16 v[62:65], v[130:133], v[176:179], v[62:65]
	v_mfma_f32_16x16x32_bf16 v[58:61], v[138:141], v[176:179], v[58:61]
	v_mfma_f32_16x16x32_bf16 v[42:45], v[138:141], v[206:209], v[42:45]
	v_mfma_f32_16x16x32_bf16 v[46:49], v[130:133], v[206:209], v[46:49]
	v_mfma_f32_16x16x32_bf16 v[38:41], v[156:159], v[206:209], v[38:41]
	v_mfma_f32_16x16x32_bf16 v[34:37], v[168:171], v[206:209], v[34:37]
	v_mfma_f32_16x16x32_bf16 v[50:53], v[168:171], v[176:179], v[50:53]
	v_mfma_f32_16x16x32_bf16 v[54:57], v[156:159], v[176:179], v[54:57]
	v_mfma_f32_16x16x32_bf16 v[22:25], v[156:159], v[214:217], v[22:25]
	v_mfma_f32_16x16x32_bf16 v[18:21], v[168:171], v[214:217], v[18:21]
	v_mfma_f32_16x16x32_bf16 v[2:5], v[168:171], v[236:239], v[2:5]
	v_mfma_f32_16x16x32_bf16 v[6:9], v[156:159], v[236:239], v[6:9]
	v_mfma_f32_16x16x32_bf16 v[14:17], v[130:133], v[236:239], v[14:17]
	v_mfma_f32_16x16x32_bf16 v[10:13], v[138:141], v[236:239], v[10:13]
	v_mfma_f32_16x16x32_bf16 v[26:29], v[138:141], v[214:217], v[26:29]
	v_mfma_f32_16x16x32_bf16 v[30:33], v[130:133], v[214:217], v[30:33]
	v_mfma_f32_16x16x32_bf16 v[62:65], v[134:137], v[180:183], v[62:65]
	v_mfma_f32_16x16x32_bf16 v[58:61], v[152:155], v[180:183], v[58:61]
	v_mfma_f32_16x16x32_bf16 v[42:45], v[152:155], v[210:213], v[42:45]
	v_mfma_f32_16x16x32_bf16 v[46:49], v[134:137], v[210:213], v[46:49]
	v_mfma_f32_16x16x32_bf16 v[38:41], v[160:163], v[210:213], v[38:41]
	v_mfma_f32_16x16x32_bf16 v[34:37], v[172:175], v[210:213], v[34:37]
	v_mfma_f32_16x16x32_bf16 v[50:53], v[172:175], v[180:183], v[50:53]
	v_mfma_f32_16x16x32_bf16 v[54:57], v[160:163], v[180:183], v[54:57]
	v_mfma_f32_16x16x32_bf16 v[22:25], v[160:163], v[218:221], v[22:25]
	v_mfma_f32_16x16x32_bf16 v[18:21], v[172:175], v[218:221], v[18:21]
	v_mfma_f32_16x16x32_bf16 v[2:5], v[172:175], v[240:243], v[2:5]
	v_mfma_f32_16x16x32_bf16 v[6:9], v[160:163], v[240:243], v[6:9]
	v_mfma_f32_16x16x32_bf16 v[14:17], v[134:137], v[240:243], v[14:17]
	v_mfma_f32_16x16x32_bf16 v[10:13], v[152:155], v[240:243], v[10:13]
	v_mfma_f32_16x16x32_bf16 v[26:29], v[152:155], v[218:221], v[26:29]
	v_mfma_f32_16x16x32_bf16 v[30:33], v[134:137], v[218:221], v[30:33]
	s_barrier
	s_add_i32 s9, s9, 2
	s_add_u32 s38, s38, 0x100
	s_addc_u32 s39, s39, 0
	s_add_u32 s7, s7, 0x100
	s_addc_u32 s8, s8, 0
	s_cmpk_gt_u32 s9, 0x7d
.LBB0_1071:
	s_add_u32 s10, s38, 0xffe00080
	s_addc_u32 s11, s39, -1
	s_add_i32 s12, 0, 0x10000
	s_cmpk_eq_i32 s9, 0x7c
	s_cselect_b32 vcc_hi, s97, s11
	s_cselect_b32 vcc_lo, s4, s10
	s_cselect_b32 s47, s5, s8
	s_cselect_b32 s46, s6, s7
	s_add_i32 s13, 0, 0x14000
	ds_read_b128 v[130:133], v186
	ds_read_b128 v[134:137], v186 offset:1024
	ds_read_b128 v[138:141], v186 offset:2048
	ds_read_b128 v[152:155], v186 offset:3072
	ds_read_b128 v[156:159], v187
	ds_read_b128 v[160:163], v187 offset:1024
	ds_read_b128 v[168:171], v187 offset:2048
	ds_read_b128 v[172:175], v187 offset:3072
	s_add_i32 m0, s74, 0xc000
	ds_read_b128 v[176:179], v166
	ds_read_b128 v[180:183], v166 offset:1024
	ds_read_b128 v[206:209], v166 offset:2048
	ds_read_b128 v[210:213], v166 offset:3072
	ds_read_b128 v[214:217], v166 offset:4096
	ds_read_b128 v[218:221], v166 offset:5120
	ds_read_b128 v[236:239], v166 offset:6144
	ds_read_b128 v[240:243], v166 offset:7168
	global_load_lds_dwordx4 v148, s[38:39]
	s_add_i32 m0, s74, 0xe000
	s_nop 0
	global_load_lds_dwordx4 v150, s[38:39]
	s_waitcnt vmcnt(8)
	s_waitcnt lgkmcnt(0)
	s_barrier
	v_mfma_f32_16x16x32_bf16 v[126:129], v[130:133], v[176:179], v[126:129]
	v_mfma_f32_16x16x32_bf16 v[122:125], v[138:141], v[176:179], v[122:125]
	v_mfma_f32_16x16x32_bf16 v[106:109], v[138:141], v[206:209], v[106:109]
	v_mfma_f32_16x16x32_bf16 v[110:113], v[130:133], v[206:209], v[110:113]
	v_mfma_f32_16x16x32_bf16 v[102:105], v[156:159], v[206:209], v[102:105]
	v_mfma_f32_16x16x32_bf16 v[98:101], v[168:171], v[206:209], v[98:101]
	v_mfma_f32_16x16x32_bf16 v[114:117], v[168:171], v[176:179], v[114:117]
	v_mfma_f32_16x16x32_bf16 v[118:121], v[156:159], v[176:179], v[118:121]
	v_mfma_f32_16x16x32_bf16 v[86:89], v[156:159], v[214:217], v[86:89]
	v_mfma_f32_16x16x32_bf16 v[82:85], v[168:171], v[214:217], v[82:85]
	v_mfma_f32_16x16x32_bf16 v[66:69], v[168:171], v[236:239], v[66:69]
	v_mfma_f32_16x16x32_bf16 v[70:73], v[156:159], v[236:239], v[70:73]
	v_mfma_f32_16x16x32_bf16 v[78:81], v[130:133], v[236:239], v[78:81]
	v_mfma_f32_16x16x32_bf16 v[74:77], v[138:141], v[236:239], v[74:77]
	v_mfma_f32_16x16x32_bf16 v[90:93], v[138:141], v[214:217], v[90:93]
	v_mfma_f32_16x16x32_bf16 v[94:97], v[130:133], v[214:217], v[94:97]
	v_mfma_f32_16x16x32_bf16 v[126:129], v[134:137], v[180:183], v[126:129]
	v_mfma_f32_16x16x32_bf16 v[122:125], v[152:155], v[180:183], v[122:125]
	v_mfma_f32_16x16x32_bf16 v[106:109], v[152:155], v[210:213], v[106:109]
	v_mfma_f32_16x16x32_bf16 v[110:113], v[134:137], v[210:213], v[110:113]
	v_mfma_f32_16x16x32_bf16 v[102:105], v[160:163], v[210:213], v[102:105]
	v_mfma_f32_16x16x32_bf16 v[98:101], v[172:175], v[210:213], v[98:101]
	v_mfma_f32_16x16x32_bf16 v[114:117], v[172:175], v[180:183], v[114:117]
	v_mfma_f32_16x16x32_bf16 v[118:121], v[160:163], v[180:183], v[118:121]
	v_mfma_f32_16x16x32_bf16 v[86:89], v[160:163], v[218:221], v[86:89]
	v_mfma_f32_16x16x32_bf16 v[82:85], v[172:175], v[218:221], v[82:85]
	v_mfma_f32_16x16x32_bf16 v[66:69], v[172:175], v[240:243], v[66:69]
	v_mfma_f32_16x16x32_bf16 v[70:73], v[160:163], v[240:243], v[70:73]
	v_mfma_f32_16x16x32_bf16 v[78:81], v[134:137], v[240:243], v[78:81]
	v_mfma_f32_16x16x32_bf16 v[74:77], v[152:155], v[240:243], v[74:77]
	v_mfma_f32_16x16x32_bf16 v[90:93], v[152:155], v[218:221], v[90:93]
	v_mfma_f32_16x16x32_bf16 v[94:97], v[134:137], v[218:221], v[94:97]
	s_barrier
; #define PG8_STAGE(bufoff, gbase, voff) do { _Pragma("unroll") for (int _i = 0; _i < 2; ++_i) \
;         __builtin_amdgcn_global_load_lds((const unsigned*)((const char*)(gbase) + (voff)[_i]), (PG8_LAS unsigned*)(lds + (bufoff) + ldsw + _i * 8192), 16, 0, 0); } while (0)
; #define PG8_LDA(dst, b, h) do { _Pragma("unroll") for (int m = 0; m < 4; ++m) _Pragma("unroll") for (int k = 0; k < 2; ++k) dst[m][k] = *(const PG8_LAS bf16x8*)(lds + PG8_SA(b, h) + aoff + m * 2048 + k * 1024); } while (0)
; #define PG8_LDB(dst, b, h) do { _Pragma("unroll") for (int n = 0; n < 2; ++n) _Pragma("unroll") for (int k = 0; k < 2; ++k) dst[n][k] = *(const PG8_LAS bf16x8*)(lds + PG8_SB(b, h) + boff + n * 2048 + k * 1024); } while (0)
; #define PG8_MMA(ai, bj, At, Bt) do { __builtin_amdgcn_s_setprio(1); _Pragma("unroll") for (int m = 0; m < 4; ++m) _Pragma("unroll") for (int n = 0; n < 2; ++n) _Pragma("unroll") for (int k = 0; k < 2; ++k) \
;         acc[ai][bj][m][n] = __builtin_amdgcn_mfma_f32_16x16x32_bf16(Bt[n][k], At[m][k], acc[ai][bj][m][n], 0, 0, 0); __builtin_amdgcn_s_setprio(0); } while (0)
; #define PG8_WAIT_V(n) asm volatile("s_waitcnt vmcnt(" #n ")" ::: "memory")
; #define PG8_WAIT_L(n) asm volatile("s_waitcnt lgkmcnt(" #n ")" ::: "memory")
; #define PG8_BAR __builtin_amdgcn_s_barrier()
; #define PG8_SCHED __builtin_amdgcn_sched_barrier(0)
; template <class Epi, class Sched, bool ALIGN_EPI = false, bool SP2 = false>
; __device__ __forceinline__ void gemm_phase(PG8_LAS unsigned char* lds, const Gemm g, const Sched& S, const Epi& E) {
;     ...
;             PG8_LDA(At, 0, 1); PG8_STAGE(PG8_SB(0, 0), b2, voffB); PG8_STAGE(PG8_SB(0, 1), b2 + hstepB, voffB); PG8_STAGE(PG8_SA(0, 0), a2, voffA);
;             PG8_WAIT_V(8); PG8_WAIT_L(0); PG8_BAR; PG8_MMA(1, 0, At, B0); PG8_MMA(1, 1, At, B1); PG8_BAR; PG8_SCHED;
;             PG8_LDB(B0, 1, 0); PG8_LDB(B1, 1, 1); PG8_SCHED; PG8_LDA(At, 1, 0); PG8_STAGE(PG8_SA(0, 1), a2 + hstep, voffA);
	s_add_i32 s10, s12, s67
	s_mov_b32 m0, s10
	ds_read_b128 v[176:179], v166 offset:16384
	ds_read_b128 v[180:183], v166 offset:17408
	ds_read_b128 v[206:209], v166 offset:18432
	ds_read_b128 v[210:213], v166 offset:19456
	ds_read_b128 v[214:217], v166 offset:20480
	ds_read_b128 v[218:221], v166 offset:21504
	ds_read_b128 v[236:239], v166 offset:22528
	ds_read_b128 v[240:243], v166 offset:23552
	global_load_lds_dwordx4 v146, s[46:47]
	s_add_i32 m0, s10, 0x2000
	s_add_u32 s10, s46, 0x80000
	s_addc_u32 s11, s47, 0
	s_add_i32 s12, s13, s67
	global_load_lds_dwordx4 v142, s[46:47]
	s_mov_b32 m0, s12
	s_nop 0
	global_load_lds_dwordx4 v146, s[10:11]
	s_add_i32 m0, s12, 0x2000
	s_nop 0
	global_load_lds_dwordx4 v142, s[10:11]
	s_mov_b32 m0, s74
	s_nop 0
	global_load_lds_dwordx4 v190, vcc
	s_mov_b32 m0, s75
	s_nop 0
	global_load_lds_dwordx4 v144, vcc
	s_waitcnt vmcnt(8)
	s_waitcnt lgkmcnt(0)
	s_barrier
	v_mfma_f32_16x16x32_bf16 v[62:65], v[130:133], v[176:179], v[62:65]
	v_mfma_f32_16x16x32_bf16 v[58:61], v[138:141], v[176:179], v[58:61]
	v_mfma_f32_16x16x32_bf16 v[42:45], v[138:141], v[206:209], v[42:45]
	v_mfma_f32_16x16x32_bf16 v[46:49], v[130:133], v[206:209], v[46:49]
	v_mfma_f32_16x16x32_bf16 v[38:41], v[156:159], v[206:209], v[38:41]
	v_mfma_f32_16x16x32_bf16 v[34:37], v[168:171], v[206:209], v[34:37]
	v_mfma_f32_16x16x32_bf16 v[50:53], v[168:171], v[176:179], v[50:53]
	v_mfma_f32_16x16x32_bf16 v[54:57], v[156:159], v[176:179], v[54:57]
	v_mfma_f32_16x16x32_bf16 v[22:25], v[156:159], v[214:217], v[22:25]
	v_mfma_f32_16x16x32_bf16 v[18:21], v[168:171], v[214:217], v[18:21]
	v_mfma_f32_16x16x32_bf16 v[2:5], v[168:171], v[236:239], v[2:5]
	v_mfma_f32_16x16x32_bf16 v[6:9], v[156:159], v[236:239], v[6:9]
	v_mfma_f32_16x16x32_bf16 v[14:17], v[130:133], v[236:239], v[14:17]
	v_mfma_f32_16x16x32_bf16 v[10:13], v[138:141], v[236:239], v[10:13]
	v_mfma_f32_16x16x32_bf16 v[26:29], v[138:141], v[214:217], v[26:29]
	v_mfma_f32_16x16x32_bf16 v[30:33], v[130:133], v[214:217], v[30:33]
	v_mfma_f32_16x16x32_bf16 v[62:65], v[134:137], v[180:183], v[62:65]
	v_mfma_f32_16x16x32_bf16 v[58:61], v[152:155], v[180:183], v[58:61]
	v_mfma_f32_16x16x32_bf16 v[42:45], v[152:155], v[210:213], v[42:45]
	v_mfma_f32_16x16x32_bf16 v[46:49], v[134:137], v[210:213], v[46:49]
	v_mfma_f32_16x16x32_bf16 v[38:41], v[160:163], v[210:213], v[38:41]
	v_mfma_f32_16x16x32_bf16 v[34:37], v[172:175], v[210:213], v[34:37]
	v_mfma_f32_16x16x32_bf16 v[50:53], v[172:175], v[180:183], v[50:53]
	v_mfma_f32_16x16x32_bf16 v[54:57], v[160:163], v[180:183], v[54:57]
	v_mfma_f32_16x16x32_bf16 v[22:25], v[160:163], v[218:221], v[22:25]
	v_mfma_f32_16x16x32_bf16 v[18:21], v[172:175], v[218:221], v[18:21]
	v_mfma_f32_16x16x32_bf16 v[2:5], v[172:175], v[240:243], v[2:5]
	v_mfma_f32_16x16x32_bf16 v[6:9], v[160:163], v[240:243], v[6:9]
	v_mfma_f32_16x16x32_bf16 v[14:17], v[134:137], v[240:243], v[14:17]
	v_mfma_f32_16x16x32_bf16 v[10:13], v[152:155], v[240:243], v[10:13]
	v_mfma_f32_16x16x32_bf16 v[26:29], v[152:155], v[218:221], v[26:29]
	v_mfma_f32_16x16x32_bf16 v[30:33], v[134:137], v[218:221], v[30:33]
	s_barrier
	s_add_i32 s12, 0, 0x18000
	s_add_i32 s13, 0, 0x1c000
	ds_read_b128 v[130:133], v198
	ds_read_b128 v[134:137], v198 offset:1024
	ds_read_b128 v[138:141], v198 offset:2048
	ds_read_b128 v[152:155], v198 offset:3072
	ds_read_b128 v[156:159], v199
	ds_read_b128 v[160:163], v199 offset:1024
	ds_read_b128 v[168:171], v199 offset:2048
	ds_read_b128 v[172:175], v199 offset:3072
	s_add_u32 s10, vcc_lo, 0x200000
	s_addc_u32 s11, vcc_hi, 0
	s_mov_b32 m0, s86
	ds_read_b128 v[176:179], v166 offset:32768
	ds_read_b128 v[180:183], v166 offset:33792
	ds_read_b128 v[206:209], v166 offset:34816
	ds_read_b128 v[210:213], v166 offset:35840
	ds_read_b128 v[214:217], v166 offset:36864
	ds_read_b128 v[218:221], v166 offset:37888
	ds_read_b128 v[236:239], v166 offset:38912
	ds_read_b128 v[240:243], v166 offset:39936
	global_load_lds_dwordx4 v190, s[10:11]
	s_mov_b32 m0, s87
	s_nop 0
	global_load_lds_dwordx4 v144, s[10:11]
	s_waitcnt vmcnt(8)
	s_waitcnt lgkmcnt(0)
	s_barrier
; #define PG8_STAGE(bufoff, gbase, voff) do { _Pragma("unroll") for (int _i = 0; _i < 2; ++_i) \
;         __builtin_amdgcn_global_load_lds((const unsigned*)((const char*)(gbase) + (voff)[_i]), (PG8_LAS unsigned*)(lds + (bufoff) + ldsw + _i * 8192), 16, 0, 0); } while (0)
; #define PG8_LDA(dst, b, h) do { _Pragma("unroll") for (int m = 0; m < 4; ++m) _Pragma("unroll") for (int k = 0; k < 2; ++k) dst[m][k] = *(const PG8_LAS bf16x8*)(lds + PG8_SA(b, h) + aoff + m * 2048 + k * 1024); } while (0)
; #define PG8_LDB(dst, b, h) do { _Pragma("unroll") for (int n = 0; n < 2; ++n) _Pragma("unroll") for (int k = 0; k < 2; ++k) dst[n][k] = *(const PG8_LAS bf16x8*)(lds + PG8_SB(b, h) + boff + n * 2048 + k * 1024); } while (0)
; #define PG8_MMA(ai, bj, At, Bt) do { __builtin_amdgcn_s_setprio(1); _Pragma("unroll") for (int m = 0; m < 4; ++m) _Pragma("unroll") for (int n = 0; n < 2; ++n) _Pragma("unroll") for (int k = 0; k < 2; ++k) \
;         acc[ai][bj][m][n] = __builtin_amdgcn_mfma_f32_16x16x32_bf16(Bt[n][k], At[m][k], acc[ai][bj][m][n], 0, 0, 0); __builtin_amdgcn_s_setprio(0); } while (0)
; #define PG8_WAIT_V(n) asm volatile("s_waitcnt vmcnt(" #n ")" ::: "memory")
; #define PG8_WAIT_L(n) asm volatile("s_waitcnt lgkmcnt(" #n ")" ::: "memory")
; #define PG8_BAR __builtin_amdgcn_s_barrier()
; #define PG8_SCHED __builtin_amdgcn_sched_barrier(0)
; template <class Epi, class Sched, bool ALIGN_EPI = false, bool SP2 = false>
; __device__ __forceinline__ void gemm_phase(PG8_LAS unsigned char* lds, const Gemm g, const Sched& S, const Epi& E) {
;     ...
;             PG8_LDB(B0, 1, 0); PG8_LDB(B1, 1, 1); PG8_SCHED; PG8_LDA(At, 1, 0); PG8_STAGE(PG8_SA(0, 1), a2 + hstep, voffA);
;             PG8_WAIT_V(8); PG8_WAIT_L(0); PG8_BAR; PG8_MMA(0, 0, At, B0); PG8_MMA(0, 1, At, B1); PG8_BAR; PG8_SCHED;
;             PG8_LDA(At, 1, 1); PG8_STAGE(PG8_SB(1, 0), b3, voffB); PG8_STAGE(PG8_SB(1, 1), b3 + hstepB, voffB); PG8_STAGE(PG8_SA(1, 0), a3, voffA);
;             PG8_WAIT_V(8); PG8_WAIT_L(0); PG8_BAR; PG8_MMA(1, 0, At, B0); PG8_MMA(1, 1, At, B1); PG8_BAR; PG8_SCHED;
	v_mfma_f32_16x16x32_bf16 v[126:129], v[130:133], v[176:179], v[126:129]
	v_mfma_f32_16x16x32_bf16 v[122:125], v[138:141], v[176:179], v[122:125]
	v_mfma_f32_16x16x32_bf16 v[106:109], v[138:141], v[206:209], v[106:109]
	v_mfma_f32_16x16x32_bf16 v[110:113], v[130:133], v[206:209], v[110:113]
	v_mfma_f32_16x16x32_bf16 v[102:105], v[156:159], v[206:209], v[102:105]
	v_mfma_f32_16x16x32_bf16 v[98:101], v[168:171], v[206:209], v[98:101]
	v_mfma_f32_16x16x32_bf16 v[114:117], v[168:171], v[176:179], v[114:117]
	v_mfma_f32_16x16x32_bf16 v[118:121], v[156:159], v[176:179], v[118:121]
	v_mfma_f32_16x16x32_bf16 v[86:89], v[156:159], v[214:217], v[86:89]
	v_mfma_f32_16x16x32_bf16 v[82:85], v[168:171], v[214:217], v[82:85]
	v_mfma_f32_16x16x32_bf16 v[66:69], v[168:171], v[236:239], v[66:69]
	v_mfma_f32_16x16x32_bf16 v[70:73], v[156:159], v[236:239], v[70:73]
	v_mfma_f32_16x16x32_bf16 v[78:81], v[130:133], v[236:239], v[78:81]
	v_mfma_f32_16x16x32_bf16 v[74:77], v[138:141], v[236:239], v[74:77]
	v_mfma_f32_16x16x32_bf16 v[90:93], v[138:141], v[214:217], v[90:93]
	v_mfma_f32_16x16x32_bf16 v[94:97], v[130:133], v[214:217], v[94:97]
	v_mfma_f32_16x16x32_bf16 v[126:129], v[134:137], v[180:183], v[126:129]
	v_mfma_f32_16x16x32_bf16 v[122:125], v[152:155], v[180:183], v[122:125]
	v_mfma_f32_16x16x32_bf16 v[106:109], v[152:155], v[210:213], v[106:109]
	v_mfma_f32_16x16x32_bf16 v[110:113], v[134:137], v[210:213], v[110:113]
	v_mfma_f32_16x16x32_bf16 v[102:105], v[160:163], v[210:213], v[102:105]
	v_mfma_f32_16x16x32_bf16 v[98:101], v[172:175], v[210:213], v[98:101]
	v_mfma_f32_16x16x32_bf16 v[114:117], v[172:175], v[180:183], v[114:117]
	v_mfma_f32_16x16x32_bf16 v[118:121], v[160:163], v[180:183], v[118:121]
	v_mfma_f32_16x16x32_bf16 v[86:89], v[160:163], v[218:221], v[86:89]
	v_mfma_f32_16x16x32_bf16 v[82:85], v[172:175], v[218:221], v[82:85]
	v_mfma_f32_16x16x32_bf16 v[66:69], v[172:175], v[240:243], v[66:69]
	v_mfma_f32_16x16x32_bf16 v[70:73], v[160:163], v[240:243], v[70:73]
	v_mfma_f32_16x16x32_bf16 v[78:81], v[134:137], v[240:243], v[78:81]
	v_mfma_f32_16x16x32_bf16 v[74:77], v[152:155], v[240:243], v[74:77]
	v_mfma_f32_16x16x32_bf16 v[90:93], v[152:155], v[218:221], v[90:93]
	v_mfma_f32_16x16x32_bf16 v[94:97], v[134:137], v[218:221], v[94:97]
	s_barrier
	s_add_i32 s10, s12, s67
	s_mov_b32 m0, s10
	ds_read_b128 v[176:179], v166 offset:49152
	ds_read_b128 v[180:183], v166 offset:50176
	ds_read_b128 v[206:209], v166 offset:51200
	ds_read_b128 v[210:213], v166 offset:52224
	ds_read_b128 v[214:217], v166 offset:53248
	ds_read_b128 v[218:221], v166 offset:54272
	ds_read_b128 v[236:239], v166 offset:55296
	ds_read_b128 v[240:243], v166 offset:56320
	s_add_u32 s100, s46, s60
	s_addc_u32 s101, s47, s61
	global_load_lds_dwordx4 v146, s[100:101]
	s_add_i32 m0, s10, 0x2000
	s_add_u32 s10, s46, 0x80080
	s_addc_u32 s11, s47, 0
	s_add_i32 s12, s13, s67
	global_load_lds_dwordx4 v142, s[100:101]
	s_mov_b32 m0, s12
	s_nop 0
	global_load_lds_dwordx4 v146, s[10:11]
	s_add_i32 m0, s12, 0x2000
	s_nop 0
	global_load_lds_dwordx4 v142, s[10:11]
	s_mov_b32 m0, s82
	s_add_u32 s100, vcc_lo, s60
	s_addc_u32 s101, vcc_hi, s61
	global_load_lds_dwordx4 v190, s[100:101]
	s_mov_b32 m0, s42
	s_nop 0
	global_load_lds_dwordx4 v144, s[100:101]
	s_waitcnt vmcnt(8)
	s_waitcnt lgkmcnt(0)
	s_barrier
	v_mfma_f32_16x16x32_bf16 v[62:65], v[130:133], v[176:179], v[62:65]
	v_mfma_f32_16x16x32_bf16 v[58:61], v[138:141], v[176:179], v[58:61]
	v_mfma_f32_16x16x32_bf16 v[42:45], v[138:141], v[206:209], v[42:45]
	v_mfma_f32_16x16x32_bf16 v[46:49], v[130:133], v[206:209], v[46:49]
	v_mfma_f32_16x16x32_bf16 v[38:41], v[156:159], v[206:209], v[38:41]
	v_mfma_f32_16x16x32_bf16 v[34:37], v[168:171], v[206:209], v[34:37]
	v_mfma_f32_16x16x32_bf16 v[50:53], v[168:171], v[176:179], v[50:53]
	v_mfma_f32_16x16x32_bf16 v[54:57], v[156:159], v[176:179], v[54:57]
	v_mfma_f32_16x16x32_bf16 v[22:25], v[156:159], v[214:217], v[22:25]
	v_mfma_f32_16x16x32_bf16 v[18:21], v[168:171], v[214:217], v[18:21]
	v_mfma_f32_16x16x32_bf16 v[2:5], v[168:171], v[236:239], v[2:5]
	v_mfma_f32_16x16x32_bf16 v[6:9], v[156:159], v[236:239], v[6:9]
	v_mfma_f32_16x16x32_bf16 v[14:17], v[130:133], v[236:239], v[14:17]
	v_mfma_f32_16x16x32_bf16 v[10:13], v[138:141], v[236:239], v[10:13]
	v_mfma_f32_16x16x32_bf16 v[26:29], v[138:141], v[214:217], v[26:29]
	v_mfma_f32_16x16x32_bf16 v[30:33], v[130:133], v[214:217], v[30:33]
	v_mfma_f32_16x16x32_bf16 v[62:65], v[134:137], v[180:183], v[62:65]
	v_mfma_f32_16x16x32_bf16 v[58:61], v[152:155], v[180:183], v[58:61]
	v_mfma_f32_16x16x32_bf16 v[42:45], v[152:155], v[210:213], v[42:45]
	v_mfma_f32_16x16x32_bf16 v[46:49], v[134:137], v[210:213], v[46:49]
	v_mfma_f32_16x16x32_bf16 v[38:41], v[160:163], v[210:213], v[38:41]
	v_mfma_f32_16x16x32_bf16 v[34:37], v[172:175], v[210:213], v[34:37]
	v_mfma_f32_16x16x32_bf16 v[50:53], v[172:175], v[180:183], v[50:53]
	v_mfma_f32_16x16x32_bf16 v[54:57], v[160:163], v[180:183], v[54:57]
	v_mfma_f32_16x16x32_bf16 v[22:25], v[160:163], v[218:221], v[22:25]
	v_mfma_f32_16x16x32_bf16 v[18:21], v[172:175], v[218:221], v[18:21]
	v_mfma_f32_16x16x32_bf16 v[2:5], v[172:175], v[240:243], v[2:5]
	v_mfma_f32_16x16x32_bf16 v[6:9], v[160:163], v[240:243], v[6:9]
	v_mfma_f32_16x16x32_bf16 v[14:17], v[134:137], v[240:243], v[14:17]
	v_mfma_f32_16x16x32_bf16 v[10:13], v[152:155], v[240:243], v[10:13]
	v_mfma_f32_16x16x32_bf16 v[26:29], v[152:155], v[218:221], v[26:29]
	v_mfma_f32_16x16x32_bf16 v[30:33], v[134:137], v[218:221], v[30:33]
	s_barrier
	s_add_i32 s9, s9, 2
	s_add_u32 s38, s38, 0x100
	s_addc_u32 s39, s39, 0
	s_add_u32 s7, s7, 0x100
	s_addc_u32 s8, s8, 0
	s_cmpk_gt_u32 s9, 0x7d
	s_cbranch_scc0 .LBB0_1071
	s_and_b64 vcc, exec, s[72:73]
	s_cbranch_vccz .LBB0_1074
	s_barrier

; #define PG8_STAGE(bufoff, gbase, voff) do { _Pragma("unroll") for (int _i = 0; _i < 2; ++_i) \
;         __builtin_amdgcn_global_load_lds((const unsigned*)((const char*)(gbase) + (voff)[_i]), (PG8_LAS unsigned*)(lds + (bufoff) + ldsw + _i * 8192), 16, 0, 0); } while (0)
; #define PG8_LDA(dst, b, h) do { _Pragma("unroll") for (int m = 0; m < 4; ++m) _Pragma("unroll") for (int k = 0; k < 2; ++k) dst[m][k] = *(const PG8_LAS bf16x8*)(lds + PG8_SA(b, h) + aoff + m * 2048 + k * 1024); } while (0)
; #define PG8_LDB(dst, b, h) do { _Pragma("unroll") for (int n = 0; n < 2; ++n) _Pragma("unroll") for (int k = 0; k < 2; ++k) dst[n][k] = *(const PG8_LAS bf16x8*)(lds + PG8_SB(b, h) + boff + n * 2048 + k * 1024); } while (0)
; #define PG8_MMA(ai, bj, At, Bt) do { __builtin_amdgcn_s_setprio(1); _Pragma("unroll") for (int m = 0; m < 4; ++m) _Pragma("unroll") for (int n = 0; n < 2; ++n) _Pragma("unroll") for (int k = 0; k < 2; ++k) \
;         acc[ai][bj][m][n] = __builtin_amdgcn_mfma_f32_16x16x32_bf16(Bt[n][k], At[m][k], acc[ai][bj][m][n], 0, 0, 0); __builtin_amdgcn_s_setprio(0); } while (0)
; #define PG8_BAR __builtin_amdgcn_s_barrier()
; template <class Epi, class Sched, bool ALIGN_EPI = false, bool SP2 = false>
; __device__ __forceinline__ void gemm_phase(PG8_LAS unsigned char* lds, const Gemm g, const Sched& S, const Epi& E) {
;     ...
;         const bool has_next = S.next(ui + 1, nxt);
;         const char* nA = has_next ? (const char*)g.A + (size_t)nxt.pm * tstep : cA; const char* nB = has_next ? (const char*)g.Bt + (size_t)nxt.pn * tstep : cB;
;         for (int t = 0; t < nt; t += 2) {
;             const bool last = (t == nt - 2);
;             const char* a1 = cA + (size_t)(t + 1) * kstep;
;             const char* a2 = last ? nA : cA + (size_t)(t + 2) * kstep; const char* b2 = last ? nB : cB + (size_t)(t + 2) * kstep;
;             const char* a3 = a2 + kstep; const char* b3 = b2 + kstep;
;             if (last && has_next) S.a_ready(nxt);
;             if constexpr (SP2) {
;             PG8_LDB(B0, 0, 0); PG8_LDB(B1, 0, 1); PG8_SCHED; PG8_LDA(At, 0, 0); PG8_STAGE(PG8_SA(1, 1), a1 + hstep, voffA);
;             PG8_WAIT_V(8); PG8_WAIT_L(0); PG8_BAR; PG8_MMA(0, 0, At, B0); PG8_MMA(0, 1, At, B1); PG8_BAR; PG8_SCHED;
;             PG8_LDA(At, 0, 1); PG8_STAGE(PG8_SB(0, 0), b2, voffB); PG8_STAGE(PG8_SB(0, 1), b2 + hstepB, voffB); PG8_STAGE(PG8_SA(0, 0), a2, voffA);
.LBB0_1232:
	s_add_u32 s36, s80, 0x100
	s_addc_u32 s37, s81, 0
	s_ashr_i32 s73, s72, 31
	s_lshl_b64 s[4:5], s[72:73], 20
	s_add_u32 s78, s0, s4
	s_addc_u32 s79, s1, s5
	s_and_b64 s[4:5], s[46:47], exec
	s_cselect_b32 s4, s79, s69
	s_cselect_b32 s5, s78, s68
	s_ashr_i32 s71, s70, 31
	s_lshl_b64 s[6:7], s[70:71], 20
	s_add_u32 s76, s34, s6
	s_addc_u32 s77, s35, s7
	s_and_b64 s[6:7], s[46:47], exec
	s_cselect_b32 s6, s77, s81
	s_cselect_b32 s7, s76, s80
	s_add_u32 s8, s68, 0x80080
	s_addc_u32 s9, s69, 0
	v_lshl_add_u64 v[140:141], s[8:9], 0, v[136:137]
	v_lshl_add_u64 v[142:143], s[8:9], 0, v[138:139]
	s_mov_b32 s8, -2
	s_mov_b64 s[80:81], 0
	v_add_u32_e32 v186, 0x10000, v145
	v_add_u32_e32 v187, 0x14000, v145
	v_add_u32_e32 v198, 0x18000, v145
	v_add_u32_e32 v199, 0x1c000, v145
	s_add_u32 s9, s68, s80
	s_addc_u32 s10, s69, s81
	s_add_u32 s9, s9, 0x100
	s_addc_u32 s10, s10, 0
	s_add_u32 s100, s9, 0x7ff80
	s_addc_u32 s101, s10, 0
	s_add_u32 s11, s36, s80
	s_addc_u32 s12, s37, s81
	s_add_i32 s13, 0, 0x10000
	s_cmpk_eq_i32 s80, 0xf00
	s_cselect_b32 s93, s4, s10
	s_cselect_b32 s92, s5, s9
	s_cselect_b32 s85, s6, s12
	s_cselect_b32 s84, s7, s11
	s_add_i32 s9, 0, 0x14000
	ds_read_b128 v[152:155], v186
	ds_read_b128 v[156:159], v186 offset:1024
	ds_read_b128 v[160:163], v186 offset:2048
	ds_read_b128 v[164:167], v186 offset:3072
	ds_read_b128 v[168:171], v187
	ds_read_b128 v[172:175], v187 offset:1024
	ds_read_b128 v[176:179], v187 offset:2048
	ds_read_b128 v[180:183], v187 offset:3072
	s_add_i32 m0, s51, 0xc000
	ds_read_b128 v[206:209], v151
	ds_read_b128 v[210:213], v151 offset:1024
	ds_read_b128 v[214:217], v151 offset:2048
	ds_read_b128 v[218:221], v151 offset:3072
	ds_read_b128 v[236:239], v151 offset:4096
	ds_read_b128 v[240:243], v151 offset:5120
	ds_read_b128 v[244:247], v151 offset:6144
	ds_read_b128 v[194:197], v151 offset:7168
	global_load_lds_dwordx4 v136, s[100:101]
	s_add_i32 m0, s51, 0xe000
	s_nop 0
	global_load_lds_dwordx4 v138, s[100:101]
	s_waitcnt vmcnt(8)
	s_waitcnt lgkmcnt(0)
	s_barrier
	v_mfma_f32_16x16x32_bf16 v[126:129], v[152:155], v[206:209], 0
	v_mfma_f32_16x16x32_bf16 v[122:125], v[160:163], v[206:209], 0
	v_mfma_f32_16x16x32_bf16 v[114:117], v[160:163], v[214:217], 0
	v_mfma_f32_16x16x32_bf16 v[118:121], v[152:155], v[214:217], 0
	v_mfma_f32_16x16x32_bf16 v[86:89], v[168:171], v[214:217], 0
	v_mfma_f32_16x16x32_bf16 v[82:85], v[176:179], v[214:217], 0
	v_mfma_f32_16x16x32_bf16 v[90:93], v[176:179], v[206:209], 0
	v_mfma_f32_16x16x32_bf16 v[94:97], v[168:171], v[206:209], 0
	v_mfma_f32_16x16x32_bf16 v[78:81], v[168:171], v[236:239], 0
	v_mfma_f32_16x16x32_bf16 v[74:77], v[176:179], v[236:239], 0
	v_mfma_f32_16x16x32_bf16 v[66:69], v[176:179], v[244:247], 0
	v_mfma_f32_16x16x32_bf16 v[70:73], v[168:171], v[244:247], 0
	v_mfma_f32_16x16x32_bf16 v[102:105], v[152:155], v[244:247], 0
	v_mfma_f32_16x16x32_bf16 v[98:101], v[160:163], v[244:247], 0
	v_mfma_f32_16x16x32_bf16 v[106:109], v[160:163], v[236:239], 0
	v_mfma_f32_16x16x32_bf16 v[110:113], v[152:155], v[236:239], 0
	v_mfma_f32_16x16x32_bf16 v[126:129], v[156:159], v[210:213], v[126:129]
	v_mfma_f32_16x16x32_bf16 v[122:125], v[164:167], v[210:213], v[122:125]
	v_mfma_f32_16x16x32_bf16 v[114:117], v[164:167], v[218:221], v[114:117]
	v_mfma_f32_16x16x32_bf16 v[118:121], v[156:159], v[218:221], v[118:121]
	v_mfma_f32_16x16x32_bf16 v[86:89], v[172:175], v[218:221], v[86:89]
	v_mfma_f32_16x16x32_bf16 v[82:85], v[180:183], v[218:221], v[82:85]
	v_mfma_f32_16x16x32_bf16 v[90:93], v[180:183], v[210:213], v[90:93]
	v_mfma_f32_16x16x32_bf16 v[94:97], v[172:175], v[210:213], v[94:97]
	v_mfma_f32_16x16x32_bf16 v[78:81], v[172:175], v[240:243], v[78:81]
	v_mfma_f32_16x16x32_bf16 v[74:77], v[180:183], v[240:243], v[74:77]
	v_mfma_f32_16x16x32_bf16 v[66:69], v[180:183], v[194:197], v[66:69]
	v_mfma_f32_16x16x32_bf16 v[70:73], v[172:175], v[194:197], v[70:73]
	v_mfma_f32_16x16x32_bf16 v[102:105], v[156:159], v[194:197], v[102:105]
	v_mfma_f32_16x16x32_bf16 v[98:101], v[164:167], v[194:197], v[98:101]
	v_mfma_f32_16x16x32_bf16 v[106:109], v[164:167], v[240:243], v[106:109]
	v_mfma_f32_16x16x32_bf16 v[110:113], v[156:159], v[240:243], v[110:113]
	s_barrier
	s_add_i32 s10, s13, s42
	s_mov_b32 m0, s10
	ds_read_b128 v[194:197], v151 offset:16384
	ds_read_b128 v[206:209], v151 offset:17408
	ds_read_b128 v[210:213], v151 offset:18432
	ds_read_b128 v[214:217], v151 offset:19456
	ds_read_b128 v[218:221], v151 offset:20480
	ds_read_b128 v[236:239], v151 offset:21504
	ds_read_b128 v[240:243], v151 offset:22528
	ds_read_b128 v[244:247], v151 offset:23552
	global_load_lds_dwordx4 v130, s[84:85]
	s_add_i32 m0, s10, 0x2000
	s_add_u32 s10, s84, 0x20000
	s_addc_u32 s11, s85, 0
	s_add_i32 s9, s9, s42
	global_load_lds_dwordx4 v134, s[84:85]
	s_mov_b32 m0, s9
	s_nop 0
	global_load_lds_dwordx4 v130, s[10:11]
	s_add_i32 m0, s9, 0x2000
	s_nop 0
	global_load_lds_dwordx4 v134, s[10:11]
	s_mov_b32 m0, s51
	s_nop 0
	global_load_lds_dwordx4 v190, s[92:93]
	s_mov_b32 m0, s67
	s_nop 0
	global_load_lds_dwordx4 v132, s[92:93]
	s_waitcnt vmcnt(8)
	s_waitcnt lgkmcnt(0)
	s_barrier
; #define PG8_STAGE(bufoff, gbase, voff) do { _Pragma("unroll") for (int _i = 0; _i < 2; ++_i) \
;         __builtin_amdgcn_global_load_lds((const unsigned*)((const char*)(gbase) + (voff)[_i]), (PG8_LAS unsigned*)(lds + (bufoff) + ldsw + _i * 8192), 16, 0, 0); } while (0)
; #define PG8_LDA(dst, b, h) do { _Pragma("unroll") for (int m = 0; m < 4; ++m) _Pragma("unroll") for (int k = 0; k < 2; ++k) dst[m][k] = *(const PG8_LAS bf16x8*)(lds + PG8_SA(b, h) + aoff + m * 2048 + k * 1024); } while (0)
; #define PG8_LDB(dst, b, h) do { _Pragma("unroll") for (int n = 0; n < 2; ++n) _Pragma("unroll") for (int k = 0; k < 2; ++k) dst[n][k] = *(const PG8_LAS bf16x8*)(lds + PG8_SB(b, h) + boff + n * 2048 + k * 1024); } while (0)
; #define PG8_MMA(ai, bj, At, Bt) do { __builtin_amdgcn_s_setprio(1); _Pragma("unroll") for (int m = 0; m < 4; ++m) _Pragma("unroll") for (int n = 0; n < 2; ++n) _Pragma("unroll") for (int k = 0; k < 2; ++k) \
;         acc[ai][bj][m][n] = __builtin_amdgcn_mfma_f32_16x16x32_bf16(Bt[n][k], At[m][k], acc[ai][bj][m][n], 0, 0, 0); __builtin_amdgcn_s_setprio(0); } while (0)
; #define PG8_WAIT_V(n) asm volatile("s_waitcnt vmcnt(" #n ")" ::: "memory")
; #define PG8_WAIT_L(n) asm volatile("s_waitcnt lgkmcnt(" #n ")" ::: "memory")
; #define PG8_BAR __builtin_amdgcn_s_barrier()
; #define PG8_SCHED __builtin_amdgcn_sched_barrier(0)
; template <class Epi, class Sched, bool ALIGN_EPI = false, bool SP2 = false>
; __device__ __forceinline__ void gemm_phase(PG8_LAS unsigned char* lds, const Gemm g, const Sched& S, const Epi& E) {
;     ...
;             PG8_WAIT_V(8); PG8_WAIT_L(0); PG8_BAR; PG8_MMA(1, 0, At, B0); PG8_MMA(1, 1, At, B1); PG8_BAR; PG8_SCHED;
;             PG8_LDB(B0, 1, 0); PG8_LDB(B1, 1, 1); PG8_SCHED; PG8_LDA(At, 1, 0); PG8_STAGE(PG8_SA(0, 1), a2 + hstep, voffA);
;             PG8_WAIT_V(8); PG8_WAIT_L(0); PG8_BAR; PG8_MMA(0, 0, At, B0); PG8_MMA(0, 1, At, B1); PG8_BAR; PG8_SCHED;
	v_mfma_f32_16x16x32_bf16 v[62:65], v[152:155], v[194:197], 0
	v_mfma_f32_16x16x32_bf16 v[58:61], v[160:163], v[194:197], 0
	v_mfma_f32_16x16x32_bf16 v[50:53], v[160:163], v[210:213], 0
	v_mfma_f32_16x16x32_bf16 v[54:57], v[152:155], v[210:213], 0
	v_mfma_f32_16x16x32_bf16 v[22:25], v[168:171], v[210:213], 0
	v_mfma_f32_16x16x32_bf16 v[18:21], v[176:179], v[210:213], 0
	v_mfma_f32_16x16x32_bf16 v[26:29], v[176:179], v[194:197], 0
	v_mfma_f32_16x16x32_bf16 v[30:33], v[168:171], v[194:197], 0
	v_mfma_f32_16x16x32_bf16 v[14:17], v[168:171], v[218:221], 0
	v_mfma_f32_16x16x32_bf16 v[10:13], v[176:179], v[218:221], 0
	v_mfma_f32_16x16x32_bf16 v[2:5], v[176:179], v[240:243], 0
	v_mfma_f32_16x16x32_bf16 v[6:9], v[168:171], v[240:243], 0
	v_mfma_f32_16x16x32_bf16 v[38:41], v[152:155], v[240:243], 0
	v_mfma_f32_16x16x32_bf16 v[34:37], v[160:163], v[240:243], 0
	v_mfma_f32_16x16x32_bf16 v[42:45], v[160:163], v[218:221], 0
	v_mfma_f32_16x16x32_bf16 v[46:49], v[152:155], v[218:221], 0
	v_mfma_f32_16x16x32_bf16 v[62:65], v[156:159], v[206:209], v[62:65]
	v_mfma_f32_16x16x32_bf16 v[58:61], v[164:167], v[206:209], v[58:61]
	v_mfma_f32_16x16x32_bf16 v[50:53], v[164:167], v[214:217], v[50:53]
	v_mfma_f32_16x16x32_bf16 v[54:57], v[156:159], v[214:217], v[54:57]
	v_mfma_f32_16x16x32_bf16 v[22:25], v[172:175], v[214:217], v[22:25]
	v_mfma_f32_16x16x32_bf16 v[18:21], v[180:183], v[214:217], v[18:21]
	v_mfma_f32_16x16x32_bf16 v[26:29], v[180:183], v[206:209], v[26:29]
	v_mfma_f32_16x16x32_bf16 v[30:33], v[172:175], v[206:209], v[30:33]
	v_mfma_f32_16x16x32_bf16 v[14:17], v[172:175], v[236:239], v[14:17]
	v_mfma_f32_16x16x32_bf16 v[10:13], v[180:183], v[236:239], v[10:13]
	v_mfma_f32_16x16x32_bf16 v[2:5], v[180:183], v[244:247], v[2:5]
	v_mfma_f32_16x16x32_bf16 v[6:9], v[172:175], v[244:247], v[6:9]
	v_mfma_f32_16x16x32_bf16 v[38:41], v[156:159], v[244:247], v[38:41]
	v_mfma_f32_16x16x32_bf16 v[34:37], v[164:167], v[244:247], v[34:37]
	v_mfma_f32_16x16x32_bf16 v[42:45], v[164:167], v[236:239], v[42:45]
	v_mfma_f32_16x16x32_bf16 v[46:49], v[156:159], v[236:239], v[46:49]
	s_barrier
	s_add_i32 s9, 0, 0x18000
	s_add_i32 s12, 0, 0x1c000
	ds_read_b128 v[152:155], v198
	ds_read_b128 v[156:159], v198 offset:1024
	ds_read_b128 v[160:163], v198 offset:2048
	ds_read_b128 v[164:167], v198 offset:3072
	ds_read_b128 v[168:171], v199
	ds_read_b128 v[172:175], v199 offset:1024
	ds_read_b128 v[176:179], v199 offset:2048
	ds_read_b128 v[180:183], v199 offset:3072
	s_add_u32 s10, s92, 0x80000
	s_addc_u32 s11, s93, 0
	s_mov_b32 m0, s74
	ds_read_b128 v[194:197], v151 offset:32768
	ds_read_b128 v[206:209], v151 offset:33792
	ds_read_b128 v[210:213], v151 offset:34816
	ds_read_b128 v[214:217], v151 offset:35840
	ds_read_b128 v[218:221], v151 offset:36864
	ds_read_b128 v[236:239], v151 offset:37888
	ds_read_b128 v[240:243], v151 offset:38912
	ds_read_b128 v[244:247], v151 offset:39936
	global_load_lds_dwordx4 v190, s[10:11]
	s_mov_b32 m0, s75
	s_nop 0
	global_load_lds_dwordx4 v132, s[10:11]
	s_waitcnt vmcnt(8)
	s_waitcnt lgkmcnt(0)
	s_barrier
	v_mfma_f32_16x16x32_bf16 v[126:129], v[152:155], v[194:197], v[126:129]
	v_mfma_f32_16x16x32_bf16 v[122:125], v[160:163], v[194:197], v[122:125]
	v_mfma_f32_16x16x32_bf16 v[114:117], v[160:163], v[210:213], v[114:117]
	v_mfma_f32_16x16x32_bf16 v[118:121], v[152:155], v[210:213], v[118:121]
	v_mfma_f32_16x16x32_bf16 v[86:89], v[168:171], v[210:213], v[86:89]
	v_mfma_f32_16x16x32_bf16 v[82:85], v[176:179], v[210:213], v[82:85]
	v_mfma_f32_16x16x32_bf16 v[90:93], v[176:179], v[194:197], v[90:93]
	v_mfma_f32_16x16x32_bf16 v[94:97], v[168:171], v[194:197], v[94:97]
	v_mfma_f32_16x16x32_bf16 v[78:81], v[168:171], v[218:221], v[78:81]
	v_mfma_f32_16x16x32_bf16 v[74:77], v[176:179], v[218:221], v[74:77]
	v_mfma_f32_16x16x32_bf16 v[66:69], v[176:179], v[240:243], v[66:69]
	v_mfma_f32_16x16x32_bf16 v[70:73], v[168:171], v[240:243], v[70:73]
	v_mfma_f32_16x16x32_bf16 v[102:105], v[152:155], v[240:243], v[102:105]
	v_mfma_f32_16x16x32_bf16 v[98:101], v[160:163], v[240:243], v[98:101]
	v_mfma_f32_16x16x32_bf16 v[106:109], v[160:163], v[218:221], v[106:109]
	v_mfma_f32_16x16x32_bf16 v[110:113], v[152:155], v[218:221], v[110:113]
	v_mfma_f32_16x16x32_bf16 v[126:129], v[156:159], v[206:209], v[126:129]
	v_mfma_f32_16x16x32_bf16 v[122:125], v[164:167], v[206:209], v[122:125]
	v_mfma_f32_16x16x32_bf16 v[114:117], v[164:167], v[214:217], v[114:117]
	v_mfma_f32_16x16x32_bf16 v[118:121], v[156:159], v[214:217], v[118:121]
	v_mfma_f32_16x16x32_bf16 v[86:89], v[172:175], v[214:217], v[86:89]
	v_mfma_f32_16x16x32_bf16 v[82:85], v[180:183], v[214:217], v[82:85]
	v_mfma_f32_16x16x32_bf16 v[90:93], v[180:183], v[206:209], v[90:93]
	v_mfma_f32_16x16x32_bf16 v[94:97], v[172:175], v[206:209], v[94:97]
	v_mfma_f32_16x16x32_bf16 v[78:81], v[172:175], v[236:239], v[78:81]
	v_mfma_f32_16x16x32_bf16 v[74:77], v[180:183], v[236:239], v[74:77]
	v_mfma_f32_16x16x32_bf16 v[66:69], v[180:183], v[244:247], v[66:69]
	v_mfma_f32_16x16x32_bf16 v[70:73], v[172:175], v[244:247], v[70:73]
	v_mfma_f32_16x16x32_bf16 v[102:105], v[156:159], v[244:247], v[102:105]
	v_mfma_f32_16x16x32_bf16 v[98:101], v[164:167], v[244:247], v[98:101]
	v_mfma_f32_16x16x32_bf16 v[106:109], v[164:167], v[236:239], v[106:109]
	v_mfma_f32_16x16x32_bf16 v[110:113], v[156:159], v[236:239], v[110:113]
	s_barrier
; #define PG8_STAGE(bufoff, gbase, voff) do { _Pragma("unroll") for (int _i = 0; _i < 2; ++_i) \
;         __builtin_amdgcn_global_load_lds((const unsigned*)((const char*)(gbase) + (voff)[_i]), (PG8_LAS unsigned*)(lds + (bufoff) + ldsw + _i * 8192), 16, 0, 0); } while (0)
; #define PG8_LDA(dst, b, h) do { _Pragma("unroll") for (int m = 0; m < 4; ++m) _Pragma("unroll") for (int k = 0; k < 2; ++k) dst[m][k] = *(const PG8_LAS bf16x8*)(lds + PG8_SA(b, h) + aoff + m * 2048 + k * 1024); } while (0)
; #define PG8_LDB(dst, b, h) do { _Pragma("unroll") for (int n = 0; n < 2; ++n) _Pragma("unroll") for (int k = 0; k < 2; ++k) dst[n][k] = *(const PG8_LAS bf16x8*)(lds + PG8_SB(b, h) + boff + n * 2048 + k * 1024); } while (0)
; #define PG8_MMA(ai, bj, At, Bt) do { __builtin_amdgcn_s_setprio(1); _Pragma("unroll") for (int m = 0; m < 4; ++m) _Pragma("unroll") for (int n = 0; n < 2; ++n) _Pragma("unroll") for (int k = 0; k < 2; ++k) \
;         acc[ai][bj][m][n] = __builtin_amdgcn_mfma_f32_16x16x32_bf16(Bt[n][k], At[m][k], acc[ai][bj][m][n], 0, 0, 0); __builtin_amdgcn_s_setprio(0); } while (0)
; #define PG8_WAIT_V(n) asm volatile("s_waitcnt vmcnt(" #n ")" ::: "memory")
; template <class Epi, class Sched, bool ALIGN_EPI = false, bool SP2 = false>
; __device__ __forceinline__ void gemm_phase(PG8_LAS unsigned char* lds, const Gemm g, const Sched& S, const Epi& E) {
;     ...
;             PG8_LDB(B0, 0, 0); PG8_LDB(B1, 0, 1); PG8_SCHED; PG8_LDA(At, 0, 0); PG8_STAGE(PG8_SA(1, 1), a1 + hstep, voffA);
;             PG8_WAIT_V(8); PG8_WAIT_L(0); PG8_BAR; PG8_MMA(0, 0, At, B0); PG8_MMA(0, 1, At, B1); PG8_BAR; PG8_SCHED;
;             PG8_LDA(At, 0, 1); PG8_STAGE(PG8_SB(0, 0), b2, voffB); PG8_STAGE(PG8_SB(0, 1), b2 + hstepB, voffB); PG8_STAGE(PG8_SA(0, 0), a2, voffA);
;             PG8_WAIT_V(8); PG8_WAIT_L(0); PG8_BAR; PG8_MMA(1, 0, At, B0); PG8_MMA(1, 1, At, B1); PG8_BAR; PG8_SCHED;
;             PG8_LDB(B0, 1, 0); PG8_LDB(B1, 1, 1); PG8_SCHED; PG8_LDA(At, 1, 0); PG8_STAGE(PG8_SA(0, 1), a2 + hstep, voffA);
;             PG8_WAIT_V(8); PG8_WAIT_L(0); PG8_BAR; PG8_MMA(0, 0, At, B0); PG8_MMA(0, 1, At, B1); PG8_BAR; PG8_SCHED;
;             PG8_LDA(At, 1, 1); PG8_STAGE(PG8_SB(1, 0), b3, voffB); PG8_STAGE(PG8_SB(1, 1), b3 + hstepB, voffB); PG8_STAGE(PG8_SA(1, 0), a3, voffA);
;             PG8_WAIT_V(8); PG8_WAIT_L(0); PG8_BAR; PG8_MMA(1, 0, At, B0); PG8_MMA(1, 1, At, B1); PG8_BAR; PG8_SCHED;
	s_add_i32 s9, s9, s42
	s_mov_b32 m0, s9
	ds_read_b128 v[194:197], v151 offset:49152
	ds_read_b128 v[206:209], v151 offset:50176
	ds_read_b128 v[210:213], v151 offset:51200
	ds_read_b128 v[214:217], v151 offset:52224
	ds_read_b128 v[218:221], v151 offset:53248
	ds_read_b128 v[236:239], v151 offset:54272
	ds_read_b128 v[240:243], v151 offset:55296
	ds_read_b128 v[244:247], v151 offset:56320
	s_add_u32 s100, s84, s60
	s_addc_u32 s101, s85, s61
	global_load_lds_dwordx4 v130, s[100:101]
	s_add_i32 m0, s9, 0x2000
	s_add_u32 s10, s84, 0x20080
	s_addc_u32 s11, s85, 0
	s_add_i32 s9, s12, s42
	global_load_lds_dwordx4 v134, s[100:101]
	s_mov_b32 m0, s9
	s_nop 0
	global_load_lds_dwordx4 v130, s[10:11]
	s_add_i32 m0, s9, 0x2000
	s_nop 0
	global_load_lds_dwordx4 v134, s[10:11]
	s_mov_b32 m0, s82
	s_add_u32 s100, s92, s60
	s_addc_u32 s101, s93, s61
	global_load_lds_dwordx4 v190, s[100:101]
	s_mov_b32 m0, s86
	s_nop 0
	global_load_lds_dwordx4 v132, s[100:101]
	s_waitcnt vmcnt(8)
	s_waitcnt lgkmcnt(0)
	s_barrier
	v_mfma_f32_16x16x32_bf16 v[62:65], v[152:155], v[194:197], v[62:65]
	v_mfma_f32_16x16x32_bf16 v[58:61], v[160:163], v[194:197], v[58:61]
	v_mfma_f32_16x16x32_bf16 v[50:53], v[160:163], v[210:213], v[50:53]
	v_mfma_f32_16x16x32_bf16 v[54:57], v[152:155], v[210:213], v[54:57]
	v_mfma_f32_16x16x32_bf16 v[22:25], v[168:171], v[210:213], v[22:25]
	v_mfma_f32_16x16x32_bf16 v[18:21], v[176:179], v[210:213], v[18:21]
	v_mfma_f32_16x16x32_bf16 v[26:29], v[176:179], v[194:197], v[26:29]
	v_mfma_f32_16x16x32_bf16 v[30:33], v[168:171], v[194:197], v[30:33]
	v_mfma_f32_16x16x32_bf16 v[14:17], v[168:171], v[218:221], v[14:17]
	v_mfma_f32_16x16x32_bf16 v[10:13], v[176:179], v[218:221], v[10:13]
	v_mfma_f32_16x16x32_bf16 v[2:5], v[176:179], v[240:243], v[2:5]
	v_mfma_f32_16x16x32_bf16 v[6:9], v[168:171], v[240:243], v[6:9]
	v_mfma_f32_16x16x32_bf16 v[38:41], v[152:155], v[240:243], v[38:41]
	v_mfma_f32_16x16x32_bf16 v[34:37], v[160:163], v[240:243], v[34:37]
	v_mfma_f32_16x16x32_bf16 v[42:45], v[160:163], v[218:221], v[42:45]
	v_mfma_f32_16x16x32_bf16 v[46:49], v[152:155], v[218:221], v[46:49]
	v_mfma_f32_16x16x32_bf16 v[62:65], v[156:159], v[206:209], v[62:65]
	v_mfma_f32_16x16x32_bf16 v[58:61], v[164:167], v[206:209], v[58:61]
	v_mfma_f32_16x16x32_bf16 v[50:53], v[164:167], v[214:217], v[50:53]
	v_mfma_f32_16x16x32_bf16 v[54:57], v[156:159], v[214:217], v[54:57]
	v_mfma_f32_16x16x32_bf16 v[22:25], v[172:175], v[214:217], v[22:25]
	v_mfma_f32_16x16x32_bf16 v[18:21], v[180:183], v[214:217], v[18:21]
	v_mfma_f32_16x16x32_bf16 v[26:29], v[180:183], v[206:209], v[26:29]
	v_mfma_f32_16x16x32_bf16 v[30:33], v[172:175], v[206:209], v[30:33]
	v_mfma_f32_16x16x32_bf16 v[14:17], v[172:175], v[236:239], v[14:17]
	v_mfma_f32_16x16x32_bf16 v[10:13], v[180:183], v[236:239], v[10:13]
	v_mfma_f32_16x16x32_bf16 v[2:5], v[180:183], v[244:247], v[2:5]
	v_mfma_f32_16x16x32_bf16 v[6:9], v[172:175], v[244:247], v[6:9]
	v_mfma_f32_16x16x32_bf16 v[38:41], v[156:159], v[244:247], v[38:41]
	v_mfma_f32_16x16x32_bf16 v[34:37], v[164:167], v[244:247], v[34:37]
	v_mfma_f32_16x16x32_bf16 v[42:45], v[164:167], v[236:239], v[42:45]
	v_mfma_f32_16x16x32_bf16 v[46:49], v[156:159], v[236:239], v[46:49]
	s_barrier
	s_add_i32 s8, s8, 2
	s_add_u32 s80, s80, 0x100
	s_addc_u32 s81, s81, 0
	s_cmp_gt_u32 s8, 29
.LBB0_1233:
	s_add_u32 s9, s68, s80
	s_addc_u32 s10, s69, s81
	s_add_u32 s9, s9, 0x100
	s_addc_u32 s10, s10, 0
	s_add_u32 s100, s9, 0x7ff80
	s_addc_u32 s101, s10, 0
	s_add_u32 s11, s36, s80
	s_addc_u32 s12, s37, s81
	s_add_i32 s13, 0, 0x10000
	s_cmpk_eq_i32 s80, 0xf00
	s_cselect_b32 s93, s4, s10
	s_cselect_b32 s92, s5, s9
	s_cselect_b32 s85, s6, s12
	s_cselect_b32 s84, s7, s11
	s_add_i32 s9, 0, 0x14000
	ds_read_b128 v[152:155], v186
	ds_read_b128 v[156:159], v186 offset:1024
	ds_read_b128 v[160:163], v186 offset:2048
	ds_read_b128 v[164:167], v186 offset:3072
	ds_read_b128 v[168:171], v187
	ds_read_b128 v[172:175], v187 offset:1024
	ds_read_b128 v[176:179], v187 offset:2048
	ds_read_b128 v[180:183], v187 offset:3072
	s_add_i32 m0, s51, 0xc000
	ds_read_b128 v[206:209], v151
	ds_read_b128 v[210:213], v151 offset:1024
	ds_read_b128 v[214:217], v151 offset:2048
	ds_read_b128 v[218:221], v151 offset:3072
	ds_read_b128 v[236:239], v151 offset:4096
	ds_read_b128 v[240:243], v151 offset:5120
	ds_read_b128 v[244:247], v151 offset:6144
	ds_read_b128 v[194:197], v151 offset:7168
	global_load_lds_dwordx4 v136, s[100:101]
	s_add_i32 m0, s51, 0xe000
	s_nop 0
	global_load_lds_dwordx4 v138, s[100:101]
	s_waitcnt vmcnt(8)
	s_waitcnt lgkmcnt(0)
	s_barrier
; #define PG8_STAGE(bufoff, gbase, voff) do { _Pragma("unroll") for (int _i = 0; _i < 2; ++_i) \
;         __builtin_amdgcn_global_load_lds((const unsigned*)((const char*)(gbase) + (voff)[_i]), (PG8_LAS unsigned*)(lds + (bufoff) + ldsw + _i * 8192), 16, 0, 0); } while (0)
; #define PG8_LDA(dst, b, h) do { _Pragma("unroll") for (int m = 0; m < 4; ++m) _Pragma("unroll") for (int k = 0; k < 2; ++k) dst[m][k] = *(const PG8_LAS bf16x8*)(lds + PG8_SA(b, h) + aoff + m * 2048 + k * 1024); } while (0)
; #define PG8_MMA(ai, bj, At, Bt) do { __builtin_amdgcn_s_setprio(1); _Pragma("unroll") for (int m = 0; m < 4; ++m) _Pragma("unroll") for (int n = 0; n < 2; ++n) _Pragma("unroll") for (int k = 0; k < 2; ++k) \
;         acc[ai][bj][m][n] = __builtin_amdgcn_mfma_f32_16x16x32_bf16(Bt[n][k], At[m][k], acc[ai][bj][m][n], 0, 0, 0); __builtin_amdgcn_s_setprio(0); } while (0)
; #define PG8_WAIT_V(n) asm volatile("s_waitcnt vmcnt(" #n ")" ::: "memory")
; #define PG8_WAIT_L(n) asm volatile("s_waitcnt lgkmcnt(" #n ")" ::: "memory")
; #define PG8_BAR __builtin_amdgcn_s_barrier()
; #define PG8_SCHED __builtin_amdgcn_sched_barrier(0)
; template <class Epi, class Sched, bool ALIGN_EPI = false, bool SP2 = false>
; __device__ __forceinline__ void gemm_phase(PG8_LAS unsigned char* lds, const Gemm g, const Sched& S, const Epi& E) {
;     ...
;             PG8_WAIT_V(8); PG8_WAIT_L(0); PG8_BAR; PG8_MMA(0, 0, At, B0); PG8_MMA(0, 1, At, B1); PG8_BAR; PG8_SCHED;
;             PG8_LDA(At, 0, 1); PG8_STAGE(PG8_SB(0, 0), b2, voffB); PG8_STAGE(PG8_SB(0, 1), b2 + hstepB, voffB); PG8_STAGE(PG8_SA(0, 0), a2, voffA);
;             PG8_WAIT_V(8); PG8_WAIT_L(0); PG8_BAR; PG8_MMA(1, 0, At, B0); PG8_MMA(1, 1, At, B1); PG8_BAR; PG8_SCHED;
	v_mfma_f32_16x16x32_bf16 v[126:129], v[152:155], v[206:209], v[126:129]
	v_mfma_f32_16x16x32_bf16 v[122:125], v[160:163], v[206:209], v[122:125]
	v_mfma_f32_16x16x32_bf16 v[114:117], v[160:163], v[214:217], v[114:117]
	v_mfma_f32_16x16x32_bf16 v[118:121], v[152:155], v[214:217], v[118:121]
	v_mfma_f32_16x16x32_bf16 v[86:89], v[168:171], v[214:217], v[86:89]
	v_mfma_f32_16x16x32_bf16 v[82:85], v[176:179], v[214:217], v[82:85]
	v_mfma_f32_16x16x32_bf16 v[90:93], v[176:179], v[206:209], v[90:93]
	v_mfma_f32_16x16x32_bf16 v[94:97], v[168:171], v[206:209], v[94:97]
	v_mfma_f32_16x16x32_bf16 v[78:81], v[168:171], v[236:239], v[78:81]
	v_mfma_f32_16x16x32_bf16 v[74:77], v[176:179], v[236:239], v[74:77]
	v_mfma_f32_16x16x32_bf16 v[66:69], v[176:179], v[244:247], v[66:69]
	v_mfma_f32_16x16x32_bf16 v[70:73], v[168:171], v[244:247], v[70:73]
	v_mfma_f32_16x16x32_bf16 v[102:105], v[152:155], v[244:247], v[102:105]
	v_mfma_f32_16x16x32_bf16 v[98:101], v[160:163], v[244:247], v[98:101]
	v_mfma_f32_16x16x32_bf16 v[106:109], v[160:163], v[236:239], v[106:109]
	v_mfma_f32_16x16x32_bf16 v[110:113], v[152:155], v[236:239], v[110:113]
	v_mfma_f32_16x16x32_bf16 v[126:129], v[156:159], v[210:213], v[126:129]
	v_mfma_f32_16x16x32_bf16 v[122:125], v[164:167], v[210:213], v[122:125]
	v_mfma_f32_16x16x32_bf16 v[114:117], v[164:167], v[218:221], v[114:117]
	v_mfma_f32_16x16x32_bf16 v[118:121], v[156:159], v[218:221], v[118:121]
	v_mfma_f32_16x16x32_bf16 v[86:89], v[172:175], v[218:221], v[86:89]
	v_mfma_f32_16x16x32_bf16 v[82:85], v[180:183], v[218:221], v[82:85]
	v_mfma_f32_16x16x32_bf16 v[90:93], v[180:183], v[210:213], v[90:93]
	v_mfma_f32_16x16x32_bf16 v[94:97], v[172:175], v[210:213], v[94:97]
	v_mfma_f32_16x16x32_bf16 v[78:81], v[172:175], v[240:243], v[78:81]
	v_mfma_f32_16x16x32_bf16 v[74:77], v[180:183], v[240:243], v[74:77]
	v_mfma_f32_16x16x32_bf16 v[66:69], v[180:183], v[194:197], v[66:69]
	v_mfma_f32_16x16x32_bf16 v[70:73], v[172:175], v[194:197], v[70:73]
	v_mfma_f32_16x16x32_bf16 v[102:105], v[156:159], v[194:197], v[102:105]
	v_mfma_f32_16x16x32_bf16 v[98:101], v[164:167], v[194:197], v[98:101]
	v_mfma_f32_16x16x32_bf16 v[106:109], v[164:167], v[240:243], v[106:109]
	v_mfma_f32_16x16x32_bf16 v[110:113], v[156:159], v[240:243], v[110:113]
	s_barrier
	s_add_i32 s10, s13, s42
	s_mov_b32 m0, s10
	ds_read_b128 v[194:197], v151 offset:16384
	ds_read_b128 v[206:209], v151 offset:17408
	ds_read_b128 v[210:213], v151 offset:18432
	ds_read_b128 v[214:217], v151 offset:19456
	ds_read_b128 v[218:221], v151 offset:20480
	ds_read_b128 v[236:239], v151 offset:21504
	ds_read_b128 v[240:243], v151 offset:22528
	ds_read_b128 v[244:247], v151 offset:23552
	global_load_lds_dwordx4 v130, s[84:85]
	s_add_i32 m0, s10, 0x2000
	s_add_u32 s10, s84, 0x20000
	s_addc_u32 s11, s85, 0
	s_add_i32 s9, s9, s42
	global_load_lds_dwordx4 v134, s[84:85]
	s_mov_b32 m0, s9
	s_nop 0
	global_load_lds_dwordx4 v130, s[10:11]
	s_add_i32 m0, s9, 0x2000
	s_nop 0
	global_load_lds_dwordx4 v134, s[10:11]
	s_mov_b32 m0, s51
	s_nop 0
	global_load_lds_dwordx4 v190, s[92:93]
	s_mov_b32 m0, s67
	s_nop 0
	global_load_lds_dwordx4 v132, s[92:93]
	s_waitcnt vmcnt(8)
	s_waitcnt lgkmcnt(0)
	s_barrier
	v_mfma_f32_16x16x32_bf16 v[62:65], v[152:155], v[194:197], v[62:65]
	v_mfma_f32_16x16x32_bf16 v[58:61], v[160:163], v[194:197], v[58:61]
	v_mfma_f32_16x16x32_bf16 v[50:53], v[160:163], v[210:213], v[50:53]
	v_mfma_f32_16x16x32_bf16 v[54:57], v[152:155], v[210:213], v[54:57]
	v_mfma_f32_16x16x32_bf16 v[22:25], v[168:171], v[210:213], v[22:25]
	v_mfma_f32_16x16x32_bf16 v[18:21], v[176:179], v[210:213], v[18:21]
	v_mfma_f32_16x16x32_bf16 v[26:29], v[176:179], v[194:197], v[26:29]
	v_mfma_f32_16x16x32_bf16 v[30:33], v[168:171], v[194:197], v[30:33]
	v_mfma_f32_16x16x32_bf16 v[14:17], v[168:171], v[218:221], v[14:17]
	v_mfma_f32_16x16x32_bf16 v[10:13], v[176:179], v[218:221], v[10:13]
	v_mfma_f32_16x16x32_bf16 v[2:5], v[176:179], v[240:243], v[2:5]
	v_mfma_f32_16x16x32_bf16 v[6:9], v[168:171], v[240:243], v[6:9]
	v_mfma_f32_16x16x32_bf16 v[38:41], v[152:155], v[240:243], v[38:41]
	v_mfma_f32_16x16x32_bf16 v[34:37], v[160:163], v[240:243], v[34:37]
	v_mfma_f32_16x16x32_bf16 v[42:45], v[160:163], v[218:221], v[42:45]
	v_mfma_f32_16x16x32_bf16 v[46:49], v[152:155], v[218:221], v[46:49]
	v_mfma_f32_16x16x32_bf16 v[62:65], v[156:159], v[206:209], v[62:65]
	v_mfma_f32_16x16x32_bf16 v[58:61], v[164:167], v[206:209], v[58:61]
	v_mfma_f32_16x16x32_bf16 v[50:53], v[164:167], v[214:217], v[50:53]
	v_mfma_f32_16x16x32_bf16 v[54:57], v[156:159], v[214:217], v[54:57]
	v_mfma_f32_16x16x32_bf16 v[22:25], v[172:175], v[214:217], v[22:25]
	v_mfma_f32_16x16x32_bf16 v[18:21], v[180:183], v[214:217], v[18:21]
	v_mfma_f32_16x16x32_bf16 v[26:29], v[180:183], v[206:209], v[26:29]
	v_mfma_f32_16x16x32_bf16 v[30:33], v[172:175], v[206:209], v[30:33]
	v_mfma_f32_16x16x32_bf16 v[14:17], v[172:175], v[236:239], v[14:17]
	v_mfma_f32_16x16x32_bf16 v[10:13], v[180:183], v[236:239], v[10:13]
	v_mfma_f32_16x16x32_bf16 v[2:5], v[180:183], v[244:247], v[2:5]
	v_mfma_f32_16x16x32_bf16 v[6:9], v[172:175], v[244:247], v[6:9]
	v_mfma_f32_16x16x32_bf16 v[38:41], v[156:159], v[244:247], v[38:41]
	v_mfma_f32_16x16x32_bf16 v[34:37], v[164:167], v[244:247], v[34:37]
	v_mfma_f32_16x16x32_bf16 v[42:45], v[164:167], v[236:239], v[42:45]
	v_mfma_f32_16x16x32_bf16 v[46:49], v[156:159], v[236:239], v[46:49]
	s_barrier
; #define PG8_STAGE(bufoff, gbase, voff) do { _Pragma("unroll") for (int _i = 0; _i < 2; ++_i) \
;         __builtin_amdgcn_global_load_lds((const unsigned*)((const char*)(gbase) + (voff)[_i]), (PG8_LAS unsigned*)(lds + (bufoff) + ldsw + _i * 8192), 16, 0, 0); } while (0)
; #define PG8_LDA(dst, b, h) do { _Pragma("unroll") for (int m = 0; m < 4; ++m) _Pragma("unroll") for (int k = 0; k < 2; ++k) dst[m][k] = *(const PG8_LAS bf16x8*)(lds + PG8_SA(b, h) + aoff + m * 2048 + k * 1024); } while (0)
; #define PG8_LDB(dst, b, h) do { _Pragma("unroll") for (int n = 0; n < 2; ++n) _Pragma("unroll") for (int k = 0; k < 2; ++k) dst[n][k] = *(const PG8_LAS bf16x8*)(lds + PG8_SB(b, h) + boff + n * 2048 + k * 1024); } while (0)
; #define PG8_MMA(ai, bj, At, Bt) do { __builtin_amdgcn_s_setprio(1); _Pragma("unroll") for (int m = 0; m < 4; ++m) _Pragma("unroll") for (int n = 0; n < 2; ++n) _Pragma("unroll") for (int k = 0; k < 2; ++k) \
;         acc[ai][bj][m][n] = __builtin_amdgcn_mfma_f32_16x16x32_bf16(Bt[n][k], At[m][k], acc[ai][bj][m][n], 0, 0, 0); __builtin_amdgcn_s_setprio(0); } while (0)
; #define PG8_WAIT_V(n) asm volatile("s_waitcnt vmcnt(" #n ")" ::: "memory")
; #define PG8_WAIT_L(n) asm volatile("s_waitcnt lgkmcnt(" #n ")" ::: "memory")
; #define PG8_BAR __builtin_amdgcn_s_barrier()
; #define PG8_SCHED __builtin_amdgcn_sched_barrier(0)
; template <class Epi, class Sched, bool ALIGN_EPI = false, bool SP2 = false>
; __device__ __forceinline__ void gemm_phase(PG8_LAS unsigned char* lds, const Gemm g, const Sched& S, const Epi& E) {
;     ...
;             PG8_LDB(B0, 1, 0); PG8_LDB(B1, 1, 1); PG8_SCHED; PG8_LDA(At, 1, 0); PG8_STAGE(PG8_SA(0, 1), a2 + hstep, voffA);
;             PG8_WAIT_V(8); PG8_WAIT_L(0); PG8_BAR; PG8_MMA(0, 0, At, B0); PG8_MMA(0, 1, At, B1); PG8_BAR; PG8_SCHED;
;             PG8_LDA(At, 1, 1); PG8_STAGE(PG8_SB(1, 0), b3, voffB); PG8_STAGE(PG8_SB(1, 1), b3 + hstepB, voffB); PG8_STAGE(PG8_SA(1, 0), a3, voffA);
;             PG8_WAIT_V(8); PG8_WAIT_L(0); PG8_BAR; PG8_MMA(1, 0, At, B0); PG8_MMA(1, 1, At, B1); PG8_BAR; PG8_SCHED;
	s_add_i32 s9, 0, 0x18000
	s_add_i32 s12, 0, 0x1c000
	ds_read_b128 v[152:155], v198
	ds_read_b128 v[156:159], v198 offset:1024
	ds_read_b128 v[160:163], v198 offset:2048
	ds_read_b128 v[164:167], v198 offset:3072
	ds_read_b128 v[168:171], v199
	ds_read_b128 v[172:175], v199 offset:1024
	ds_read_b128 v[176:179], v199 offset:2048
	ds_read_b128 v[180:183], v199 offset:3072
	s_add_u32 s10, s92, 0x80000
	s_addc_u32 s11, s93, 0
	s_mov_b32 m0, s74
	ds_read_b128 v[194:197], v151 offset:32768
	ds_read_b128 v[206:209], v151 offset:33792
	ds_read_b128 v[210:213], v151 offset:34816
	ds_read_b128 v[214:217], v151 offset:35840
	ds_read_b128 v[218:221], v151 offset:36864
	ds_read_b128 v[236:239], v151 offset:37888
	ds_read_b128 v[240:243], v151 offset:38912
	ds_read_b128 v[244:247], v151 offset:39936
	global_load_lds_dwordx4 v190, s[10:11]
	s_mov_b32 m0, s75
	s_nop 0
	global_load_lds_dwordx4 v132, s[10:11]
	s_waitcnt vmcnt(8)
	s_waitcnt lgkmcnt(0)
	s_barrier
	v_mfma_f32_16x16x32_bf16 v[126:129], v[152:155], v[194:197], v[126:129]
	v_mfma_f32_16x16x32_bf16 v[122:125], v[160:163], v[194:197], v[122:125]
	v_mfma_f32_16x16x32_bf16 v[114:117], v[160:163], v[210:213], v[114:117]
	v_mfma_f32_16x16x32_bf16 v[118:121], v[152:155], v[210:213], v[118:121]
	v_mfma_f32_16x16x32_bf16 v[86:89], v[168:171], v[210:213], v[86:89]
	v_mfma_f32_16x16x32_bf16 v[82:85], v[176:179], v[210:213], v[82:85]
	v_mfma_f32_16x16x32_bf16 v[90:93], v[176:179], v[194:197], v[90:93]
	v_mfma_f32_16x16x32_bf16 v[94:97], v[168:171], v[194:197], v[94:97]
	v_mfma_f32_16x16x32_bf16 v[78:81], v[168:171], v[218:221], v[78:81]
	v_mfma_f32_16x16x32_bf16 v[74:77], v[176:179], v[218:221], v[74:77]
	v_mfma_f32_16x16x32_bf16 v[66:69], v[176:179], v[240:243], v[66:69]
	v_mfma_f32_16x16x32_bf16 v[70:73], v[168:171], v[240:243], v[70:73]
	v_mfma_f32_16x16x32_bf16 v[102:105], v[152:155], v[240:243], v[102:105]
	v_mfma_f32_16x16x32_bf16 v[98:101], v[160:163], v[240:243], v[98:101]
	v_mfma_f32_16x16x32_bf16 v[106:109], v[160:163], v[218:221], v[106:109]
	v_mfma_f32_16x16x32_bf16 v[110:113], v[152:155], v[218:221], v[110:113]
	v_mfma_f32_16x16x32_bf16 v[126:129], v[156:159], v[206:209], v[126:129]
	v_mfma_f32_16x16x32_bf16 v[122:125], v[164:167], v[206:209], v[122:125]
	v_mfma_f32_16x16x32_bf16 v[114:117], v[164:167], v[214:217], v[114:117]
	v_mfma_f32_16x16x32_bf16 v[118:121], v[156:159], v[214:217], v[118:121]
	v_mfma_f32_16x16x32_bf16 v[86:89], v[172:175], v[214:217], v[86:89]
	v_mfma_f32_16x16x32_bf16 v[82:85], v[180:183], v[214:217], v[82:85]
	v_mfma_f32_16x16x32_bf16 v[90:93], v[180:183], v[206:209], v[90:93]
	v_mfma_f32_16x16x32_bf16 v[94:97], v[172:175], v[206:209], v[94:97]
	v_mfma_f32_16x16x32_bf16 v[78:81], v[172:175], v[236:239], v[78:81]
	v_mfma_f32_16x16x32_bf16 v[74:77], v[180:183], v[236:239], v[74:77]
	v_mfma_f32_16x16x32_bf16 v[66:69], v[180:183], v[244:247], v[66:69]
	v_mfma_f32_16x16x32_bf16 v[70:73], v[172:175], v[244:247], v[70:73]
	v_mfma_f32_16x16x32_bf16 v[102:105], v[156:159], v[244:247], v[102:105]
	v_mfma_f32_16x16x32_bf16 v[98:101], v[164:167], v[244:247], v[98:101]
	v_mfma_f32_16x16x32_bf16 v[106:109], v[164:167], v[236:239], v[106:109]
	v_mfma_f32_16x16x32_bf16 v[110:113], v[156:159], v[236:239], v[110:113]
	s_barrier
	s_add_i32 s9, s9, s42
	s_mov_b32 m0, s9
	ds_read_b128 v[194:197], v151 offset:49152
	ds_read_b128 v[206:209], v151 offset:50176
	ds_read_b128 v[210:213], v151 offset:51200
	ds_read_b128 v[214:217], v151 offset:52224
	ds_read_b128 v[218:221], v151 offset:53248
	ds_read_b128 v[236:239], v151 offset:54272
	ds_read_b128 v[240:243], v151 offset:55296
	ds_read_b128 v[244:247], v151 offset:56320
	s_add_u32 s100, s84, s60
	s_addc_u32 s101, s85, s61
	global_load_lds_dwordx4 v130, s[100:101]
	s_add_i32 m0, s9, 0x2000
	s_add_u32 s10, s84, 0x20080
	s_addc_u32 s11, s85, 0
	s_add_i32 s9, s12, s42
	global_load_lds_dwordx4 v134, s[100:101]
	s_mov_b32 m0, s9
	s_nop 0
	global_load_lds_dwordx4 v130, s[10:11]
	s_add_i32 m0, s9, 0x2000
	s_nop 0
	global_load_lds_dwordx4 v134, s[10:11]
	s_mov_b32 m0, s82
	s_add_u32 s100, s92, s60
	s_addc_u32 s101, s93, s61
	global_load_lds_dwordx4 v190, s[100:101]
	s_mov_b32 m0, s86
	s_nop 0
	global_load_lds_dwordx4 v132, s[100:101]
	s_waitcnt vmcnt(8)
	s_waitcnt lgkmcnt(0)
	s_barrier
	v_mfma_f32_16x16x32_bf16 v[62:65], v[152:155], v[194:197], v[62:65]
	v_mfma_f32_16x16x32_bf16 v[58:61], v[160:163], v[194:197], v[58:61]
	v_mfma_f32_16x16x32_bf16 v[50:53], v[160:163], v[210:213], v[50:53]
	v_mfma_f32_16x16x32_bf16 v[54:57], v[152:155], v[210:213], v[54:57]
	v_mfma_f32_16x16x32_bf16 v[22:25], v[168:171], v[210:213], v[22:25]
	v_mfma_f32_16x16x32_bf16 v[18:21], v[176:179], v[210:213], v[18:21]
	v_mfma_f32_16x16x32_bf16 v[26:29], v[176:179], v[194:197], v[26:29]
	v_mfma_f32_16x16x32_bf16 v[30:33], v[168:171], v[194:197], v[30:33]
	v_mfma_f32_16x16x32_bf16 v[14:17], v[168:171], v[218:221], v[14:17]
	v_mfma_f32_16x16x32_bf16 v[10:13], v[176:179], v[218:221], v[10:13]
	v_mfma_f32_16x16x32_bf16 v[2:5], v[176:179], v[240:243], v[2:5]
	v_mfma_f32_16x16x32_bf16 v[6:9], v[168:171], v[240:243], v[6:9]
	v_mfma_f32_16x16x32_bf16 v[38:41], v[152:155], v[240:243], v[38:41]
	v_mfma_f32_16x16x32_bf16 v[34:37], v[160:163], v[240:243], v[34:37]
	v_mfma_f32_16x16x32_bf16 v[42:45], v[160:163], v[218:221], v[42:45]
	v_mfma_f32_16x16x32_bf16 v[46:49], v[152:155], v[218:221], v[46:49]
	v_mfma_f32_16x16x32_bf16 v[62:65], v[156:159], v[206:209], v[62:65]
	v_mfma_f32_16x16x32_bf16 v[58:61], v[164:167], v[206:209], v[58:61]
	v_mfma_f32_16x16x32_bf16 v[50:53], v[164:167], v[214:217], v[50:53]
	v_mfma_f32_16x16x32_bf16 v[54:57], v[156:159], v[214:217], v[54:57]
	v_mfma_f32_16x16x32_bf16 v[22:25], v[172:175], v[214:217], v[22:25]
	v_mfma_f32_16x16x32_bf16 v[18:21], v[180:183], v[214:217], v[18:21]
	v_mfma_f32_16x16x32_bf16 v[26:29], v[180:183], v[206:209], v[26:29]
	v_mfma_f32_16x16x32_bf16 v[30:33], v[172:175], v[206:209], v[30:33]
	v_mfma_f32_16x16x32_bf16 v[14:17], v[172:175], v[236:239], v[14:17]
	v_mfma_f32_16x16x32_bf16 v[10:13], v[180:183], v[236:239], v[10:13]
	v_mfma_f32_16x16x32_bf16 v[2:5], v[180:183], v[244:247], v[2:5]
	v_mfma_f32_16x16x32_bf16 v[6:9], v[172:175], v[244:247], v[6:9]
	v_mfma_f32_16x16x32_bf16 v[38:41], v[156:159], v[244:247], v[38:41]
	v_mfma_f32_16x16x32_bf16 v[34:37], v[164:167], v[244:247], v[34:37]
	v_mfma_f32_16x16x32_bf16 v[42:45], v[164:167], v[236:239], v[42:45]
	v_mfma_f32_16x16x32_bf16 v[46:49], v[156:159], v[236:239], v[46:49]
	s_barrier
	s_add_i32 s8, s8, 2
	s_add_u32 s80, s80, 0x100
	s_addc_u32 s81, s81, 0
	s_cmp_gt_u32 s8, 29
	s_cbranch_scc0 .LBB0_1233
	s_and_b64 vcc, exec, s[62:63]
	s_cbranch_vccz .LBB0_1236
	s_barrier
